# peel stack plus hand-written P1/P12 conversion tails (w_ffn1_down / w_ffn2_down on workgroups 216..255): dwordx4 loads, 3 load buffers in flight per wave, counted vmcnt, same items and rounding
# speedup vs baseline: 1.0074x; 1.0015x over previous
; #define GAS __attribute__((address_space(1)))
; #define LAS __attribute__((address_space(3)))
; #define LDS_WAIT() asm volatile("s_waitcnt lgkmcnt(0)" ::: "memory")
; __device__ __forceinline__ unsigned pk2(float lo, float hi) { return f2bf(lo) | (f2bf(hi) << 16); }
;     if (ldt == 0) ldt = K;
;     asm volatile("" : "+v"(lane));
;     const int kb = item / nblk, nb = item % nblk, k0 = 64 * kb, n0 = 32 * nb;
;     { float wv[32];
;       const float* wp = W + (size_t)(k0 + (lane >> 5)) * ldw + n0 + (lane & 31);
; #pragma unroll
;       for (int i = 0; i < 32; ++i) wv[i] = wp[(size_t)(2 * i) * ldw];
; #pragma unroll
;       for (int i = 0; i < 32; ++i) scr[(2 * i + (lane >> 5)) * 33 + (lane & 31)] = wv[i]; }
;     LDS_WAIT(); asm volatile("" ::: "memory");
;     const int c = lane & 7;
;     const int r0 = (mode == 0) ? n0 : (256 * (n0 >> 7) + (n0 & 127) + (mode == 2 ? 128 : 0));
; #pragma unroll
;     for (int j = 0; j < 4; ++j) { const int n = (lane >> 3) + 8 * j; const LAS float* s = scr + (8 * c) * 33 + n;
;         v4u o; o.x = pk2(s[0 * 33], s[1 * 33]); o.y = pk2(s[2 * 33], s[3 * 33]); o.z = pk2(s[4 * 33], s[5 * 33]); o.w = pk2(s[6 * 33], s[7 * 33]);
;         *(GAS v4u*)(WT + (size_t)(r0 + n) * ldt + k0 + 8 * c) = o; }
;     LDS_WAIT(); asm volatile("" ::: "memory");
; }
; template <bool LATE = false>
; __device__ __forceinline__ void transpose_tail(Frame& F, const Args& a, int bx, int lo, int first, int count) {
;     if (F.G != 256 || bx < lo) return;
;     LAS float* scr = (LAS float*)(F.lds + F.wave * 16384);
;     for (int j = (bx - lo) * NWAVES + F.wave; j < count; j += (F.G - lo) * NWAVES) { if (LATE) transpose_late(a, F, scr, first + j); else transpose_early(a, F, scr, first + j); }
; }
.LBB0_95:
	s_lshl_b32 s6, s2, 3
	s_add_i32 s6, s97, s6
	s_cmpk_lg_i32 s96, 0x100
	s_cselect_b64 s[8:9], -1, 0
	s_cmpk_lt_i32 s2, 0xd8
	s_cselect_b64 s[10:11], -1, 0
	s_or_b64 s[8:9], s[10:11], s[8:9]
	s_add_i32 s7, s6, 0xfffff940
	s_cmpk_gt_i32 s7, 0x15ff
	s_cselect_b64 s[10:11], -1, 0
	s_or_b64 s[8:9], s[8:9], s[10:11]
	v_mov_b32_e32 v2, v1
	s_and_b64 vcc, exec, s[8:9]
	s_cbranch_vccnz .LBB0_106
	s_mov_b64 s[6:7], s[62:63]
	s_add_u32 s8, s34, 0x2d00000
	s_addc_u32 s9, s35, 0
	s_lshl_b32 s18, s2, 3
	s_add_i32 s18, s18, s97
	s_addk_i32 s18, 0xf940
	s_lshl_b32 s19, s97, 14
	v_mbcnt_lo_u32_b32 v2, -1, 0
	v_mbcnt_hi_u32_b32 v2, -1, v2
	v_lshrrev_b32_e32 v120, 3, v2
	v_and_b32_e32 v121, 7, v2
	v_lshlrev_b32_e32 v3, 13, v120
	v_lshl_add_u32 v3, v121, 4, v3
	v_add_u32_e32 v4, 0x10000, v3
	v_add_u32_e32 v5, 0x20000, v3
	v_add_u32_e32 v6, 0x30000, v3
	v_add_u32_e32 v7, 0x40000, v3
	v_add_u32_e32 v8, 0x50000, v3
	v_add_u32_e32 v9, 0x60000, v3
	v_add_u32_e32 v10, 0x70000, v3
	v_mul_u32_u24_e32 v11, 0x2c00, v120
	v_lshl_add_u32 v11, v121, 4, v11
	v_add_u32_e32 v12, 0x16000, v11
	v_add_u32_e32 v13, 0x2c000, v11
	v_add_u32_e32 v14, 0x42000, v11
	v_mul_u32_u24_e32 v15, 132, v120
	v_lshl_add_u32 v15, v121, 4, v15
	v_add_u32_e32 v15, s19, v15
	v_add_u32_e32 v16, 1056, v15
	v_add_u32_e32 v17, 2112, v15
	v_add_u32_e32 v18, 3168, v15
	v_add_u32_e32 v19, 4224, v15
	v_add_u32_e32 v20, 5280, v15
	v_add_u32_e32 v21, 6336, v15
	v_add_u32_e32 v22, 7392, v15
	v_mul_u32_u24_e32 v23, 1056, v121
	v_lshl_add_u32 v23, v120, 2, v23
	v_add_u32_e32 v23, s19, v23
	s_add_i32 s28, s18, 0x0
	s_lshr_b32 s20, s28, 6
	s_and_b32 s21, s28, 63
	s_lshl_b32 s10, s20, 19
	s_lshl_b32 s11, s21, 7
	s_add_u32 s10, s10, s11
	s_add_u32 s10, s10, s6
	s_addc_u32 s11, s7, 0
	global_load_dwordx4 v[24:27], v3, s[10:11]
	global_load_dwordx4 v[28:31], v4, s[10:11]
	global_load_dwordx4 v[32:35], v5, s[10:11]
	global_load_dwordx4 v[36:39], v6, s[10:11]
	global_load_dwordx4 v[40:43], v7, s[10:11]
	global_load_dwordx4 v[44:47], v8, s[10:11]
	global_load_dwordx4 v[48:51], v9, s[10:11]
	global_load_dwordx4 v[52:55], v10, s[10:11]
	s_add_i32 s28, s18, 0x140
	s_lshr_b32 s20, s28, 6
	s_and_b32 s21, s28, 63
	s_lshl_b32 s10, s20, 19
	s_lshl_b32 s11, s21, 7
	s_add_u32 s10, s10, s11
	s_add_u32 s10, s10, s6
	s_addc_u32 s11, s7, 0
	global_load_dwordx4 v[56:59], v3, s[10:11]
	global_load_dwordx4 v[60:63], v4, s[10:11]
	global_load_dwordx4 v[64:67], v5, s[10:11]
	global_load_dwordx4 v[68:71], v6, s[10:11]
	global_load_dwordx4 v[72:75], v7, s[10:11]
	global_load_dwordx4 v[76:79], v8, s[10:11]
	global_load_dwordx4 v[80:83], v9, s[10:11]
	global_load_dwordx4 v[84:87], v10, s[10:11]
	s_add_i32 s28, s18, 0x280
	s_lshr_b32 s20, s28, 6
	s_and_b32 s21, s28, 63
	s_lshl_b32 s10, s20, 19
	s_lshl_b32 s11, s21, 7
	s_add_u32 s10, s10, s11
	s_add_u32 s10, s10, s6
	s_addc_u32 s11, s7, 0
	global_load_dwordx4 v[88:91], v3, s[10:11]
	global_load_dwordx4 v[92:95], v4, s[10:11]
	global_load_dwordx4 v[96:99], v5, s[10:11]
	global_load_dwordx4 v[100:103], v6, s[10:11]
	global_load_dwordx4 v[104:107], v7, s[10:11]
	global_load_dwordx4 v[108:111], v8, s[10:11]
	global_load_dwordx4 v[112:115], v9, s[10:11]
	global_load_dwordx4 v[116:119], v10, s[10:11]
	s_add_i32 s28, s18, 0x0
	s_lshr_b32 s20, s28, 6
	s_and_b32 s21, s28, 63
	s_mul_i32 s14, s21, 0x58000
	s_lshl_b32 s15, s20, 7
	s_add_u32 s14, s14, s15
	s_add_u32 s14, s14, s8
	s_addc_u32 s15, s9, 0
	s_waitcnt vmcnt(16)
	ds_write2_b32 v15, v24, v25 offset1:1
	ds_write2_b32 v15, v26, v27 offset0:2 offset1:3
	ds_write2_b32 v16, v28, v29 offset1:1
	ds_write2_b32 v16, v30, v31 offset0:2 offset1:3
	ds_write2_b32 v17, v32, v33 offset1:1
	ds_write2_b32 v17, v34, v35 offset0:2 offset1:3
	ds_write2_b32 v18, v36, v37 offset1:1
	ds_write2_b32 v18, v38, v39 offset0:2 offset1:3
	ds_write2_b32 v19, v40, v41 offset1:1
	ds_write2_b32 v19, v42, v43 offset0:2 offset1:3
	ds_write2_b32 v20, v44, v45 offset1:1
	ds_write2_b32 v20, v46, v47 offset0:2 offset1:3
	ds_write2_b32 v21, v48, v49 offset1:1
	ds_write2_b32 v21, v50, v51 offset0:2 offset1:3
	ds_write2_b32 v22, v52, v53 offset1:1
	ds_write2_b32 v22, v54, v55 offset0:2 offset1:3
	s_waitcnt lgkmcnt(0)
	ds_read2_b32 v[120:121], v23 offset0:0 offset1:33
	ds_read2_b32 v[122:123], v23 offset0:66 offset1:99
	ds_read2_b32 v[124:125], v23 offset0:132 offset1:165
	ds_read2_b32 v[126:127], v23 offset0:198 offset1:231
	s_waitcnt lgkmcnt(0)
	v_cvt_pk_bf16_f32 v128, v120, v121
	v_cvt_pk_bf16_f32 v129, v122, v123
	v_cvt_pk_bf16_f32 v130, v124, v125
	v_cvt_pk_bf16_f32 v131, v126, v127
	global_store_dwordx4 v11, v[128:131], s[14:15]
	s_nop 1
	ds_read2_b32 v[120:121], v23 offset0:8 offset1:41
	ds_read2_b32 v[122:123], v23 offset0:74 offset1:107
	ds_read2_b32 v[124:125], v23 offset0:140 offset1:173
	ds_read2_b32 v[126:127], v23 offset0:206 offset1:239
	s_waitcnt lgkmcnt(0)
	v_cvt_pk_bf16_f32 v128, v120, v121
	v_cvt_pk_bf16_f32 v129, v122, v123
	v_cvt_pk_bf16_f32 v130, v124, v125
	v_cvt_pk_bf16_f32 v131, v126, v127
	global_store_dwordx4 v12, v[128:131], s[14:15]
	s_nop 1
	ds_read2_b32 v[120:121], v23 offset0:16 offset1:49
	ds_read2_b32 v[122:123], v23 offset0:82 offset1:115
	ds_read2_b32 v[124:125], v23 offset0:148 offset1:181
	ds_read2_b32 v[126:127], v23 offset0:214 offset1:247
	s_waitcnt lgkmcnt(0)
	v_cvt_pk_bf16_f32 v128, v120, v121
	v_cvt_pk_bf16_f32 v129, v122, v123
	v_cvt_pk_bf16_f32 v130, v124, v125
	v_cvt_pk_bf16_f32 v131, v126, v127
	global_store_dwordx4 v13, v[128:131], s[14:15]
	s_nop 1
	ds_read2_b32 v[120:121], v23 offset0:24 offset1:57
	ds_read2_b32 v[122:123], v23 offset0:90 offset1:123
	ds_read2_b32 v[124:125], v23 offset0:156 offset1:189
	ds_read2_b32 v[126:127], v23 offset0:222 offset1:255
	s_waitcnt lgkmcnt(0)
; #define GAS __attribute__((address_space(1)))
; #define LAS __attribute__((address_space(3)))
; #define LDS_WAIT() asm volatile("s_waitcnt lgkmcnt(0)" ::: "memory")
; __device__ __forceinline__ unsigned pk2(float lo, float hi) { return f2bf(lo) | (f2bf(hi) << 16); }
;     if (ldt == 0) ldt = K;
;     asm volatile("" : "+v"(lane));
;     const int kb = item / nblk, nb = item % nblk, k0 = 64 * kb, n0 = 32 * nb;
;     { float wv[32];
;       const float* wp = W + (size_t)(k0 + (lane >> 5)) * ldw + n0 + (lane & 31);
; #pragma unroll
;       for (int i = 0; i < 32; ++i) wv[i] = wp[(size_t)(2 * i) * ldw];
; #pragma unroll
;       for (int i = 0; i < 32; ++i) scr[(2 * i + (lane >> 5)) * 33 + (lane & 31)] = wv[i]; }
;     LDS_WAIT(); asm volatile("" ::: "memory");
;     const int c = lane & 7;
;     const int r0 = (mode == 0) ? n0 : (256 * (n0 >> 7) + (n0 & 127) + (mode == 2 ? 128 : 0));
; #pragma unroll
;     for (int j = 0; j < 4; ++j) { const int n = (lane >> 3) + 8 * j; const LAS float* s = scr + (8 * c) * 33 + n;
;         v4u o; o.x = pk2(s[0 * 33], s[1 * 33]); o.y = pk2(s[2 * 33], s[3 * 33]); o.z = pk2(s[4 * 33], s[5 * 33]); o.w = pk2(s[6 * 33], s[7 * 33]);
;         *(GAS v4u*)(WT + (size_t)(r0 + n) * ldt + k0 + 8 * c) = o; }
;     LDS_WAIT(); asm volatile("" ::: "memory");
; }
	v_cvt_pk_bf16_f32 v128, v120, v121
	v_cvt_pk_bf16_f32 v129, v122, v123
	v_cvt_pk_bf16_f32 v130, v124, v125
	v_cvt_pk_bf16_f32 v131, v126, v127
	global_store_dwordx4 v14, v[128:131], s[14:15]
	s_nop 1
	s_add_i32 s28, s18, 0x3c0
	s_lshr_b32 s20, s28, 6
	s_and_b32 s21, s28, 63
	s_lshl_b32 s10, s20, 19
	s_lshl_b32 s11, s21, 7
	s_add_u32 s10, s10, s11
	s_add_u32 s10, s10, s6
	s_addc_u32 s11, s7, 0
	global_load_dwordx4 v[24:27], v3, s[10:11]
	global_load_dwordx4 v[28:31], v4, s[10:11]
	global_load_dwordx4 v[32:35], v5, s[10:11]
	global_load_dwordx4 v[36:39], v6, s[10:11]
	global_load_dwordx4 v[40:43], v7, s[10:11]
	global_load_dwordx4 v[44:47], v8, s[10:11]
	global_load_dwordx4 v[48:51], v9, s[10:11]
	global_load_dwordx4 v[52:55], v10, s[10:11]
	s_add_i32 s28, s18, 0x140
	s_lshr_b32 s20, s28, 6
	s_and_b32 s21, s28, 63
	s_mul_i32 s14, s21, 0x58000
	s_lshl_b32 s15, s20, 7
	s_add_u32 s14, s14, s15
	s_add_u32 s14, s14, s8
	s_addc_u32 s15, s9, 0
	s_waitcnt vmcnt(20)
	ds_write2_b32 v15, v56, v57 offset1:1
	ds_write2_b32 v15, v58, v59 offset0:2 offset1:3
	ds_write2_b32 v16, v60, v61 offset1:1
	ds_write2_b32 v16, v62, v63 offset0:2 offset1:3
	ds_write2_b32 v17, v64, v65 offset1:1
	ds_write2_b32 v17, v66, v67 offset0:2 offset1:3
	ds_write2_b32 v18, v68, v69 offset1:1
	ds_write2_b32 v18, v70, v71 offset0:2 offset1:3
	ds_write2_b32 v19, v72, v73 offset1:1
	ds_write2_b32 v19, v74, v75 offset0:2 offset1:3
	ds_write2_b32 v20, v76, v77 offset1:1
	ds_write2_b32 v20, v78, v79 offset0:2 offset1:3
	ds_write2_b32 v21, v80, v81 offset1:1
	ds_write2_b32 v21, v82, v83 offset0:2 offset1:3
	ds_write2_b32 v22, v84, v85 offset1:1
	ds_write2_b32 v22, v86, v87 offset0:2 offset1:3
	s_waitcnt lgkmcnt(0)
	ds_read2_b32 v[120:121], v23 offset0:0 offset1:33
	ds_read2_b32 v[122:123], v23 offset0:66 offset1:99
	ds_read2_b32 v[124:125], v23 offset0:132 offset1:165
	ds_read2_b32 v[126:127], v23 offset0:198 offset1:231
	s_waitcnt lgkmcnt(0)
	v_cvt_pk_bf16_f32 v128, v120, v121
	v_cvt_pk_bf16_f32 v129, v122, v123
	v_cvt_pk_bf16_f32 v130, v124, v125
	v_cvt_pk_bf16_f32 v131, v126, v127
	global_store_dwordx4 v11, v[128:131], s[14:15]
	s_nop 1
	ds_read2_b32 v[120:121], v23 offset0:8 offset1:41
	ds_read2_b32 v[122:123], v23 offset0:74 offset1:107
	ds_read2_b32 v[124:125], v23 offset0:140 offset1:173
	ds_read2_b32 v[126:127], v23 offset0:206 offset1:239
	s_waitcnt lgkmcnt(0)
	v_cvt_pk_bf16_f32 v128, v120, v121
	v_cvt_pk_bf16_f32 v129, v122, v123
	v_cvt_pk_bf16_f32 v130, v124, v125
	v_cvt_pk_bf16_f32 v131, v126, v127
	global_store_dwordx4 v12, v[128:131], s[14:15]
	s_nop 1
	ds_read2_b32 v[120:121], v23 offset0:16 offset1:49
	ds_read2_b32 v[122:123], v23 offset0:82 offset1:115
	ds_read2_b32 v[124:125], v23 offset0:148 offset1:181
	ds_read2_b32 v[126:127], v23 offset0:214 offset1:247
	s_waitcnt lgkmcnt(0)
	v_cvt_pk_bf16_f32 v128, v120, v121
	v_cvt_pk_bf16_f32 v129, v122, v123
	v_cvt_pk_bf16_f32 v130, v124, v125
	v_cvt_pk_bf16_f32 v131, v126, v127
	global_store_dwordx4 v13, v[128:131], s[14:15]
	s_nop 1
	ds_read2_b32 v[120:121], v23 offset0:24 offset1:57
	ds_read2_b32 v[122:123], v23 offset0:90 offset1:123
	ds_read2_b32 v[124:125], v23 offset0:156 offset1:189
	ds_read2_b32 v[126:127], v23 offset0:222 offset1:255
	s_waitcnt lgkmcnt(0)
	v_cvt_pk_bf16_f32 v128, v120, v121
	v_cvt_pk_bf16_f32 v129, v122, v123
	v_cvt_pk_bf16_f32 v130, v124, v125
	v_cvt_pk_bf16_f32 v131, v126, v127
	global_store_dwordx4 v14, v[128:131], s[14:15]
	s_nop 1
	s_add_i32 s28, s18, 0x500
	s_lshr_b32 s20, s28, 6
	s_and_b32 s21, s28, 63
	s_lshl_b32 s10, s20, 19
	s_lshl_b32 s11, s21, 7
	s_add_u32 s10, s10, s11
	s_add_u32 s10, s10, s6
	s_addc_u32 s11, s7, 0
	global_load_dwordx4 v[56:59], v3, s[10:11]
	global_load_dwordx4 v[60:63], v4, s[10:11]
	global_load_dwordx4 v[64:67], v5, s[10:11]
	global_load_dwordx4 v[68:71], v6, s[10:11]
	global_load_dwordx4 v[72:75], v7, s[10:11]
	global_load_dwordx4 v[76:79], v8, s[10:11]
	global_load_dwordx4 v[80:83], v9, s[10:11]
	global_load_dwordx4 v[84:87], v10, s[10:11]
	s_add_i32 s28, s18, 0x280
	s_lshr_b32 s20, s28, 6
	s_and_b32 s21, s28, 63
	s_mul_i32 s14, s21, 0x58000
	s_lshl_b32 s15, s20, 7
	s_add_u32 s14, s14, s15
	s_add_u32 s14, s14, s8
	s_addc_u32 s15, s9, 0
	s_waitcnt vmcnt(24)
	ds_write2_b32 v15, v88, v89 offset1:1
	ds_write2_b32 v15, v90, v91 offset0:2 offset1:3
	ds_write2_b32 v16, v92, v93 offset1:1
	ds_write2_b32 v16, v94, v95 offset0:2 offset1:3
	ds_write2_b32 v17, v96, v97 offset1:1
	ds_write2_b32 v17, v98, v99 offset0:2 offset1:3
	ds_write2_b32 v18, v100, v101 offset1:1
	ds_write2_b32 v18, v102, v103 offset0:2 offset1:3
	ds_write2_b32 v19, v104, v105 offset1:1
	ds_write2_b32 v19, v106, v107 offset0:2 offset1:3
	ds_write2_b32 v20, v108, v109 offset1:1
	ds_write2_b32 v20, v110, v111 offset0:2 offset1:3
	ds_write2_b32 v21, v112, v113 offset1:1
	ds_write2_b32 v21, v114, v115 offset0:2 offset1:3
	ds_write2_b32 v22, v116, v117 offset1:1
	ds_write2_b32 v22, v118, v119 offset0:2 offset1:3
	s_waitcnt lgkmcnt(0)
	ds_read2_b32 v[120:121], v23 offset0:0 offset1:33
	ds_read2_b32 v[122:123], v23 offset0:66 offset1:99
	ds_read2_b32 v[124:125], v23 offset0:132 offset1:165
	ds_read2_b32 v[126:127], v23 offset0:198 offset1:231
	s_waitcnt lgkmcnt(0)
	v_cvt_pk_bf16_f32 v128, v120, v121
	v_cvt_pk_bf16_f32 v129, v122, v123
	v_cvt_pk_bf16_f32 v130, v124, v125
	v_cvt_pk_bf16_f32 v131, v126, v127
	global_store_dwordx4 v11, v[128:131], s[14:15]
	s_nop 1
	ds_read2_b32 v[120:121], v23 offset0:8 offset1:41
	ds_read2_b32 v[122:123], v23 offset0:74 offset1:107
	ds_read2_b32 v[124:125], v23 offset0:140 offset1:173
	ds_read2_b32 v[126:127], v23 offset0:206 offset1:239
	s_waitcnt lgkmcnt(0)
; #define GAS __attribute__((address_space(1)))
; #define LAS __attribute__((address_space(3)))
; #define LDS_WAIT() asm volatile("s_waitcnt lgkmcnt(0)" ::: "memory")
; __device__ __forceinline__ unsigned pk2(float lo, float hi) { return f2bf(lo) | (f2bf(hi) << 16); }
;     if (ldt == 0) ldt = K;
;     asm volatile("" : "+v"(lane));
;     const int kb = item / nblk, nb = item % nblk, k0 = 64 * kb, n0 = 32 * nb;
;     { float wv[32];
;       const float* wp = W + (size_t)(k0 + (lane >> 5)) * ldw + n0 + (lane & 31);
; #pragma unroll
;       for (int i = 0; i < 32; ++i) wv[i] = wp[(size_t)(2 * i) * ldw];
; #pragma unroll
;       for (int i = 0; i < 32; ++i) scr[(2 * i + (lane >> 5)) * 33 + (lane & 31)] = wv[i]; }
;     LDS_WAIT(); asm volatile("" ::: "memory");
;     const int c = lane & 7;
;     const int r0 = (mode == 0) ? n0 : (256 * (n0 >> 7) + (n0 & 127) + (mode == 2 ? 128 : 0));
; #pragma unroll
;     for (int j = 0; j < 4; ++j) { const int n = (lane >> 3) + 8 * j; const LAS float* s = scr + (8 * c) * 33 + n;
;         v4u o; o.x = pk2(s[0 * 33], s[1 * 33]); o.y = pk2(s[2 * 33], s[3 * 33]); o.z = pk2(s[4 * 33], s[5 * 33]); o.w = pk2(s[6 * 33], s[7 * 33]);
;         *(GAS v4u*)(WT + (size_t)(r0 + n) * ldt + k0 + 8 * c) = o; }
;     LDS_WAIT(); asm volatile("" ::: "memory");
; }
	v_cvt_pk_bf16_f32 v128, v120, v121
	v_cvt_pk_bf16_f32 v129, v122, v123
	v_cvt_pk_bf16_f32 v130, v124, v125
	v_cvt_pk_bf16_f32 v131, v126, v127
	global_store_dwordx4 v12, v[128:131], s[14:15]
	s_nop 1
	ds_read2_b32 v[120:121], v23 offset0:16 offset1:49
	ds_read2_b32 v[122:123], v23 offset0:82 offset1:115
	ds_read2_b32 v[124:125], v23 offset0:148 offset1:181
	ds_read2_b32 v[126:127], v23 offset0:214 offset1:247
	s_waitcnt lgkmcnt(0)
	v_cvt_pk_bf16_f32 v128, v120, v121
	v_cvt_pk_bf16_f32 v129, v122, v123
	v_cvt_pk_bf16_f32 v130, v124, v125
	v_cvt_pk_bf16_f32 v131, v126, v127
	global_store_dwordx4 v13, v[128:131], s[14:15]
	s_nop 1
	ds_read2_b32 v[120:121], v23 offset0:24 offset1:57
	ds_read2_b32 v[122:123], v23 offset0:90 offset1:123
	ds_read2_b32 v[124:125], v23 offset0:156 offset1:189
	ds_read2_b32 v[126:127], v23 offset0:222 offset1:255
	s_waitcnt lgkmcnt(0)
	v_cvt_pk_bf16_f32 v128, v120, v121
	v_cvt_pk_bf16_f32 v129, v122, v123
	v_cvt_pk_bf16_f32 v130, v124, v125
	v_cvt_pk_bf16_f32 v131, v126, v127
	global_store_dwordx4 v14, v[128:131], s[14:15]
	s_nop 1
	s_add_i32 s28, s18, 0x640
	s_lshr_b32 s20, s28, 6
	s_and_b32 s21, s28, 63
	s_lshl_b32 s10, s20, 19
	s_lshl_b32 s11, s21, 7
	s_add_u32 s10, s10, s11
	s_add_u32 s10, s10, s6
	s_addc_u32 s11, s7, 0
	global_load_dwordx4 v[88:91], v3, s[10:11]
	global_load_dwordx4 v[92:95], v4, s[10:11]
	global_load_dwordx4 v[96:99], v5, s[10:11]
	global_load_dwordx4 v[100:103], v6, s[10:11]
	global_load_dwordx4 v[104:107], v7, s[10:11]
	global_load_dwordx4 v[108:111], v8, s[10:11]
	global_load_dwordx4 v[112:115], v9, s[10:11]
	global_load_dwordx4 v[116:119], v10, s[10:11]
	s_add_i32 s28, s18, 0x3c0
	s_lshr_b32 s20, s28, 6
	s_and_b32 s21, s28, 63
	s_mul_i32 s14, s21, 0x58000
	s_lshl_b32 s15, s20, 7
	s_add_u32 s14, s14, s15
	s_add_u32 s14, s14, s8
	s_addc_u32 s15, s9, 0
	s_waitcnt vmcnt(24)
	ds_write2_b32 v15, v24, v25 offset1:1
	ds_write2_b32 v15, v26, v27 offset0:2 offset1:3
	ds_write2_b32 v16, v28, v29 offset1:1
	ds_write2_b32 v16, v30, v31 offset0:2 offset1:3
	ds_write2_b32 v17, v32, v33 offset1:1
	ds_write2_b32 v17, v34, v35 offset0:2 offset1:3
	ds_write2_b32 v18, v36, v37 offset1:1
	ds_write2_b32 v18, v38, v39 offset0:2 offset1:3
	ds_write2_b32 v19, v40, v41 offset1:1
	ds_write2_b32 v19, v42, v43 offset0:2 offset1:3
	ds_write2_b32 v20, v44, v45 offset1:1
	ds_write2_b32 v20, v46, v47 offset0:2 offset1:3
	ds_write2_b32 v21, v48, v49 offset1:1
	ds_write2_b32 v21, v50, v51 offset0:2 offset1:3
	ds_write2_b32 v22, v52, v53 offset1:1
	ds_write2_b32 v22, v54, v55 offset0:2 offset1:3
	s_waitcnt lgkmcnt(0)
	ds_read2_b32 v[120:121], v23 offset0:0 offset1:33
	ds_read2_b32 v[122:123], v23 offset0:66 offset1:99
	ds_read2_b32 v[124:125], v23 offset0:132 offset1:165
	ds_read2_b32 v[126:127], v23 offset0:198 offset1:231
	s_waitcnt lgkmcnt(0)
	v_cvt_pk_bf16_f32 v128, v120, v121
	v_cvt_pk_bf16_f32 v129, v122, v123
	v_cvt_pk_bf16_f32 v130, v124, v125
	v_cvt_pk_bf16_f32 v131, v126, v127
	global_store_dwordx4 v11, v[128:131], s[14:15]
	s_nop 1
	ds_read2_b32 v[120:121], v23 offset0:8 offset1:41
	ds_read2_b32 v[122:123], v23 offset0:74 offset1:107
	ds_read2_b32 v[124:125], v23 offset0:140 offset1:173
	ds_read2_b32 v[126:127], v23 offset0:206 offset1:239
	s_waitcnt lgkmcnt(0)
	v_cvt_pk_bf16_f32 v128, v120, v121
	v_cvt_pk_bf16_f32 v129, v122, v123
	v_cvt_pk_bf16_f32 v130, v124, v125
	v_cvt_pk_bf16_f32 v131, v126, v127
	global_store_dwordx4 v12, v[128:131], s[14:15]
	s_nop 1
	ds_read2_b32 v[120:121], v23 offset0:16 offset1:49
	ds_read2_b32 v[122:123], v23 offset0:82 offset1:115
	ds_read2_b32 v[124:125], v23 offset0:148 offset1:181
	ds_read2_b32 v[126:127], v23 offset0:214 offset1:247
	s_waitcnt lgkmcnt(0)
	v_cvt_pk_bf16_f32 v128, v120, v121
	v_cvt_pk_bf16_f32 v129, v122, v123
	v_cvt_pk_bf16_f32 v130, v124, v125
	v_cvt_pk_bf16_f32 v131, v126, v127
	global_store_dwordx4 v13, v[128:131], s[14:15]
	s_nop 1
	ds_read2_b32 v[120:121], v23 offset0:24 offset1:57
	ds_read2_b32 v[122:123], v23 offset0:90 offset1:123
	ds_read2_b32 v[124:125], v23 offset0:156 offset1:189
	ds_read2_b32 v[126:127], v23 offset0:222 offset1:255
	s_waitcnt lgkmcnt(0)
	v_cvt_pk_bf16_f32 v128, v120, v121
	v_cvt_pk_bf16_f32 v129, v122, v123
	v_cvt_pk_bf16_f32 v130, v124, v125
	v_cvt_pk_bf16_f32 v131, v126, v127
	global_store_dwordx4 v14, v[128:131], s[14:15]
	s_nop 1
	s_add_i32 s28, s18, 0x780
	s_lshr_b32 s20, s28, 6
	s_and_b32 s21, s28, 63
	s_lshl_b32 s10, s20, 19
	s_lshl_b32 s11, s21, 7
	s_add_u32 s10, s10, s11
	s_add_u32 s10, s10, s6
	s_addc_u32 s11, s7, 0
	global_load_dwordx4 v[24:27], v3, s[10:11]
	global_load_dwordx4 v[28:31], v4, s[10:11]
	global_load_dwordx4 v[32:35], v5, s[10:11]
	global_load_dwordx4 v[36:39], v6, s[10:11]
	global_load_dwordx4 v[40:43], v7, s[10:11]
	global_load_dwordx4 v[44:47], v8, s[10:11]
	global_load_dwordx4 v[48:51], v9, s[10:11]
	global_load_dwordx4 v[52:55], v10, s[10:11]
	s_add_i32 s28, s18, 0x500
	s_lshr_b32 s20, s28, 6
	s_and_b32 s21, s28, 63
	s_mul_i32 s14, s21, 0x58000
	s_lshl_b32 s15, s20, 7
	s_add_u32 s14, s14, s15
	s_add_u32 s14, s14, s8
	s_addc_u32 s15, s9, 0
	s_waitcnt vmcnt(24)
	ds_write2_b32 v15, v56, v57 offset1:1
	ds_write2_b32 v15, v58, v59 offset0:2 offset1:3
	ds_write2_b32 v16, v60, v61 offset1:1
	ds_write2_b32 v16, v62, v63 offset0:2 offset1:3
	ds_write2_b32 v17, v64, v65 offset1:1
	ds_write2_b32 v17, v66, v67 offset0:2 offset1:3
	ds_write2_b32 v18, v68, v69 offset1:1
	ds_write2_b32 v18, v70, v71 offset0:2 offset1:3
	ds_write2_b32 v19, v72, v73 offset1:1
	ds_write2_b32 v19, v74, v75 offset0:2 offset1:3
	ds_write2_b32 v20, v76, v77 offset1:1
	ds_write2_b32 v20, v78, v79 offset0:2 offset1:3
	ds_write2_b32 v21, v80, v81 offset1:1
	ds_write2_b32 v21, v82, v83 offset0:2 offset1:3
	ds_write2_b32 v22, v84, v85 offset1:1
	ds_write2_b32 v22, v86, v87 offset0:2 offset1:3
	s_waitcnt lgkmcnt(0)
; #define GAS __attribute__((address_space(1)))
; #define LAS __attribute__((address_space(3)))
; #define LDS_WAIT() asm volatile("s_waitcnt lgkmcnt(0)" ::: "memory")
; __device__ __forceinline__ unsigned pk2(float lo, float hi) { return f2bf(lo) | (f2bf(hi) << 16); }
;     if (ldt == 0) ldt = K;
;     asm volatile("" : "+v"(lane));
;     const int kb = item / nblk, nb = item % nblk, k0 = 64 * kb, n0 = 32 * nb;
;     { float wv[32];
;       const float* wp = W + (size_t)(k0 + (lane >> 5)) * ldw + n0 + (lane & 31);
; #pragma unroll
;       for (int i = 0; i < 32; ++i) wv[i] = wp[(size_t)(2 * i) * ldw];
; #pragma unroll
;       for (int i = 0; i < 32; ++i) scr[(2 * i + (lane >> 5)) * 33 + (lane & 31)] = wv[i]; }
;     LDS_WAIT(); asm volatile("" ::: "memory");
;     const int c = lane & 7;
;     const int r0 = (mode == 0) ? n0 : (256 * (n0 >> 7) + (n0 & 127) + (mode == 2 ? 128 : 0));
; #pragma unroll
;     for (int j = 0; j < 4; ++j) { const int n = (lane >> 3) + 8 * j; const LAS float* s = scr + (8 * c) * 33 + n;
;         v4u o; o.x = pk2(s[0 * 33], s[1 * 33]); o.y = pk2(s[2 * 33], s[3 * 33]); o.z = pk2(s[4 * 33], s[5 * 33]); o.w = pk2(s[6 * 33], s[7 * 33]);
;         *(GAS v4u*)(WT + (size_t)(r0 + n) * ldt + k0 + 8 * c) = o; }
;     LDS_WAIT(); asm volatile("" ::: "memory");
; }
	ds_read2_b32 v[120:121], v23 offset0:0 offset1:33
	ds_read2_b32 v[122:123], v23 offset0:66 offset1:99
	ds_read2_b32 v[124:125], v23 offset0:132 offset1:165
	ds_read2_b32 v[126:127], v23 offset0:198 offset1:231
	s_waitcnt lgkmcnt(0)
	v_cvt_pk_bf16_f32 v128, v120, v121
	v_cvt_pk_bf16_f32 v129, v122, v123
	v_cvt_pk_bf16_f32 v130, v124, v125
	v_cvt_pk_bf16_f32 v131, v126, v127
	global_store_dwordx4 v11, v[128:131], s[14:15]
	s_nop 1
	ds_read2_b32 v[120:121], v23 offset0:8 offset1:41
	ds_read2_b32 v[122:123], v23 offset0:74 offset1:107
	ds_read2_b32 v[124:125], v23 offset0:140 offset1:173
	ds_read2_b32 v[126:127], v23 offset0:206 offset1:239
	s_waitcnt lgkmcnt(0)
	v_cvt_pk_bf16_f32 v128, v120, v121
	v_cvt_pk_bf16_f32 v129, v122, v123
	v_cvt_pk_bf16_f32 v130, v124, v125
	v_cvt_pk_bf16_f32 v131, v126, v127
	global_store_dwordx4 v12, v[128:131], s[14:15]
	s_nop 1
	ds_read2_b32 v[120:121], v23 offset0:16 offset1:49
	ds_read2_b32 v[122:123], v23 offset0:82 offset1:115
	ds_read2_b32 v[124:125], v23 offset0:148 offset1:181
	ds_read2_b32 v[126:127], v23 offset0:214 offset1:247
	s_waitcnt lgkmcnt(0)
	v_cvt_pk_bf16_f32 v128, v120, v121
	v_cvt_pk_bf16_f32 v129, v122, v123
	v_cvt_pk_bf16_f32 v130, v124, v125
	v_cvt_pk_bf16_f32 v131, v126, v127
	global_store_dwordx4 v13, v[128:131], s[14:15]
	s_nop 1
	ds_read2_b32 v[120:121], v23 offset0:24 offset1:57
	ds_read2_b32 v[122:123], v23 offset0:90 offset1:123
	ds_read2_b32 v[124:125], v23 offset0:156 offset1:189
	ds_read2_b32 v[126:127], v23 offset0:222 offset1:255
	s_waitcnt lgkmcnt(0)
	v_cvt_pk_bf16_f32 v128, v120, v121
	v_cvt_pk_bf16_f32 v129, v122, v123
	v_cvt_pk_bf16_f32 v130, v124, v125
	v_cvt_pk_bf16_f32 v131, v126, v127
	global_store_dwordx4 v14, v[128:131], s[14:15]
	s_nop 1
	s_add_i32 s28, s18, 0x8c0
	s_lshr_b32 s20, s28, 6
	s_and_b32 s21, s28, 63
	s_lshl_b32 s10, s20, 19
	s_lshl_b32 s11, s21, 7
	s_add_u32 s10, s10, s11
	s_add_u32 s10, s10, s6
	s_addc_u32 s11, s7, 0
	global_load_dwordx4 v[56:59], v3, s[10:11]
	global_load_dwordx4 v[60:63], v4, s[10:11]
	global_load_dwordx4 v[64:67], v5, s[10:11]
	global_load_dwordx4 v[68:71], v6, s[10:11]
	global_load_dwordx4 v[72:75], v7, s[10:11]
	global_load_dwordx4 v[76:79], v8, s[10:11]
	global_load_dwordx4 v[80:83], v9, s[10:11]
	global_load_dwordx4 v[84:87], v10, s[10:11]
	s_add_i32 s28, s18, 0x640
	s_lshr_b32 s20, s28, 6
	s_and_b32 s21, s28, 63
	s_mul_i32 s14, s21, 0x58000
	s_lshl_b32 s15, s20, 7
	s_add_u32 s14, s14, s15
	s_add_u32 s14, s14, s8
	s_addc_u32 s15, s9, 0
	s_waitcnt vmcnt(24)
	ds_write2_b32 v15, v88, v89 offset1:1
	ds_write2_b32 v15, v90, v91 offset0:2 offset1:3
	ds_write2_b32 v16, v92, v93 offset1:1
	ds_write2_b32 v16, v94, v95 offset0:2 offset1:3
	ds_write2_b32 v17, v96, v97 offset1:1
	ds_write2_b32 v17, v98, v99 offset0:2 offset1:3
	ds_write2_b32 v18, v100, v101 offset1:1
	ds_write2_b32 v18, v102, v103 offset0:2 offset1:3
	ds_write2_b32 v19, v104, v105 offset1:1
	ds_write2_b32 v19, v106, v107 offset0:2 offset1:3
	ds_write2_b32 v20, v108, v109 offset1:1
	ds_write2_b32 v20, v110, v111 offset0:2 offset1:3
	ds_write2_b32 v21, v112, v113 offset1:1
	ds_write2_b32 v21, v114, v115 offset0:2 offset1:3
	ds_write2_b32 v22, v116, v117 offset1:1
	ds_write2_b32 v22, v118, v119 offset0:2 offset1:3
	s_waitcnt lgkmcnt(0)
	ds_read2_b32 v[120:121], v23 offset0:0 offset1:33
	ds_read2_b32 v[122:123], v23 offset0:66 offset1:99
	ds_read2_b32 v[124:125], v23 offset0:132 offset1:165
	ds_read2_b32 v[126:127], v23 offset0:198 offset1:231
	s_waitcnt lgkmcnt(0)
	v_cvt_pk_bf16_f32 v128, v120, v121
	v_cvt_pk_bf16_f32 v129, v122, v123
	v_cvt_pk_bf16_f32 v130, v124, v125
	v_cvt_pk_bf16_f32 v131, v126, v127
	global_store_dwordx4 v11, v[128:131], s[14:15]
	s_nop 1
	ds_read2_b32 v[120:121], v23 offset0:8 offset1:41
	ds_read2_b32 v[122:123], v23 offset0:74 offset1:107
	ds_read2_b32 v[124:125], v23 offset0:140 offset1:173
	ds_read2_b32 v[126:127], v23 offset0:206 offset1:239
	s_waitcnt lgkmcnt(0)
	v_cvt_pk_bf16_f32 v128, v120, v121
	v_cvt_pk_bf16_f32 v129, v122, v123
	v_cvt_pk_bf16_f32 v130, v124, v125
	v_cvt_pk_bf16_f32 v131, v126, v127
	global_store_dwordx4 v12, v[128:131], s[14:15]
	s_nop 1
	ds_read2_b32 v[120:121], v23 offset0:16 offset1:49
	ds_read2_b32 v[122:123], v23 offset0:82 offset1:115
	ds_read2_b32 v[124:125], v23 offset0:148 offset1:181
	ds_read2_b32 v[126:127], v23 offset0:214 offset1:247
	s_waitcnt lgkmcnt(0)
	v_cvt_pk_bf16_f32 v128, v120, v121
	v_cvt_pk_bf16_f32 v129, v122, v123
	v_cvt_pk_bf16_f32 v130, v124, v125
	v_cvt_pk_bf16_f32 v131, v126, v127
	global_store_dwordx4 v13, v[128:131], s[14:15]
	s_nop 1
	ds_read2_b32 v[120:121], v23 offset0:24 offset1:57
	ds_read2_b32 v[122:123], v23 offset0:90 offset1:123
	ds_read2_b32 v[124:125], v23 offset0:156 offset1:189
	ds_read2_b32 v[126:127], v23 offset0:222 offset1:255
	s_waitcnt lgkmcnt(0)
	v_cvt_pk_bf16_f32 v128, v120, v121
	v_cvt_pk_bf16_f32 v129, v122, v123
	v_cvt_pk_bf16_f32 v130, v124, v125
	v_cvt_pk_bf16_f32 v131, v126, v127
	global_store_dwordx4 v14, v[128:131], s[14:15]
	s_nop 1
	s_add_i32 s28, s18, 0xa00
	s_lshr_b32 s20, s28, 6
	s_and_b32 s21, s28, 63
	s_lshl_b32 s10, s20, 19
	s_lshl_b32 s11, s21, 7
	s_add_u32 s10, s10, s11
	s_add_u32 s10, s10, s6
	s_addc_u32 s11, s7, 0
	global_load_dwordx4 v[88:91], v3, s[10:11]
	global_load_dwordx4 v[92:95], v4, s[10:11]
	global_load_dwordx4 v[96:99], v5, s[10:11]
	global_load_dwordx4 v[100:103], v6, s[10:11]
	global_load_dwordx4 v[104:107], v7, s[10:11]
	global_load_dwordx4 v[108:111], v8, s[10:11]
	global_load_dwordx4 v[112:115], v9, s[10:11]
	global_load_dwordx4 v[116:119], v10, s[10:11]
	s_add_i32 s28, s18, 0x780
	s_lshr_b32 s20, s28, 6
	s_and_b32 s21, s28, 63
	s_mul_i32 s14, s21, 0x58000
	s_lshl_b32 s15, s20, 7
	s_add_u32 s14, s14, s15
	s_add_u32 s14, s14, s8
	s_addc_u32 s15, s9, 0
	s_waitcnt vmcnt(24)
; #define GAS __attribute__((address_space(1)))
; #define LAS __attribute__((address_space(3)))
; #define LDS_WAIT() asm volatile("s_waitcnt lgkmcnt(0)" ::: "memory")
; __device__ __forceinline__ unsigned pk2(float lo, float hi) { return f2bf(lo) | (f2bf(hi) << 16); }
;     if (ldt == 0) ldt = K;
;     asm volatile("" : "+v"(lane));
;     const int kb = item / nblk, nb = item % nblk, k0 = 64 * kb, n0 = 32 * nb;
;     { float wv[32];
;       const float* wp = W + (size_t)(k0 + (lane >> 5)) * ldw + n0 + (lane & 31);
; #pragma unroll
;       for (int i = 0; i < 32; ++i) wv[i] = wp[(size_t)(2 * i) * ldw];
; #pragma unroll
;       for (int i = 0; i < 32; ++i) scr[(2 * i + (lane >> 5)) * 33 + (lane & 31)] = wv[i]; }
;     LDS_WAIT(); asm volatile("" ::: "memory");
;     const int c = lane & 7;
;     const int r0 = (mode == 0) ? n0 : (256 * (n0 >> 7) + (n0 & 127) + (mode == 2 ? 128 : 0));
; #pragma unroll
;     for (int j = 0; j < 4; ++j) { const int n = (lane >> 3) + 8 * j; const LAS float* s = scr + (8 * c) * 33 + n;
;         v4u o; o.x = pk2(s[0 * 33], s[1 * 33]); o.y = pk2(s[2 * 33], s[3 * 33]); o.z = pk2(s[4 * 33], s[5 * 33]); o.w = pk2(s[6 * 33], s[7 * 33]);
;         *(GAS v4u*)(WT + (size_t)(r0 + n) * ldt + k0 + 8 * c) = o; }
;     LDS_WAIT(); asm volatile("" ::: "memory");
; }
	ds_write2_b32 v15, v24, v25 offset1:1
	ds_write2_b32 v15, v26, v27 offset0:2 offset1:3
	ds_write2_b32 v16, v28, v29 offset1:1
	ds_write2_b32 v16, v30, v31 offset0:2 offset1:3
	ds_write2_b32 v17, v32, v33 offset1:1
	ds_write2_b32 v17, v34, v35 offset0:2 offset1:3
	ds_write2_b32 v18, v36, v37 offset1:1
	ds_write2_b32 v18, v38, v39 offset0:2 offset1:3
	ds_write2_b32 v19, v40, v41 offset1:1
	ds_write2_b32 v19, v42, v43 offset0:2 offset1:3
	ds_write2_b32 v20, v44, v45 offset1:1
	ds_write2_b32 v20, v46, v47 offset0:2 offset1:3
	ds_write2_b32 v21, v48, v49 offset1:1
	ds_write2_b32 v21, v50, v51 offset0:2 offset1:3
	ds_write2_b32 v22, v52, v53 offset1:1
	ds_write2_b32 v22, v54, v55 offset0:2 offset1:3
	s_waitcnt lgkmcnt(0)
	ds_read2_b32 v[120:121], v23 offset0:0 offset1:33
	ds_read2_b32 v[122:123], v23 offset0:66 offset1:99
	ds_read2_b32 v[124:125], v23 offset0:132 offset1:165
	ds_read2_b32 v[126:127], v23 offset0:198 offset1:231
	s_waitcnt lgkmcnt(0)
	v_cvt_pk_bf16_f32 v128, v120, v121
	v_cvt_pk_bf16_f32 v129, v122, v123
	v_cvt_pk_bf16_f32 v130, v124, v125
	v_cvt_pk_bf16_f32 v131, v126, v127
	global_store_dwordx4 v11, v[128:131], s[14:15]
	s_nop 1
	ds_read2_b32 v[120:121], v23 offset0:8 offset1:41
	ds_read2_b32 v[122:123], v23 offset0:74 offset1:107
	ds_read2_b32 v[124:125], v23 offset0:140 offset1:173
	ds_read2_b32 v[126:127], v23 offset0:206 offset1:239
	s_waitcnt lgkmcnt(0)
	v_cvt_pk_bf16_f32 v128, v120, v121
	v_cvt_pk_bf16_f32 v129, v122, v123
	v_cvt_pk_bf16_f32 v130, v124, v125
	v_cvt_pk_bf16_f32 v131, v126, v127
	global_store_dwordx4 v12, v[128:131], s[14:15]
	s_nop 1
	ds_read2_b32 v[120:121], v23 offset0:16 offset1:49
	ds_read2_b32 v[122:123], v23 offset0:82 offset1:115
	ds_read2_b32 v[124:125], v23 offset0:148 offset1:181
	ds_read2_b32 v[126:127], v23 offset0:214 offset1:247
	s_waitcnt lgkmcnt(0)
	v_cvt_pk_bf16_f32 v128, v120, v121
	v_cvt_pk_bf16_f32 v129, v122, v123
	v_cvt_pk_bf16_f32 v130, v124, v125
	v_cvt_pk_bf16_f32 v131, v126, v127
	global_store_dwordx4 v13, v[128:131], s[14:15]
	s_nop 1
	ds_read2_b32 v[120:121], v23 offset0:24 offset1:57
	ds_read2_b32 v[122:123], v23 offset0:90 offset1:123
	ds_read2_b32 v[124:125], v23 offset0:156 offset1:189
	ds_read2_b32 v[126:127], v23 offset0:222 offset1:255
	s_waitcnt lgkmcnt(0)
	v_cvt_pk_bf16_f32 v128, v120, v121
	v_cvt_pk_bf16_f32 v129, v122, v123
	v_cvt_pk_bf16_f32 v130, v124, v125
	v_cvt_pk_bf16_f32 v131, v126, v127
	global_store_dwordx4 v14, v[128:131], s[14:15]
	s_nop 1
	s_add_i32 s28, s18, 0xb40
	s_lshr_b32 s20, s28, 6
	s_and_b32 s21, s28, 63
	s_lshl_b32 s10, s20, 19
	s_lshl_b32 s11, s21, 7
	s_add_u32 s10, s10, s11
	s_add_u32 s10, s10, s6
	s_addc_u32 s11, s7, 0
	global_load_dwordx4 v[24:27], v3, s[10:11]
	global_load_dwordx4 v[28:31], v4, s[10:11]
	global_load_dwordx4 v[32:35], v5, s[10:11]
	global_load_dwordx4 v[36:39], v6, s[10:11]
	global_load_dwordx4 v[40:43], v7, s[10:11]
	global_load_dwordx4 v[44:47], v8, s[10:11]
	global_load_dwordx4 v[48:51], v9, s[10:11]
	global_load_dwordx4 v[52:55], v10, s[10:11]
	s_add_i32 s28, s18, 0x8c0
	s_lshr_b32 s20, s28, 6
	s_and_b32 s21, s28, 63
	s_mul_i32 s14, s21, 0x58000
	s_lshl_b32 s15, s20, 7
	s_add_u32 s14, s14, s15
	s_add_u32 s14, s14, s8
	s_addc_u32 s15, s9, 0
	s_waitcnt vmcnt(24)
	ds_write2_b32 v15, v56, v57 offset1:1
	ds_write2_b32 v15, v58, v59 offset0:2 offset1:3
	ds_write2_b32 v16, v60, v61 offset1:1
	ds_write2_b32 v16, v62, v63 offset0:2 offset1:3
	ds_write2_b32 v17, v64, v65 offset1:1
	ds_write2_b32 v17, v66, v67 offset0:2 offset1:3
	ds_write2_b32 v18, v68, v69 offset1:1
	ds_write2_b32 v18, v70, v71 offset0:2 offset1:3
	ds_write2_b32 v19, v72, v73 offset1:1
	ds_write2_b32 v19, v74, v75 offset0:2 offset1:3
	ds_write2_b32 v20, v76, v77 offset1:1
	ds_write2_b32 v20, v78, v79 offset0:2 offset1:3
	ds_write2_b32 v21, v80, v81 offset1:1
	ds_write2_b32 v21, v82, v83 offset0:2 offset1:3
	ds_write2_b32 v22, v84, v85 offset1:1
	ds_write2_b32 v22, v86, v87 offset0:2 offset1:3
	s_waitcnt lgkmcnt(0)
	ds_read2_b32 v[120:121], v23 offset0:0 offset1:33
	ds_read2_b32 v[122:123], v23 offset0:66 offset1:99
	ds_read2_b32 v[124:125], v23 offset0:132 offset1:165
	ds_read2_b32 v[126:127], v23 offset0:198 offset1:231
	s_waitcnt lgkmcnt(0)
	v_cvt_pk_bf16_f32 v128, v120, v121
	v_cvt_pk_bf16_f32 v129, v122, v123
	v_cvt_pk_bf16_f32 v130, v124, v125
	v_cvt_pk_bf16_f32 v131, v126, v127
	global_store_dwordx4 v11, v[128:131], s[14:15]
	s_nop 1
	ds_read2_b32 v[120:121], v23 offset0:8 offset1:41
	ds_read2_b32 v[122:123], v23 offset0:74 offset1:107
	ds_read2_b32 v[124:125], v23 offset0:140 offset1:173
	ds_read2_b32 v[126:127], v23 offset0:206 offset1:239
	s_waitcnt lgkmcnt(0)
	v_cvt_pk_bf16_f32 v128, v120, v121
	v_cvt_pk_bf16_f32 v129, v122, v123
	v_cvt_pk_bf16_f32 v130, v124, v125
	v_cvt_pk_bf16_f32 v131, v126, v127
	global_store_dwordx4 v12, v[128:131], s[14:15]
	s_nop 1
	ds_read2_b32 v[120:121], v23 offset0:16 offset1:49
	ds_read2_b32 v[122:123], v23 offset0:82 offset1:115
	ds_read2_b32 v[124:125], v23 offset0:148 offset1:181
	ds_read2_b32 v[126:127], v23 offset0:214 offset1:247
	s_waitcnt lgkmcnt(0)
	v_cvt_pk_bf16_f32 v128, v120, v121
	v_cvt_pk_bf16_f32 v129, v122, v123
	v_cvt_pk_bf16_f32 v130, v124, v125
	v_cvt_pk_bf16_f32 v131, v126, v127
	global_store_dwordx4 v13, v[128:131], s[14:15]
	s_nop 1
	ds_read2_b32 v[120:121], v23 offset0:24 offset1:57
	ds_read2_b32 v[122:123], v23 offset0:90 offset1:123
	ds_read2_b32 v[124:125], v23 offset0:156 offset1:189
	ds_read2_b32 v[126:127], v23 offset0:222 offset1:255
	s_waitcnt lgkmcnt(0)
; #define GAS __attribute__((address_space(1)))
; #define LAS __attribute__((address_space(3)))
; #define LDS_WAIT() asm volatile("s_waitcnt lgkmcnt(0)" ::: "memory")
; __device__ __forceinline__ unsigned pk2(float lo, float hi) { return f2bf(lo) | (f2bf(hi) << 16); }
;     if (ldt == 0) ldt = K;
;     asm volatile("" : "+v"(lane));
;     const int kb = item / nblk, nb = item % nblk, k0 = 64 * kb, n0 = 32 * nb;
;     { float wv[32];
;       const float* wp = W + (size_t)(k0 + (lane >> 5)) * ldw + n0 + (lane & 31);
; #pragma unroll
;       for (int i = 0; i < 32; ++i) wv[i] = wp[(size_t)(2 * i) * ldw];
; #pragma unroll
;       for (int i = 0; i < 32; ++i) scr[(2 * i + (lane >> 5)) * 33 + (lane & 31)] = wv[i]; }
;     LDS_WAIT(); asm volatile("" ::: "memory");
;     const int c = lane & 7;
;     const int r0 = (mode == 0) ? n0 : (256 * (n0 >> 7) + (n0 & 127) + (mode == 2 ? 128 : 0));
; #pragma unroll
;     for (int j = 0; j < 4; ++j) { const int n = (lane >> 3) + 8 * j; const LAS float* s = scr + (8 * c) * 33 + n;
;         v4u o; o.x = pk2(s[0 * 33], s[1 * 33]); o.y = pk2(s[2 * 33], s[3 * 33]); o.z = pk2(s[4 * 33], s[5 * 33]); o.w = pk2(s[6 * 33], s[7 * 33]);
;         *(GAS v4u*)(WT + (size_t)(r0 + n) * ldt + k0 + 8 * c) = o; }
;     LDS_WAIT(); asm volatile("" ::: "memory");
; }
	v_cvt_pk_bf16_f32 v128, v120, v121
	v_cvt_pk_bf16_f32 v129, v122, v123
	v_cvt_pk_bf16_f32 v130, v124, v125
	v_cvt_pk_bf16_f32 v131, v126, v127
	global_store_dwordx4 v14, v[128:131], s[14:15]
	s_nop 1
	s_add_i32 s28, s18, 0xc80
	s_lshr_b32 s20, s28, 6
	s_and_b32 s21, s28, 63
	s_lshl_b32 s10, s20, 19
	s_lshl_b32 s11, s21, 7
	s_add_u32 s10, s10, s11
	s_add_u32 s10, s10, s6
	s_addc_u32 s11, s7, 0
	global_load_dwordx4 v[56:59], v3, s[10:11]
	global_load_dwordx4 v[60:63], v4, s[10:11]
	global_load_dwordx4 v[64:67], v5, s[10:11]
	global_load_dwordx4 v[68:71], v6, s[10:11]
	global_load_dwordx4 v[72:75], v7, s[10:11]
	global_load_dwordx4 v[76:79], v8, s[10:11]
	global_load_dwordx4 v[80:83], v9, s[10:11]
	global_load_dwordx4 v[84:87], v10, s[10:11]
	s_add_i32 s28, s18, 0xa00
	s_lshr_b32 s20, s28, 6
	s_and_b32 s21, s28, 63
	s_mul_i32 s14, s21, 0x58000
	s_lshl_b32 s15, s20, 7
	s_add_u32 s14, s14, s15
	s_add_u32 s14, s14, s8
	s_addc_u32 s15, s9, 0
	s_waitcnt vmcnt(24)
	ds_write2_b32 v15, v88, v89 offset1:1
	ds_write2_b32 v15, v90, v91 offset0:2 offset1:3
	ds_write2_b32 v16, v92, v93 offset1:1
	ds_write2_b32 v16, v94, v95 offset0:2 offset1:3
	ds_write2_b32 v17, v96, v97 offset1:1
	ds_write2_b32 v17, v98, v99 offset0:2 offset1:3
	ds_write2_b32 v18, v100, v101 offset1:1
	ds_write2_b32 v18, v102, v103 offset0:2 offset1:3
	ds_write2_b32 v19, v104, v105 offset1:1
	ds_write2_b32 v19, v106, v107 offset0:2 offset1:3
	ds_write2_b32 v20, v108, v109 offset1:1
	ds_write2_b32 v20, v110, v111 offset0:2 offset1:3
	ds_write2_b32 v21, v112, v113 offset1:1
	ds_write2_b32 v21, v114, v115 offset0:2 offset1:3
	ds_write2_b32 v22, v116, v117 offset1:1
	ds_write2_b32 v22, v118, v119 offset0:2 offset1:3
	s_waitcnt lgkmcnt(0)
	ds_read2_b32 v[120:121], v23 offset0:0 offset1:33
	ds_read2_b32 v[122:123], v23 offset0:66 offset1:99
	ds_read2_b32 v[124:125], v23 offset0:132 offset1:165
	ds_read2_b32 v[126:127], v23 offset0:198 offset1:231
	s_waitcnt lgkmcnt(0)
	v_cvt_pk_bf16_f32 v128, v120, v121
	v_cvt_pk_bf16_f32 v129, v122, v123
	v_cvt_pk_bf16_f32 v130, v124, v125
	v_cvt_pk_bf16_f32 v131, v126, v127
	global_store_dwordx4 v11, v[128:131], s[14:15]
	s_nop 1
	ds_read2_b32 v[120:121], v23 offset0:8 offset1:41
	ds_read2_b32 v[122:123], v23 offset0:74 offset1:107
	ds_read2_b32 v[124:125], v23 offset0:140 offset1:173
	ds_read2_b32 v[126:127], v23 offset0:206 offset1:239
	s_waitcnt lgkmcnt(0)
	v_cvt_pk_bf16_f32 v128, v120, v121
	v_cvt_pk_bf16_f32 v129, v122, v123
	v_cvt_pk_bf16_f32 v130, v124, v125
	v_cvt_pk_bf16_f32 v131, v126, v127
	global_store_dwordx4 v12, v[128:131], s[14:15]
	s_nop 1
	ds_read2_b32 v[120:121], v23 offset0:16 offset1:49
	ds_read2_b32 v[122:123], v23 offset0:82 offset1:115
	ds_read2_b32 v[124:125], v23 offset0:148 offset1:181
	ds_read2_b32 v[126:127], v23 offset0:214 offset1:247
	s_waitcnt lgkmcnt(0)
	v_cvt_pk_bf16_f32 v128, v120, v121
	v_cvt_pk_bf16_f32 v129, v122, v123
	v_cvt_pk_bf16_f32 v130, v124, v125
	v_cvt_pk_bf16_f32 v131, v126, v127
	global_store_dwordx4 v13, v[128:131], s[14:15]
	s_nop 1
	ds_read2_b32 v[120:121], v23 offset0:24 offset1:57
	ds_read2_b32 v[122:123], v23 offset0:90 offset1:123
	ds_read2_b32 v[124:125], v23 offset0:156 offset1:189
	ds_read2_b32 v[126:127], v23 offset0:222 offset1:255
	s_waitcnt lgkmcnt(0)
	v_cvt_pk_bf16_f32 v128, v120, v121
	v_cvt_pk_bf16_f32 v129, v122, v123
	v_cvt_pk_bf16_f32 v130, v124, v125
	v_cvt_pk_bf16_f32 v131, v126, v127
	global_store_dwordx4 v14, v[128:131], s[14:15]
	s_nop 1
	s_add_i32 s28, s18, 0xdc0
	s_lshr_b32 s20, s28, 6
	s_and_b32 s21, s28, 63
	s_lshl_b32 s10, s20, 19
	s_lshl_b32 s11, s21, 7
	s_add_u32 s10, s10, s11
	s_add_u32 s10, s10, s6
	s_addc_u32 s11, s7, 0
	global_load_dwordx4 v[88:91], v3, s[10:11]
	global_load_dwordx4 v[92:95], v4, s[10:11]
	global_load_dwordx4 v[96:99], v5, s[10:11]
	global_load_dwordx4 v[100:103], v6, s[10:11]
	global_load_dwordx4 v[104:107], v7, s[10:11]
	global_load_dwordx4 v[108:111], v8, s[10:11]
	global_load_dwordx4 v[112:115], v9, s[10:11]
	global_load_dwordx4 v[116:119], v10, s[10:11]
	s_add_i32 s28, s18, 0xb40
	s_lshr_b32 s20, s28, 6
	s_and_b32 s21, s28, 63
	s_mul_i32 s14, s21, 0x58000
	s_lshl_b32 s15, s20, 7
	s_add_u32 s14, s14, s15
	s_add_u32 s14, s14, s8
	s_addc_u32 s15, s9, 0
	s_waitcnt vmcnt(24)
	ds_write2_b32 v15, v24, v25 offset1:1
	ds_write2_b32 v15, v26, v27 offset0:2 offset1:3
	ds_write2_b32 v16, v28, v29 offset1:1
	ds_write2_b32 v16, v30, v31 offset0:2 offset1:3
	ds_write2_b32 v17, v32, v33 offset1:1
	ds_write2_b32 v17, v34, v35 offset0:2 offset1:3
	ds_write2_b32 v18, v36, v37 offset1:1
	ds_write2_b32 v18, v38, v39 offset0:2 offset1:3
	ds_write2_b32 v19, v40, v41 offset1:1
	ds_write2_b32 v19, v42, v43 offset0:2 offset1:3
	ds_write2_b32 v20, v44, v45 offset1:1
	ds_write2_b32 v20, v46, v47 offset0:2 offset1:3
	ds_write2_b32 v21, v48, v49 offset1:1
	ds_write2_b32 v21, v50, v51 offset0:2 offset1:3
	ds_write2_b32 v22, v52, v53 offset1:1
	ds_write2_b32 v22, v54, v55 offset0:2 offset1:3
	s_waitcnt lgkmcnt(0)
	ds_read2_b32 v[120:121], v23 offset0:0 offset1:33
	ds_read2_b32 v[122:123], v23 offset0:66 offset1:99
	ds_read2_b32 v[124:125], v23 offset0:132 offset1:165
	ds_read2_b32 v[126:127], v23 offset0:198 offset1:231
	s_waitcnt lgkmcnt(0)
	v_cvt_pk_bf16_f32 v128, v120, v121
	v_cvt_pk_bf16_f32 v129, v122, v123
	v_cvt_pk_bf16_f32 v130, v124, v125
	v_cvt_pk_bf16_f32 v131, v126, v127
	global_store_dwordx4 v11, v[128:131], s[14:15]
	s_nop 1
	ds_read2_b32 v[120:121], v23 offset0:8 offset1:41
	ds_read2_b32 v[122:123], v23 offset0:74 offset1:107
	ds_read2_b32 v[124:125], v23 offset0:140 offset1:173
	ds_read2_b32 v[126:127], v23 offset0:206 offset1:239
	s_waitcnt lgkmcnt(0)
; #define GAS __attribute__((address_space(1)))
; #define LAS __attribute__((address_space(3)))
; #define LDS_WAIT() asm volatile("s_waitcnt lgkmcnt(0)" ::: "memory")
; __device__ __forceinline__ unsigned pk2(float lo, float hi) { return f2bf(lo) | (f2bf(hi) << 16); }
;     if (ldt == 0) ldt = K;
;     asm volatile("" : "+v"(lane));
;     const int kb = item / nblk, nb = item % nblk, k0 = 64 * kb, n0 = 32 * nb;
;     { float wv[32];
;       const float* wp = W + (size_t)(k0 + (lane >> 5)) * ldw + n0 + (lane & 31);
; #pragma unroll
;       for (int i = 0; i < 32; ++i) wv[i] = wp[(size_t)(2 * i) * ldw];
; #pragma unroll
;       for (int i = 0; i < 32; ++i) scr[(2 * i + (lane >> 5)) * 33 + (lane & 31)] = wv[i]; }
;     LDS_WAIT(); asm volatile("" ::: "memory");
;     const int c = lane & 7;
;     const int r0 = (mode == 0) ? n0 : (256 * (n0 >> 7) + (n0 & 127) + (mode == 2 ? 128 : 0));
; #pragma unroll
;     for (int j = 0; j < 4; ++j) { const int n = (lane >> 3) + 8 * j; const LAS float* s = scr + (8 * c) * 33 + n;
;         v4u o; o.x = pk2(s[0 * 33], s[1 * 33]); o.y = pk2(s[2 * 33], s[3 * 33]); o.z = pk2(s[4 * 33], s[5 * 33]); o.w = pk2(s[6 * 33], s[7 * 33]);
;         *(GAS v4u*)(WT + (size_t)(r0 + n) * ldt + k0 + 8 * c) = o; }
;     LDS_WAIT(); asm volatile("" ::: "memory");
; }
	v_cvt_pk_bf16_f32 v128, v120, v121
	v_cvt_pk_bf16_f32 v129, v122, v123
	v_cvt_pk_bf16_f32 v130, v124, v125
	v_cvt_pk_bf16_f32 v131, v126, v127
	global_store_dwordx4 v12, v[128:131], s[14:15]
	s_nop 1
	ds_read2_b32 v[120:121], v23 offset0:16 offset1:49
	ds_read2_b32 v[122:123], v23 offset0:82 offset1:115
	ds_read2_b32 v[124:125], v23 offset0:148 offset1:181
	ds_read2_b32 v[126:127], v23 offset0:214 offset1:247
	s_waitcnt lgkmcnt(0)
	v_cvt_pk_bf16_f32 v128, v120, v121
	v_cvt_pk_bf16_f32 v129, v122, v123
	v_cvt_pk_bf16_f32 v130, v124, v125
	v_cvt_pk_bf16_f32 v131, v126, v127
	global_store_dwordx4 v13, v[128:131], s[14:15]
	s_nop 1
	ds_read2_b32 v[120:121], v23 offset0:24 offset1:57
	ds_read2_b32 v[122:123], v23 offset0:90 offset1:123
	ds_read2_b32 v[124:125], v23 offset0:156 offset1:189
	ds_read2_b32 v[126:127], v23 offset0:222 offset1:255
	s_waitcnt lgkmcnt(0)
	v_cvt_pk_bf16_f32 v128, v120, v121
	v_cvt_pk_bf16_f32 v129, v122, v123
	v_cvt_pk_bf16_f32 v130, v124, v125
	v_cvt_pk_bf16_f32 v131, v126, v127
	global_store_dwordx4 v14, v[128:131], s[14:15]
	s_nop 1
	s_add_i32 s28, s18, 0xf00
	s_lshr_b32 s20, s28, 6
	s_and_b32 s21, s28, 63
	s_lshl_b32 s10, s20, 19
	s_lshl_b32 s11, s21, 7
	s_add_u32 s10, s10, s11
	s_add_u32 s10, s10, s6
	s_addc_u32 s11, s7, 0
	global_load_dwordx4 v[24:27], v3, s[10:11]
	global_load_dwordx4 v[28:31], v4, s[10:11]
	global_load_dwordx4 v[32:35], v5, s[10:11]
	global_load_dwordx4 v[36:39], v6, s[10:11]
	global_load_dwordx4 v[40:43], v7, s[10:11]
	global_load_dwordx4 v[44:47], v8, s[10:11]
	global_load_dwordx4 v[48:51], v9, s[10:11]
	global_load_dwordx4 v[52:55], v10, s[10:11]
	s_add_i32 s28, s18, 0xc80
	s_lshr_b32 s20, s28, 6
	s_and_b32 s21, s28, 63
	s_mul_i32 s14, s21, 0x58000
	s_lshl_b32 s15, s20, 7
	s_add_u32 s14, s14, s15
	s_add_u32 s14, s14, s8
	s_addc_u32 s15, s9, 0
	s_waitcnt vmcnt(24)
	ds_write2_b32 v15, v56, v57 offset1:1
	ds_write2_b32 v15, v58, v59 offset0:2 offset1:3
	ds_write2_b32 v16, v60, v61 offset1:1
	ds_write2_b32 v16, v62, v63 offset0:2 offset1:3
	ds_write2_b32 v17, v64, v65 offset1:1
	ds_write2_b32 v17, v66, v67 offset0:2 offset1:3
	ds_write2_b32 v18, v68, v69 offset1:1
	ds_write2_b32 v18, v70, v71 offset0:2 offset1:3
	ds_write2_b32 v19, v72, v73 offset1:1
	ds_write2_b32 v19, v74, v75 offset0:2 offset1:3
	ds_write2_b32 v20, v76, v77 offset1:1
	ds_write2_b32 v20, v78, v79 offset0:2 offset1:3
	ds_write2_b32 v21, v80, v81 offset1:1
	ds_write2_b32 v21, v82, v83 offset0:2 offset1:3
	ds_write2_b32 v22, v84, v85 offset1:1
	ds_write2_b32 v22, v86, v87 offset0:2 offset1:3
	s_waitcnt lgkmcnt(0)
	ds_read2_b32 v[120:121], v23 offset0:0 offset1:33
	ds_read2_b32 v[122:123], v23 offset0:66 offset1:99
	ds_read2_b32 v[124:125], v23 offset0:132 offset1:165
	ds_read2_b32 v[126:127], v23 offset0:198 offset1:231
	s_waitcnt lgkmcnt(0)
	v_cvt_pk_bf16_f32 v128, v120, v121
	v_cvt_pk_bf16_f32 v129, v122, v123
	v_cvt_pk_bf16_f32 v130, v124, v125
	v_cvt_pk_bf16_f32 v131, v126, v127
	global_store_dwordx4 v11, v[128:131], s[14:15]
	s_nop 1
	ds_read2_b32 v[120:121], v23 offset0:8 offset1:41
	ds_read2_b32 v[122:123], v23 offset0:74 offset1:107
	ds_read2_b32 v[124:125], v23 offset0:140 offset1:173
	ds_read2_b32 v[126:127], v23 offset0:206 offset1:239
	s_waitcnt lgkmcnt(0)
	v_cvt_pk_bf16_f32 v128, v120, v121
	v_cvt_pk_bf16_f32 v129, v122, v123
	v_cvt_pk_bf16_f32 v130, v124, v125
	v_cvt_pk_bf16_f32 v131, v126, v127
	global_store_dwordx4 v12, v[128:131], s[14:15]
	s_nop 1
	ds_read2_b32 v[120:121], v23 offset0:16 offset1:49
	ds_read2_b32 v[122:123], v23 offset0:82 offset1:115
	ds_read2_b32 v[124:125], v23 offset0:148 offset1:181
	ds_read2_b32 v[126:127], v23 offset0:214 offset1:247
	s_waitcnt lgkmcnt(0)
	v_cvt_pk_bf16_f32 v128, v120, v121
	v_cvt_pk_bf16_f32 v129, v122, v123
	v_cvt_pk_bf16_f32 v130, v124, v125
	v_cvt_pk_bf16_f32 v131, v126, v127
	global_store_dwordx4 v13, v[128:131], s[14:15]
	s_nop 1
	ds_read2_b32 v[120:121], v23 offset0:24 offset1:57
	ds_read2_b32 v[122:123], v23 offset0:90 offset1:123
	ds_read2_b32 v[124:125], v23 offset0:156 offset1:189
	ds_read2_b32 v[126:127], v23 offset0:222 offset1:255
	s_waitcnt lgkmcnt(0)
	v_cvt_pk_bf16_f32 v128, v120, v121
	v_cvt_pk_bf16_f32 v129, v122, v123
	v_cvt_pk_bf16_f32 v130, v124, v125
	v_cvt_pk_bf16_f32 v131, v126, v127
	global_store_dwordx4 v14, v[128:131], s[14:15]
	s_nop 1
	s_add_i32 s28, s18, 0x1040
	s_lshr_b32 s20, s28, 6
	s_and_b32 s21, s28, 63
	s_lshl_b32 s10, s20, 19
	s_lshl_b32 s11, s21, 7
	s_add_u32 s10, s10, s11
	s_add_u32 s10, s10, s6
	s_addc_u32 s11, s7, 0
	global_load_dwordx4 v[56:59], v3, s[10:11]
	global_load_dwordx4 v[60:63], v4, s[10:11]
	global_load_dwordx4 v[64:67], v5, s[10:11]
	global_load_dwordx4 v[68:71], v6, s[10:11]
	global_load_dwordx4 v[72:75], v7, s[10:11]
	global_load_dwordx4 v[76:79], v8, s[10:11]
	global_load_dwordx4 v[80:83], v9, s[10:11]
	global_load_dwordx4 v[84:87], v10, s[10:11]
	s_add_i32 s28, s18, 0xdc0
	s_lshr_b32 s20, s28, 6
	s_and_b32 s21, s28, 63
	s_mul_i32 s14, s21, 0x58000
	s_lshl_b32 s15, s20, 7
	s_add_u32 s14, s14, s15
	s_add_u32 s14, s14, s8
	s_addc_u32 s15, s9, 0
	s_waitcnt vmcnt(24)
	ds_write2_b32 v15, v88, v89 offset1:1
	ds_write2_b32 v15, v90, v91 offset0:2 offset1:3
	ds_write2_b32 v16, v92, v93 offset1:1
	ds_write2_b32 v16, v94, v95 offset0:2 offset1:3
	ds_write2_b32 v17, v96, v97 offset1:1
	ds_write2_b32 v17, v98, v99 offset0:2 offset1:3
	ds_write2_b32 v18, v100, v101 offset1:1
	ds_write2_b32 v18, v102, v103 offset0:2 offset1:3
	ds_write2_b32 v19, v104, v105 offset1:1
	ds_write2_b32 v19, v106, v107 offset0:2 offset1:3
	ds_write2_b32 v20, v108, v109 offset1:1
	ds_write2_b32 v20, v110, v111 offset0:2 offset1:3
	ds_write2_b32 v21, v112, v113 offset1:1
	ds_write2_b32 v21, v114, v115 offset0:2 offset1:3
	ds_write2_b32 v22, v116, v117 offset1:1
	ds_write2_b32 v22, v118, v119 offset0:2 offset1:3
	s_waitcnt lgkmcnt(0)
; #define GAS __attribute__((address_space(1)))
; #define LAS __attribute__((address_space(3)))
; #define LDS_WAIT() asm volatile("s_waitcnt lgkmcnt(0)" ::: "memory")
; __device__ __forceinline__ unsigned pk2(float lo, float hi) { return f2bf(lo) | (f2bf(hi) << 16); }
;     if (ldt == 0) ldt = K;
;     asm volatile("" : "+v"(lane));
;     const int kb = item / nblk, nb = item % nblk, k0 = 64 * kb, n0 = 32 * nb;
;     { float wv[32];
;       const float* wp = W + (size_t)(k0 + (lane >> 5)) * ldw + n0 + (lane & 31);
; #pragma unroll
;       for (int i = 0; i < 32; ++i) wv[i] = wp[(size_t)(2 * i) * ldw];
; #pragma unroll
;       for (int i = 0; i < 32; ++i) scr[(2 * i + (lane >> 5)) * 33 + (lane & 31)] = wv[i]; }
;     LDS_WAIT(); asm volatile("" ::: "memory");
;     const int c = lane & 7;
;     const int r0 = (mode == 0) ? n0 : (256 * (n0 >> 7) + (n0 & 127) + (mode == 2 ? 128 : 0));
; #pragma unroll
;     for (int j = 0; j < 4; ++j) { const int n = (lane >> 3) + 8 * j; const LAS float* s = scr + (8 * c) * 33 + n;
;         v4u o; o.x = pk2(s[0 * 33], s[1 * 33]); o.y = pk2(s[2 * 33], s[3 * 33]); o.z = pk2(s[4 * 33], s[5 * 33]); o.w = pk2(s[6 * 33], s[7 * 33]);
;         *(GAS v4u*)(WT + (size_t)(r0 + n) * ldt + k0 + 8 * c) = o; }
;     LDS_WAIT(); asm volatile("" ::: "memory");
; }
	ds_read2_b32 v[120:121], v23 offset0:0 offset1:33
	ds_read2_b32 v[122:123], v23 offset0:66 offset1:99
	ds_read2_b32 v[124:125], v23 offset0:132 offset1:165
	ds_read2_b32 v[126:127], v23 offset0:198 offset1:231
	s_waitcnt lgkmcnt(0)
	v_cvt_pk_bf16_f32 v128, v120, v121
	v_cvt_pk_bf16_f32 v129, v122, v123
	v_cvt_pk_bf16_f32 v130, v124, v125
	v_cvt_pk_bf16_f32 v131, v126, v127
	global_store_dwordx4 v11, v[128:131], s[14:15]
	s_nop 1
	ds_read2_b32 v[120:121], v23 offset0:8 offset1:41
	ds_read2_b32 v[122:123], v23 offset0:74 offset1:107
	ds_read2_b32 v[124:125], v23 offset0:140 offset1:173
	ds_read2_b32 v[126:127], v23 offset0:206 offset1:239
	s_waitcnt lgkmcnt(0)
	v_cvt_pk_bf16_f32 v128, v120, v121
	v_cvt_pk_bf16_f32 v129, v122, v123
	v_cvt_pk_bf16_f32 v130, v124, v125
	v_cvt_pk_bf16_f32 v131, v126, v127
	global_store_dwordx4 v12, v[128:131], s[14:15]
	s_nop 1
	ds_read2_b32 v[120:121], v23 offset0:16 offset1:49
	ds_read2_b32 v[122:123], v23 offset0:82 offset1:115
	ds_read2_b32 v[124:125], v23 offset0:148 offset1:181
	ds_read2_b32 v[126:127], v23 offset0:214 offset1:247
	s_waitcnt lgkmcnt(0)
	v_cvt_pk_bf16_f32 v128, v120, v121
	v_cvt_pk_bf16_f32 v129, v122, v123
	v_cvt_pk_bf16_f32 v130, v124, v125
	v_cvt_pk_bf16_f32 v131, v126, v127
	global_store_dwordx4 v13, v[128:131], s[14:15]
	s_nop 1
	ds_read2_b32 v[120:121], v23 offset0:24 offset1:57
	ds_read2_b32 v[122:123], v23 offset0:90 offset1:123
	ds_read2_b32 v[124:125], v23 offset0:156 offset1:189
	ds_read2_b32 v[126:127], v23 offset0:222 offset1:255
	s_waitcnt lgkmcnt(0)
	v_cvt_pk_bf16_f32 v128, v120, v121
	v_cvt_pk_bf16_f32 v129, v122, v123
	v_cvt_pk_bf16_f32 v130, v124, v125
	v_cvt_pk_bf16_f32 v131, v126, v127
	global_store_dwordx4 v14, v[128:131], s[14:15]
	s_nop 1
	s_add_i32 s28, s18, 0x1180
	s_lshr_b32 s20, s28, 6
	s_and_b32 s21, s28, 63
	s_lshl_b32 s10, s20, 19
	s_lshl_b32 s11, s21, 7
	s_add_u32 s10, s10, s11
	s_add_u32 s10, s10, s6
	s_addc_u32 s11, s7, 0
	global_load_dwordx4 v[88:91], v3, s[10:11]
	global_load_dwordx4 v[92:95], v4, s[10:11]
	global_load_dwordx4 v[96:99], v5, s[10:11]
	global_load_dwordx4 v[100:103], v6, s[10:11]
	global_load_dwordx4 v[104:107], v7, s[10:11]
	global_load_dwordx4 v[108:111], v8, s[10:11]
	global_load_dwordx4 v[112:115], v9, s[10:11]
	global_load_dwordx4 v[116:119], v10, s[10:11]
	s_add_i32 s28, s18, 0xf00
	s_lshr_b32 s20, s28, 6
	s_and_b32 s21, s28, 63
	s_mul_i32 s14, s21, 0x58000
	s_lshl_b32 s15, s20, 7
	s_add_u32 s14, s14, s15
	s_add_u32 s14, s14, s8
	s_addc_u32 s15, s9, 0
	s_waitcnt vmcnt(24)
	ds_write2_b32 v15, v24, v25 offset1:1
	ds_write2_b32 v15, v26, v27 offset0:2 offset1:3
	ds_write2_b32 v16, v28, v29 offset1:1
	ds_write2_b32 v16, v30, v31 offset0:2 offset1:3
	ds_write2_b32 v17, v32, v33 offset1:1
	ds_write2_b32 v17, v34, v35 offset0:2 offset1:3
	ds_write2_b32 v18, v36, v37 offset1:1
	ds_write2_b32 v18, v38, v39 offset0:2 offset1:3
	ds_write2_b32 v19, v40, v41 offset1:1
	ds_write2_b32 v19, v42, v43 offset0:2 offset1:3
	ds_write2_b32 v20, v44, v45 offset1:1
	ds_write2_b32 v20, v46, v47 offset0:2 offset1:3
	ds_write2_b32 v21, v48, v49 offset1:1
	ds_write2_b32 v21, v50, v51 offset0:2 offset1:3
	ds_write2_b32 v22, v52, v53 offset1:1
	ds_write2_b32 v22, v54, v55 offset0:2 offset1:3
	s_waitcnt lgkmcnt(0)
	ds_read2_b32 v[120:121], v23 offset0:0 offset1:33
	ds_read2_b32 v[122:123], v23 offset0:66 offset1:99
	ds_read2_b32 v[124:125], v23 offset0:132 offset1:165
	ds_read2_b32 v[126:127], v23 offset0:198 offset1:231
	s_waitcnt lgkmcnt(0)
	v_cvt_pk_bf16_f32 v128, v120, v121
	v_cvt_pk_bf16_f32 v129, v122, v123
	v_cvt_pk_bf16_f32 v130, v124, v125
	v_cvt_pk_bf16_f32 v131, v126, v127
	global_store_dwordx4 v11, v[128:131], s[14:15]
	s_nop 1
	ds_read2_b32 v[120:121], v23 offset0:8 offset1:41
	ds_read2_b32 v[122:123], v23 offset0:74 offset1:107
	ds_read2_b32 v[124:125], v23 offset0:140 offset1:173
	ds_read2_b32 v[126:127], v23 offset0:206 offset1:239
	s_waitcnt lgkmcnt(0)
	v_cvt_pk_bf16_f32 v128, v120, v121
	v_cvt_pk_bf16_f32 v129, v122, v123
	v_cvt_pk_bf16_f32 v130, v124, v125
	v_cvt_pk_bf16_f32 v131, v126, v127
	global_store_dwordx4 v12, v[128:131], s[14:15]
	s_nop 1
	ds_read2_b32 v[120:121], v23 offset0:16 offset1:49
	ds_read2_b32 v[122:123], v23 offset0:82 offset1:115
	ds_read2_b32 v[124:125], v23 offset0:148 offset1:181
	ds_read2_b32 v[126:127], v23 offset0:214 offset1:247
	s_waitcnt lgkmcnt(0)
	v_cvt_pk_bf16_f32 v128, v120, v121
	v_cvt_pk_bf16_f32 v129, v122, v123
	v_cvt_pk_bf16_f32 v130, v124, v125
	v_cvt_pk_bf16_f32 v131, v126, v127
	global_store_dwordx4 v13, v[128:131], s[14:15]
	s_nop 1
	ds_read2_b32 v[120:121], v23 offset0:24 offset1:57
	ds_read2_b32 v[122:123], v23 offset0:90 offset1:123
	ds_read2_b32 v[124:125], v23 offset0:156 offset1:189
	ds_read2_b32 v[126:127], v23 offset0:222 offset1:255
	s_waitcnt lgkmcnt(0)
	v_cvt_pk_bf16_f32 v128, v120, v121
	v_cvt_pk_bf16_f32 v129, v122, v123
	v_cvt_pk_bf16_f32 v130, v124, v125
	v_cvt_pk_bf16_f32 v131, v126, v127
	global_store_dwordx4 v14, v[128:131], s[14:15]
	s_nop 1
	s_add_i32 s28, s18, 0x12c0
	s_lshr_b32 s20, s28, 6
	s_and_b32 s21, s28, 63
	s_lshl_b32 s10, s20, 19
	s_lshl_b32 s11, s21, 7
	s_add_u32 s10, s10, s11
	s_add_u32 s10, s10, s6
	s_addc_u32 s11, s7, 0
	global_load_dwordx4 v[24:27], v3, s[10:11]
	global_load_dwordx4 v[28:31], v4, s[10:11]
	global_load_dwordx4 v[32:35], v5, s[10:11]
	global_load_dwordx4 v[36:39], v6, s[10:11]
	global_load_dwordx4 v[40:43], v7, s[10:11]
	global_load_dwordx4 v[44:47], v8, s[10:11]
	global_load_dwordx4 v[48:51], v9, s[10:11]
	global_load_dwordx4 v[52:55], v10, s[10:11]
	s_add_i32 s28, s18, 0x1040
	s_lshr_b32 s20, s28, 6
	s_and_b32 s21, s28, 63
	s_mul_i32 s14, s21, 0x58000
	s_lshl_b32 s15, s20, 7
	s_add_u32 s14, s14, s15
	s_add_u32 s14, s14, s8
	s_addc_u32 s15, s9, 0
	s_waitcnt vmcnt(24)
; #define GAS __attribute__((address_space(1)))
; #define LAS __attribute__((address_space(3)))
; #define LDS_WAIT() asm volatile("s_waitcnt lgkmcnt(0)" ::: "memory")
; __device__ __forceinline__ unsigned pk2(float lo, float hi) { return f2bf(lo) | (f2bf(hi) << 16); }
;     if (ldt == 0) ldt = K;
;     asm volatile("" : "+v"(lane));
;     const int kb = item / nblk, nb = item % nblk, k0 = 64 * kb, n0 = 32 * nb;
;     { float wv[32];
;       const float* wp = W + (size_t)(k0 + (lane >> 5)) * ldw + n0 + (lane & 31);
; #pragma unroll
;       for (int i = 0; i < 32; ++i) wv[i] = wp[(size_t)(2 * i) * ldw];
; #pragma unroll
;       for (int i = 0; i < 32; ++i) scr[(2 * i + (lane >> 5)) * 33 + (lane & 31)] = wv[i]; }
;     LDS_WAIT(); asm volatile("" ::: "memory");
;     const int c = lane & 7;
;     const int r0 = (mode == 0) ? n0 : (256 * (n0 >> 7) + (n0 & 127) + (mode == 2 ? 128 : 0));
; #pragma unroll
;     for (int j = 0; j < 4; ++j) { const int n = (lane >> 3) + 8 * j; const LAS float* s = scr + (8 * c) * 33 + n;
;         v4u o; o.x = pk2(s[0 * 33], s[1 * 33]); o.y = pk2(s[2 * 33], s[3 * 33]); o.z = pk2(s[4 * 33], s[5 * 33]); o.w = pk2(s[6 * 33], s[7 * 33]);
;         *(GAS v4u*)(WT + (size_t)(r0 + n) * ldt + k0 + 8 * c) = o; }
;     LDS_WAIT(); asm volatile("" ::: "memory");
; }
	ds_write2_b32 v15, v56, v57 offset1:1
	ds_write2_b32 v15, v58, v59 offset0:2 offset1:3
	ds_write2_b32 v16, v60, v61 offset1:1
	ds_write2_b32 v16, v62, v63 offset0:2 offset1:3
	ds_write2_b32 v17, v64, v65 offset1:1
	ds_write2_b32 v17, v66, v67 offset0:2 offset1:3
	ds_write2_b32 v18, v68, v69 offset1:1
	ds_write2_b32 v18, v70, v71 offset0:2 offset1:3
	ds_write2_b32 v19, v72, v73 offset1:1
	ds_write2_b32 v19, v74, v75 offset0:2 offset1:3
	ds_write2_b32 v20, v76, v77 offset1:1
	ds_write2_b32 v20, v78, v79 offset0:2 offset1:3
	ds_write2_b32 v21, v80, v81 offset1:1
	ds_write2_b32 v21, v82, v83 offset0:2 offset1:3
	ds_write2_b32 v22, v84, v85 offset1:1
	ds_write2_b32 v22, v86, v87 offset0:2 offset1:3
	s_waitcnt lgkmcnt(0)
	ds_read2_b32 v[120:121], v23 offset0:0 offset1:33
	ds_read2_b32 v[122:123], v23 offset0:66 offset1:99
	ds_read2_b32 v[124:125], v23 offset0:132 offset1:165
	ds_read2_b32 v[126:127], v23 offset0:198 offset1:231
	s_waitcnt lgkmcnt(0)
	v_cvt_pk_bf16_f32 v128, v120, v121
	v_cvt_pk_bf16_f32 v129, v122, v123
	v_cvt_pk_bf16_f32 v130, v124, v125
	v_cvt_pk_bf16_f32 v131, v126, v127
	global_store_dwordx4 v11, v[128:131], s[14:15]
	s_nop 1
	ds_read2_b32 v[120:121], v23 offset0:8 offset1:41
	ds_read2_b32 v[122:123], v23 offset0:74 offset1:107
	ds_read2_b32 v[124:125], v23 offset0:140 offset1:173
	ds_read2_b32 v[126:127], v23 offset0:206 offset1:239
	s_waitcnt lgkmcnt(0)
	v_cvt_pk_bf16_f32 v128, v120, v121
	v_cvt_pk_bf16_f32 v129, v122, v123
	v_cvt_pk_bf16_f32 v130, v124, v125
	v_cvt_pk_bf16_f32 v131, v126, v127
	global_store_dwordx4 v12, v[128:131], s[14:15]
	s_nop 1
	ds_read2_b32 v[120:121], v23 offset0:16 offset1:49
	ds_read2_b32 v[122:123], v23 offset0:82 offset1:115
	ds_read2_b32 v[124:125], v23 offset0:148 offset1:181
	ds_read2_b32 v[126:127], v23 offset0:214 offset1:247
	s_waitcnt lgkmcnt(0)
	v_cvt_pk_bf16_f32 v128, v120, v121
	v_cvt_pk_bf16_f32 v129, v122, v123
	v_cvt_pk_bf16_f32 v130, v124, v125
	v_cvt_pk_bf16_f32 v131, v126, v127
	global_store_dwordx4 v13, v[128:131], s[14:15]
	s_nop 1
	ds_read2_b32 v[120:121], v23 offset0:24 offset1:57
	ds_read2_b32 v[122:123], v23 offset0:90 offset1:123
	ds_read2_b32 v[124:125], v23 offset0:156 offset1:189
	ds_read2_b32 v[126:127], v23 offset0:222 offset1:255
	s_waitcnt lgkmcnt(0)
	v_cvt_pk_bf16_f32 v128, v120, v121
	v_cvt_pk_bf16_f32 v129, v122, v123
	v_cvt_pk_bf16_f32 v130, v124, v125
	v_cvt_pk_bf16_f32 v131, v126, v127
	global_store_dwordx4 v14, v[128:131], s[14:15]
	s_nop 1
	s_add_i32 s28, s18, 0x1400
	s_lshr_b32 s20, s28, 6
	s_and_b32 s21, s28, 63
	s_lshl_b32 s10, s20, 19
	s_lshl_b32 s11, s21, 7
	s_add_u32 s10, s10, s11
	s_add_u32 s10, s10, s6
	s_addc_u32 s11, s7, 0
	global_load_dwordx4 v[56:59], v3, s[10:11]
	global_load_dwordx4 v[60:63], v4, s[10:11]
	global_load_dwordx4 v[64:67], v5, s[10:11]
	global_load_dwordx4 v[68:71], v6, s[10:11]
	global_load_dwordx4 v[72:75], v7, s[10:11]
	global_load_dwordx4 v[76:79], v8, s[10:11]
	global_load_dwordx4 v[80:83], v9, s[10:11]
	global_load_dwordx4 v[84:87], v10, s[10:11]
	s_add_i32 s28, s18, 0x1180
	s_lshr_b32 s20, s28, 6
	s_and_b32 s21, s28, 63
	s_mul_i32 s14, s21, 0x58000
	s_lshl_b32 s15, s20, 7
	s_add_u32 s14, s14, s15
	s_add_u32 s14, s14, s8
	s_addc_u32 s15, s9, 0
	s_waitcnt vmcnt(24)
	ds_write2_b32 v15, v88, v89 offset1:1
	ds_write2_b32 v15, v90, v91 offset0:2 offset1:3
	ds_write2_b32 v16, v92, v93 offset1:1
	ds_write2_b32 v16, v94, v95 offset0:2 offset1:3
	ds_write2_b32 v17, v96, v97 offset1:1
	ds_write2_b32 v17, v98, v99 offset0:2 offset1:3
	ds_write2_b32 v18, v100, v101 offset1:1
	ds_write2_b32 v18, v102, v103 offset0:2 offset1:3
	ds_write2_b32 v19, v104, v105 offset1:1
	ds_write2_b32 v19, v106, v107 offset0:2 offset1:3
	ds_write2_b32 v20, v108, v109 offset1:1
	ds_write2_b32 v20, v110, v111 offset0:2 offset1:3
	ds_write2_b32 v21, v112, v113 offset1:1
	ds_write2_b32 v21, v114, v115 offset0:2 offset1:3
	ds_write2_b32 v22, v116, v117 offset1:1
	ds_write2_b32 v22, v118, v119 offset0:2 offset1:3
	s_waitcnt lgkmcnt(0)
	ds_read2_b32 v[120:121], v23 offset0:0 offset1:33
	ds_read2_b32 v[122:123], v23 offset0:66 offset1:99
	ds_read2_b32 v[124:125], v23 offset0:132 offset1:165
	ds_read2_b32 v[126:127], v23 offset0:198 offset1:231
	s_waitcnt lgkmcnt(0)
	v_cvt_pk_bf16_f32 v128, v120, v121
	v_cvt_pk_bf16_f32 v129, v122, v123
	v_cvt_pk_bf16_f32 v130, v124, v125
	v_cvt_pk_bf16_f32 v131, v126, v127
	global_store_dwordx4 v11, v[128:131], s[14:15]
	s_nop 1
	ds_read2_b32 v[120:121], v23 offset0:8 offset1:41
	ds_read2_b32 v[122:123], v23 offset0:74 offset1:107
	ds_read2_b32 v[124:125], v23 offset0:140 offset1:173
	ds_read2_b32 v[126:127], v23 offset0:206 offset1:239
	s_waitcnt lgkmcnt(0)
	v_cvt_pk_bf16_f32 v128, v120, v121
	v_cvt_pk_bf16_f32 v129, v122, v123
	v_cvt_pk_bf16_f32 v130, v124, v125
	v_cvt_pk_bf16_f32 v131, v126, v127
	global_store_dwordx4 v12, v[128:131], s[14:15]
	s_nop 1
	ds_read2_b32 v[120:121], v23 offset0:16 offset1:49
	ds_read2_b32 v[122:123], v23 offset0:82 offset1:115
	ds_read2_b32 v[124:125], v23 offset0:148 offset1:181
	ds_read2_b32 v[126:127], v23 offset0:214 offset1:247
	s_waitcnt lgkmcnt(0)
	v_cvt_pk_bf16_f32 v128, v120, v121
	v_cvt_pk_bf16_f32 v129, v122, v123
	v_cvt_pk_bf16_f32 v130, v124, v125
	v_cvt_pk_bf16_f32 v131, v126, v127
	global_store_dwordx4 v13, v[128:131], s[14:15]
	s_nop 1
	ds_read2_b32 v[120:121], v23 offset0:24 offset1:57
	ds_read2_b32 v[122:123], v23 offset0:90 offset1:123
	ds_read2_b32 v[124:125], v23 offset0:156 offset1:189
	ds_read2_b32 v[126:127], v23 offset0:222 offset1:255
	s_waitcnt lgkmcnt(0)
	v_cvt_pk_bf16_f32 v128, v120, v121
	v_cvt_pk_bf16_f32 v129, v122, v123
	v_cvt_pk_bf16_f32 v130, v124, v125
	v_cvt_pk_bf16_f32 v131, v126, v127
	global_store_dwordx4 v14, v[128:131], s[14:15]
	s_nop 1
	s_cmpk_lt_i32 s18, 0xc0
	s_cbranch_scc0 .Ltr1dP1_no14
	s_add_i32 s28, s18, 0x1540
	s_lshr_b32 s20, s28, 6
	s_and_b32 s21, s28, 63
	s_lshl_b32 s10, s20, 19
	s_lshl_b32 s11, s21, 7
	s_add_u32 s10, s10, s11
	s_add_u32 s10, s10, s6
	s_addc_u32 s11, s7, 0
	global_load_dwordx4 v[88:91], v3, s[10:11]
	global_load_dwordx4 v[92:95], v4, s[10:11]
	global_load_dwordx4 v[96:99], v5, s[10:11]
	global_load_dwordx4 v[100:103], v6, s[10:11]
	global_load_dwordx4 v[104:107], v7, s[10:11]
	global_load_dwordx4 v[108:111], v8, s[10:11]
	global_load_dwordx4 v[112:115], v9, s[10:11]
	global_load_dwordx4 v[116:119], v10, s[10:11]
; #define GAS __attribute__((address_space(1)))
; #define LAS __attribute__((address_space(3)))
; #define LDS_WAIT() asm volatile("s_waitcnt lgkmcnt(0)" ::: "memory")
; __device__ __forceinline__ unsigned pk2(float lo, float hi) { return f2bf(lo) | (f2bf(hi) << 16); }
;     ...
;     for (int j = 0; j < 4; ++j) { const int n = (lane >> 3) + 8 * j; const LAS float* s = scr + (8 * c) * 33 + n;
;         v4u o; o.x = pk2(s[0 * 33], s[1 * 33]); o.y = pk2(s[2 * 33], s[3 * 33]); o.z = pk2(s[4 * 33], s[5 * 33]); o.w = pk2(s[6 * 33], s[7 * 33]);
;         *(GAS v4u*)(WT + (size_t)(r0 + n) * ldt + k0 + 8 * c) = o; }
;     LDS_WAIT(); asm volatile("" ::: "memory");
; }
.Ltr1dP1_no14:
	s_add_i32 s28, s18, 0x12c0
	s_lshr_b32 s20, s28, 6
	s_and_b32 s21, s28, 63
	s_mul_i32 s14, s21, 0x58000
	s_lshl_b32 s15, s20, 7
	s_add_u32 s14, s14, s15
	s_add_u32 s14, s14, s8
	s_addc_u32 s15, s9, 0
	s_waitcnt vmcnt(16)
	ds_write2_b32 v15, v24, v25 offset1:1
	ds_write2_b32 v15, v26, v27 offset0:2 offset1:3
	ds_write2_b32 v16, v28, v29 offset1:1
	ds_write2_b32 v16, v30, v31 offset0:2 offset1:3
	ds_write2_b32 v17, v32, v33 offset1:1
	ds_write2_b32 v17, v34, v35 offset0:2 offset1:3
	ds_write2_b32 v18, v36, v37 offset1:1
	ds_write2_b32 v18, v38, v39 offset0:2 offset1:3
	ds_write2_b32 v19, v40, v41 offset1:1
	ds_write2_b32 v19, v42, v43 offset0:2 offset1:3
	ds_write2_b32 v20, v44, v45 offset1:1
	ds_write2_b32 v20, v46, v47 offset0:2 offset1:3
	ds_write2_b32 v21, v48, v49 offset1:1
	ds_write2_b32 v21, v50, v51 offset0:2 offset1:3
	ds_write2_b32 v22, v52, v53 offset1:1
	ds_write2_b32 v22, v54, v55 offset0:2 offset1:3
	s_waitcnt lgkmcnt(0)
	ds_read2_b32 v[120:121], v23 offset0:0 offset1:33
	ds_read2_b32 v[122:123], v23 offset0:66 offset1:99
	ds_read2_b32 v[124:125], v23 offset0:132 offset1:165
	ds_read2_b32 v[126:127], v23 offset0:198 offset1:231
	s_waitcnt lgkmcnt(0)
	v_cvt_pk_bf16_f32 v128, v120, v121
	v_cvt_pk_bf16_f32 v129, v122, v123
	v_cvt_pk_bf16_f32 v130, v124, v125
	v_cvt_pk_bf16_f32 v131, v126, v127
	global_store_dwordx4 v11, v[128:131], s[14:15]
	s_nop 1
	ds_read2_b32 v[120:121], v23 offset0:8 offset1:41
	ds_read2_b32 v[122:123], v23 offset0:74 offset1:107
	ds_read2_b32 v[124:125], v23 offset0:140 offset1:173
	ds_read2_b32 v[126:127], v23 offset0:206 offset1:239
	s_waitcnt lgkmcnt(0)
	v_cvt_pk_bf16_f32 v128, v120, v121
	v_cvt_pk_bf16_f32 v129, v122, v123
	v_cvt_pk_bf16_f32 v130, v124, v125
	v_cvt_pk_bf16_f32 v131, v126, v127
	global_store_dwordx4 v12, v[128:131], s[14:15]
	s_nop 1
	ds_read2_b32 v[120:121], v23 offset0:16 offset1:49
	ds_read2_b32 v[122:123], v23 offset0:82 offset1:115
	ds_read2_b32 v[124:125], v23 offset0:148 offset1:181
	ds_read2_b32 v[126:127], v23 offset0:214 offset1:247
	s_waitcnt lgkmcnt(0)
	v_cvt_pk_bf16_f32 v128, v120, v121
	v_cvt_pk_bf16_f32 v129, v122, v123
	v_cvt_pk_bf16_f32 v130, v124, v125
	v_cvt_pk_bf16_f32 v131, v126, v127
	global_store_dwordx4 v13, v[128:131], s[14:15]
	s_nop 1
	ds_read2_b32 v[120:121], v23 offset0:24 offset1:57
	ds_read2_b32 v[122:123], v23 offset0:90 offset1:123
	ds_read2_b32 v[124:125], v23 offset0:156 offset1:189
	ds_read2_b32 v[126:127], v23 offset0:222 offset1:255
	s_waitcnt lgkmcnt(0)
	v_cvt_pk_bf16_f32 v128, v120, v121
	v_cvt_pk_bf16_f32 v129, v122, v123
	v_cvt_pk_bf16_f32 v130, v124, v125
	v_cvt_pk_bf16_f32 v131, v126, v127
	global_store_dwordx4 v14, v[128:131], s[14:15]
	s_nop 1
	s_add_i32 s28, s18, 0x1400
	s_lshr_b32 s20, s28, 6
	s_and_b32 s21, s28, 63
	s_mul_i32 s14, s21, 0x58000
	s_lshl_b32 s15, s20, 7
	s_add_u32 s14, s14, s15
	s_add_u32 s14, s14, s8
	s_addc_u32 s15, s9, 0
	s_waitcnt vmcnt(8)
	ds_write2_b32 v15, v56, v57 offset1:1
	ds_write2_b32 v15, v58, v59 offset0:2 offset1:3
	ds_write2_b32 v16, v60, v61 offset1:1
	ds_write2_b32 v16, v62, v63 offset0:2 offset1:3
	ds_write2_b32 v17, v64, v65 offset1:1
	ds_write2_b32 v17, v66, v67 offset0:2 offset1:3
	ds_write2_b32 v18, v68, v69 offset1:1
	ds_write2_b32 v18, v70, v71 offset0:2 offset1:3
	ds_write2_b32 v19, v72, v73 offset1:1
	ds_write2_b32 v19, v74, v75 offset0:2 offset1:3
	ds_write2_b32 v20, v76, v77 offset1:1
	ds_write2_b32 v20, v78, v79 offset0:2 offset1:3
	ds_write2_b32 v21, v80, v81 offset1:1
	ds_write2_b32 v21, v82, v83 offset0:2 offset1:3
	ds_write2_b32 v22, v84, v85 offset1:1
	ds_write2_b32 v22, v86, v87 offset0:2 offset1:3
	s_waitcnt lgkmcnt(0)
	ds_read2_b32 v[120:121], v23 offset0:0 offset1:33
	ds_read2_b32 v[122:123], v23 offset0:66 offset1:99
	ds_read2_b32 v[124:125], v23 offset0:132 offset1:165
	ds_read2_b32 v[126:127], v23 offset0:198 offset1:231
	s_waitcnt lgkmcnt(0)
	v_cvt_pk_bf16_f32 v128, v120, v121
	v_cvt_pk_bf16_f32 v129, v122, v123
	v_cvt_pk_bf16_f32 v130, v124, v125
	v_cvt_pk_bf16_f32 v131, v126, v127
	global_store_dwordx4 v11, v[128:131], s[14:15]
	s_nop 1
	ds_read2_b32 v[120:121], v23 offset0:8 offset1:41
	ds_read2_b32 v[122:123], v23 offset0:74 offset1:107
	ds_read2_b32 v[124:125], v23 offset0:140 offset1:173
	ds_read2_b32 v[126:127], v23 offset0:206 offset1:239
	s_waitcnt lgkmcnt(0)
	v_cvt_pk_bf16_f32 v128, v120, v121
	v_cvt_pk_bf16_f32 v129, v122, v123
	v_cvt_pk_bf16_f32 v130, v124, v125
	v_cvt_pk_bf16_f32 v131, v126, v127
	global_store_dwordx4 v12, v[128:131], s[14:15]
	s_nop 1
	ds_read2_b32 v[120:121], v23 offset0:16 offset1:49
	ds_read2_b32 v[122:123], v23 offset0:82 offset1:115
	ds_read2_b32 v[124:125], v23 offset0:148 offset1:181
	ds_read2_b32 v[126:127], v23 offset0:214 offset1:247
	s_waitcnt lgkmcnt(0)
	v_cvt_pk_bf16_f32 v128, v120, v121
	v_cvt_pk_bf16_f32 v129, v122, v123
	v_cvt_pk_bf16_f32 v130, v124, v125
	v_cvt_pk_bf16_f32 v131, v126, v127
	global_store_dwordx4 v13, v[128:131], s[14:15]
	s_nop 1
	ds_read2_b32 v[120:121], v23 offset0:24 offset1:57
	ds_read2_b32 v[122:123], v23 offset0:90 offset1:123
	ds_read2_b32 v[124:125], v23 offset0:156 offset1:189
	ds_read2_b32 v[126:127], v23 offset0:222 offset1:255
	s_waitcnt lgkmcnt(0)
	v_cvt_pk_bf16_f32 v128, v120, v121
	v_cvt_pk_bf16_f32 v129, v122, v123
	v_cvt_pk_bf16_f32 v130, v124, v125
	v_cvt_pk_bf16_f32 v131, v126, v127
	global_store_dwordx4 v14, v[128:131], s[14:15]
	s_nop 1
	s_cmpk_lt_i32 s18, 0xc0
	s_cbranch_scc0 .Ltr1dP1_done
; #define GAS __attribute__((address_space(1)))
; #define LAS __attribute__((address_space(3)))
; #define LDS_WAIT() asm volatile("s_waitcnt lgkmcnt(0)" ::: "memory")
; __device__ __forceinline__ unsigned pk2(float lo, float hi) { return f2bf(lo) | (f2bf(hi) << 16); }
; __device__ __forceinline__ void xcd_barrier(const XcdBarrier& b) {
;     asm volatile("s_waitcnt vmcnt(0)" ::: "memory");
;     __syncthreads();
;     if (threadIdx.x == 0) {
;         unsigned* bar = b.bar;
;         __builtin_amdgcn_s_waitcnt(0);
;         unsigned nloc = b.st[0], nx = b.st[1];
;         if (nloc == 0u) { xcd_barrier_complete(bar, b.x, nloc, nx); b.st[0] = nloc; b.st[1] = nx; }
;     ...
;     for (int j = 0; j < 4; ++j) { const int n = (lane >> 3) + 8 * j; const LAS float* s = scr + (8 * c) * 33 + n;
;         v4u o; o.x = pk2(s[0 * 33], s[1 * 33]); o.y = pk2(s[2 * 33], s[3 * 33]); o.z = pk2(s[4 * 33], s[5 * 33]); o.w = pk2(s[6 * 33], s[7 * 33]);
;         *(GAS v4u*)(WT + (size_t)(r0 + n) * ldt + k0 + 8 * c) = o; }
;     LDS_WAIT(); asm volatile("" ::: "memory");
; }
	s_add_i32 s28, s18, 0x1540
	s_lshr_b32 s20, s28, 6
	s_and_b32 s21, s28, 63
	s_mul_i32 s14, s21, 0x58000
	s_lshl_b32 s15, s20, 7
	s_add_u32 s14, s14, s15
	s_add_u32 s14, s14, s8
	s_addc_u32 s15, s9, 0
	s_waitcnt vmcnt(8)
	ds_write2_b32 v15, v88, v89 offset1:1
	ds_write2_b32 v15, v90, v91 offset0:2 offset1:3
	ds_write2_b32 v16, v92, v93 offset1:1
	ds_write2_b32 v16, v94, v95 offset0:2 offset1:3
	ds_write2_b32 v17, v96, v97 offset1:1
	ds_write2_b32 v17, v98, v99 offset0:2 offset1:3
	ds_write2_b32 v18, v100, v101 offset1:1
	ds_write2_b32 v18, v102, v103 offset0:2 offset1:3
	ds_write2_b32 v19, v104, v105 offset1:1
	ds_write2_b32 v19, v106, v107 offset0:2 offset1:3
	ds_write2_b32 v20, v108, v109 offset1:1
	ds_write2_b32 v20, v110, v111 offset0:2 offset1:3
	ds_write2_b32 v21, v112, v113 offset1:1
	ds_write2_b32 v21, v114, v115 offset0:2 offset1:3
	ds_write2_b32 v22, v116, v117 offset1:1
	ds_write2_b32 v22, v118, v119 offset0:2 offset1:3
	s_waitcnt lgkmcnt(0)
	ds_read2_b32 v[120:121], v23 offset0:0 offset1:33
	ds_read2_b32 v[122:123], v23 offset0:66 offset1:99
	ds_read2_b32 v[124:125], v23 offset0:132 offset1:165
	ds_read2_b32 v[126:127], v23 offset0:198 offset1:231
	s_waitcnt lgkmcnt(0)
	v_cvt_pk_bf16_f32 v128, v120, v121
	v_cvt_pk_bf16_f32 v129, v122, v123
	v_cvt_pk_bf16_f32 v130, v124, v125
	v_cvt_pk_bf16_f32 v131, v126, v127
	global_store_dwordx4 v11, v[128:131], s[14:15]
	s_nop 1
	ds_read2_b32 v[120:121], v23 offset0:8 offset1:41
	ds_read2_b32 v[122:123], v23 offset0:74 offset1:107
	ds_read2_b32 v[124:125], v23 offset0:140 offset1:173
	ds_read2_b32 v[126:127], v23 offset0:206 offset1:239
	s_waitcnt lgkmcnt(0)
	v_cvt_pk_bf16_f32 v128, v120, v121
	v_cvt_pk_bf16_f32 v129, v122, v123
	v_cvt_pk_bf16_f32 v130, v124, v125
	v_cvt_pk_bf16_f32 v131, v126, v127
	global_store_dwordx4 v12, v[128:131], s[14:15]
	s_nop 1
	ds_read2_b32 v[120:121], v23 offset0:16 offset1:49
	ds_read2_b32 v[122:123], v23 offset0:82 offset1:115
	ds_read2_b32 v[124:125], v23 offset0:148 offset1:181
	ds_read2_b32 v[126:127], v23 offset0:214 offset1:247
	s_waitcnt lgkmcnt(0)
	v_cvt_pk_bf16_f32 v128, v120, v121
	v_cvt_pk_bf16_f32 v129, v122, v123
	v_cvt_pk_bf16_f32 v130, v124, v125
	v_cvt_pk_bf16_f32 v131, v126, v127
	global_store_dwordx4 v13, v[128:131], s[14:15]
	s_nop 1
	ds_read2_b32 v[120:121], v23 offset0:24 offset1:57
	ds_read2_b32 v[122:123], v23 offset0:90 offset1:123
	ds_read2_b32 v[124:125], v23 offset0:156 offset1:189
	ds_read2_b32 v[126:127], v23 offset0:222 offset1:255
	s_waitcnt lgkmcnt(0)
	v_cvt_pk_bf16_f32 v128, v120, v121
	v_cvt_pk_bf16_f32 v129, v122, v123
	v_cvt_pk_bf16_f32 v130, v124, v125
	v_cvt_pk_bf16_f32 v131, v126, v127
	global_store_dwordx4 v14, v[128:131], s[14:15]
	s_nop 1
.Ltr1dP1_done:
.LBB0_106:
	s_cmp_gt_i32 s93, 2
	s_cselect_b64 s[6:7], -1, 0
	s_and_b64 s[4:5], s[4:5], s[6:7]
	s_andn2_b64 vcc, exec, s[4:5]
	v_writelane_b32 v245, s82, 42
	s_nop 1
	v_writelane_b32 v245, s83, 43
	s_cbranch_vccnz .LBB0_155
	s_cmp_gt_i32 s92, -1
	s_mov_b64 s[4:5], -1
	s_cbranch_scc0 .LBB0_142
	s_waitcnt vmcnt(0)
	s_waitcnt vmcnt(0)
	s_barrier
	s_mov_b64 s[4:5], exec
	v_readlane_b32 s8, v245, 31
	v_readlane_b32 s9, v245, 32
	s_and_b64 s[8:9], s[4:5], s[8:9]
	s_mov_b64 exec, s[8:9]
	s_cbranch_execz .LBB0_141
	s_add_i32 s3, 0, 0x26020
	v_mov_b32_e32 v2, s3
	s_waitcnt vmcnt(0) expcnt(0) lgkmcnt(0)
	ds_read_b32 v2, v2
	s_add_i32 s3, 0, 0x26024
	v_mov_b32_e32 v3, s3
	ds_read_b32 v5, v3
	s_waitcnt lgkmcnt(1)
	v_cmp_ne_u32_e32 vcc, 0, v2
	s_cbranch_vccnz .LBB0_134
	v_readlane_b32 s8, v245, 8
	v_readlane_b32 s9, v245, 9
	s_load_dwordx2 s[12:13], s[8:9], 0x4
	s_add_u32 s8, s34, 0x4200
	s_addc_u32 s9, s35, 0
	s_add_u32 s10, s34, 0x4400
	s_addc_u32 s11, s35, 0
	s_waitcnt lgkmcnt(0)
	s_mul_i32 s3, s12, s96
	s_add_u32 s12, s34, 0x4500
	s_mul_i32 s3, s3, s13
	s_addc_u32 s13, s35, 0
	s_add_u32 s14, s34, 0x4600
	s_addc_u32 s15, s35, 0
	s_add_u32 s20, s34, 0x4700
	s_addc_u32 s21, s35, 0
	s_add_u32 s22, s34, 0x4800
	s_addc_u32 s23, s35, 0
	s_add_u32 s36, s34, 0x4900
	s_addc_u32 s37, s35, 0
	s_add_u32 s38, s34, 0x4a00
	s_addc_u32 s39, s35, 0
	s_add_u32 s40, s34, 0x4b00
	s_addc_u32 s41, s35, 0
	s_add_u32 s42, s34, 0x4c00
	s_addc_u32 s43, s35, 0
	s_add_u32 s44, s34, 0x4d00
	s_addc_u32 s45, s35, 0
	s_add_u32 s46, s34, 0x4e00
	s_addc_u32 s47, s35, 0
	s_add_u32 s48, s34, 0x4f00
	s_addc_u32 s49, s35, 0
	s_add_u32 s50, s34, 0x5000
	s_addc_u32 s51, s35, 0
	s_add_u32 s52, s34, 0x5100
	s_addc_u32 s53, s35, 0
	s_add_u32 s54, s34, 0x5200
	s_addc_u32 s55, s35, 0
	s_add_u32 s56, s34, 0x5300
	s_addc_u32 s57, s35, 0
	s_mov_b32 s16, 1
	v_mov_b32_e32 v18, 0
	s_branch .LBB0_113

; #define GAS __attribute__((address_space(1)))
; #define LAS __attribute__((address_space(3)))
; #define LDS_WAIT() asm volatile("s_waitcnt lgkmcnt(0)" ::: "memory")
; __device__ __forceinline__ unsigned pk2(float lo, float hi) { return f2bf(lo) | (f2bf(hi) << 16); }
;     if (ldt == 0) ldt = K;
;     asm volatile("" : "+v"(lane));
;     const int kb = item / nblk, nb = item % nblk, k0 = 64 * kb, n0 = 32 * nb;
;     { float wv[32];
;       const float* wp = W + (size_t)(k0 + (lane >> 5)) * ldw + n0 + (lane & 31);
; #pragma unroll
;       for (int i = 0; i < 32; ++i) wv[i] = wp[(size_t)(2 * i) * ldw];
; #pragma unroll
;       for (int i = 0; i < 32; ++i) scr[(2 * i + (lane >> 5)) * 33 + (lane & 31)] = wv[i]; }
;     LDS_WAIT(); asm volatile("" ::: "memory");
;     const int c = lane & 7;
;     const int r0 = (mode == 0) ? n0 : (256 * (n0 >> 7) + (n0 & 127) + (mode == 2 ? 128 : 0));
; #pragma unroll
;     for (int j = 0; j < 4; ++j) { const int n = (lane >> 3) + 8 * j; const LAS float* s = scr + (8 * c) * 33 + n;
;         v4u o; o.x = pk2(s[0 * 33], s[1 * 33]); o.y = pk2(s[2 * 33], s[3 * 33]); o.z = pk2(s[4 * 33], s[5 * 33]); o.w = pk2(s[6 * 33], s[7 * 33]);
;         *(GAS v4u*)(WT + (size_t)(r0 + n) * ldt + k0 + 8 * c) = o; }
;     LDS_WAIT(); asm volatile("" ::: "memory");
; }
; __device__ __forceinline__ void transpose_late(const Args& a, Frame& F, LAS float* scr, int r) {
;     ...
;     if (r < IT_FG) { p0_transpose_item(a.in[I_W2G], FF, D, W2, 1, FF / 32, scr, r, F.lane); return; } r -= IT_FG;
;     if (r < IT_FG) { p0_transpose_item(a.in[I_W2U], FF, D, W2, 2, FF / 32, scr, r, F.lane); return; } r -= IT_FG;
;     p0_transpose_item(a.in[I_W2D], D, FF, W2D, 0, D / 32, scr, r, F.lane);
; }
; template <bool LATE = false>
; __device__ __forceinline__ void transpose_tail(Frame& F, const Args& a, int bx, int lo, int first, int count) {
;     if (F.G != 256 || bx < lo) return;
;     LAS float* scr = (LAS float*)(F.lds + F.wave * 16384);
;     for (int j = (bx - lo) * NWAVES + F.wave; j < count; j += (F.G - lo) * NWAVES) { if (LATE) transpose_late(a, F, scr, first + j); else transpose_early(a, F, scr, first + j); }
.LBB0_1558:
	s_lshl_b32 s0, s2, 3
	s_add_i32 s0, s97, s0
	s_cmpk_lt_i32 s2, 0xd8
	s_cselect_b64 s[8:9], -1, 0
	s_or_b64 s[4:5], s[8:9], s[4:5]
	s_add_i32 s1, s0, 0xfffff940
	s_cmpk_gt_i32 s1, 0x15ff
	s_cselect_b64 s[8:9], -1, 0
	s_or_b64 s[4:5], s[4:5], s[8:9]
	v_mov_b32_e32 v2, v1
	s_and_b64 vcc, exec, s[4:5]
	s_cbranch_vccnz .LBB0_1590
	v_readlane_b32 s36, v244, 16
	v_readlane_b32 s37, v244, 17
	s_add_u32 s38, s34, 0xc900000
	s_addc_u32 s39, s35, 0
	s_lshl_b32 s44, s2, 3
	s_add_i32 s44, s44, s97
	s_addk_i32 s44, 0xf940
	s_lshl_b32 s45, s97, 14
	v_mbcnt_lo_u32_b32 v2, -1, 0
	v_mbcnt_hi_u32_b32 v2, -1, v2
	v_lshrrev_b32_e32 v120, 3, v2
	v_and_b32_e32 v121, 7, v2
	v_lshlrev_b32_e32 v3, 13, v120
	v_lshl_add_u32 v3, v121, 4, v3
	v_add_u32_e32 v4, 0x10000, v3
	v_add_u32_e32 v5, 0x20000, v3
	v_add_u32_e32 v6, 0x30000, v3
	v_add_u32_e32 v7, 0x40000, v3
	v_add_u32_e32 v8, 0x50000, v3
	v_add_u32_e32 v9, 0x60000, v3
	v_add_u32_e32 v10, 0x70000, v3
	v_mul_u32_u24_e32 v11, 0x2c00, v120
	v_lshl_add_u32 v11, v121, 4, v11
	v_add_u32_e32 v12, 0x16000, v11
	v_add_u32_e32 v13, 0x2c000, v11
	v_add_u32_e32 v14, 0x42000, v11
	v_mul_u32_u24_e32 v15, 132, v120
	v_lshl_add_u32 v15, v121, 4, v15
	v_add_u32_e32 v15, s45, v15
	v_add_u32_e32 v16, 1056, v15
	v_add_u32_e32 v17, 2112, v15
	v_add_u32_e32 v18, 3168, v15
	v_add_u32_e32 v19, 4224, v15
	v_add_u32_e32 v20, 5280, v15
	v_add_u32_e32 v21, 6336, v15
	v_add_u32_e32 v22, 7392, v15
	v_mul_u32_u24_e32 v23, 1056, v121
	v_lshl_add_u32 v23, v120, 2, v23
	v_add_u32_e32 v23, s45, v23
	s_add_i32 s48, s44, 0x0
	s_lshr_b32 s46, s48, 6
	s_and_b32 s47, s48, 63
	s_lshl_b32 s40, s46, 19
	s_lshl_b32 s41, s47, 7
	s_add_u32 s40, s40, s41
	s_add_u32 s40, s40, s36
	s_addc_u32 s41, s37, 0
	global_load_dwordx4 v[24:27], v3, s[40:41]
	global_load_dwordx4 v[28:31], v4, s[40:41]
	global_load_dwordx4 v[32:35], v5, s[40:41]
	global_load_dwordx4 v[36:39], v6, s[40:41]
	global_load_dwordx4 v[40:43], v7, s[40:41]
	global_load_dwordx4 v[44:47], v8, s[40:41]
	global_load_dwordx4 v[48:51], v9, s[40:41]
	global_load_dwordx4 v[52:55], v10, s[40:41]
	s_add_i32 s48, s44, 0x140
	s_lshr_b32 s46, s48, 6
	s_and_b32 s47, s48, 63
	s_lshl_b32 s40, s46, 19
	s_lshl_b32 s41, s47, 7
	s_add_u32 s40, s40, s41
	s_add_u32 s40, s40, s36
	s_addc_u32 s41, s37, 0
	global_load_dwordx4 v[56:59], v3, s[40:41]
	global_load_dwordx4 v[60:63], v4, s[40:41]
	global_load_dwordx4 v[64:67], v5, s[40:41]
	global_load_dwordx4 v[68:71], v6, s[40:41]
	global_load_dwordx4 v[72:75], v7, s[40:41]
	global_load_dwordx4 v[76:79], v8, s[40:41]
	global_load_dwordx4 v[80:83], v9, s[40:41]
	global_load_dwordx4 v[84:87], v10, s[40:41]
	s_add_i32 s48, s44, 0x280
	s_lshr_b32 s46, s48, 6
	s_and_b32 s47, s48, 63
	s_lshl_b32 s40, s46, 19
	s_lshl_b32 s41, s47, 7
	s_add_u32 s40, s40, s41
	s_add_u32 s40, s40, s36
	s_addc_u32 s41, s37, 0
	global_load_dwordx4 v[88:91], v3, s[40:41]
	global_load_dwordx4 v[92:95], v4, s[40:41]
	global_load_dwordx4 v[96:99], v5, s[40:41]
	global_load_dwordx4 v[100:103], v6, s[40:41]
	global_load_dwordx4 v[104:107], v7, s[40:41]
	global_load_dwordx4 v[108:111], v8, s[40:41]
	global_load_dwordx4 v[112:115], v9, s[40:41]
	global_load_dwordx4 v[116:119], v10, s[40:41]
	s_add_i32 s48, s44, 0x0
	s_lshr_b32 s46, s48, 6
	s_and_b32 s47, s48, 63
	s_mul_i32 s42, s47, 0x58000
	s_lshl_b32 s43, s46, 7
	s_add_u32 s42, s42, s43
	s_add_u32 s42, s42, s38
	s_addc_u32 s43, s39, 0
	s_waitcnt vmcnt(16)
	ds_write2_b32 v15, v24, v25 offset1:1
	ds_write2_b32 v15, v26, v27 offset0:2 offset1:3
	ds_write2_b32 v16, v28, v29 offset1:1
	ds_write2_b32 v16, v30, v31 offset0:2 offset1:3
	ds_write2_b32 v17, v32, v33 offset1:1
	ds_write2_b32 v17, v34, v35 offset0:2 offset1:3
	ds_write2_b32 v18, v36, v37 offset1:1
	ds_write2_b32 v18, v38, v39 offset0:2 offset1:3
	ds_write2_b32 v19, v40, v41 offset1:1
	ds_write2_b32 v19, v42, v43 offset0:2 offset1:3
	ds_write2_b32 v20, v44, v45 offset1:1
	ds_write2_b32 v20, v46, v47 offset0:2 offset1:3
	ds_write2_b32 v21, v48, v49 offset1:1
	ds_write2_b32 v21, v50, v51 offset0:2 offset1:3
	ds_write2_b32 v22, v52, v53 offset1:1
	ds_write2_b32 v22, v54, v55 offset0:2 offset1:3
	s_waitcnt lgkmcnt(0)
	ds_read2_b32 v[120:121], v23 offset0:0 offset1:33
	ds_read2_b32 v[122:123], v23 offset0:66 offset1:99
	ds_read2_b32 v[124:125], v23 offset0:132 offset1:165
	ds_read2_b32 v[126:127], v23 offset0:198 offset1:231
	s_waitcnt lgkmcnt(0)
	v_cvt_pk_bf16_f32 v128, v120, v121
	v_cvt_pk_bf16_f32 v129, v122, v123
	v_cvt_pk_bf16_f32 v130, v124, v125
	v_cvt_pk_bf16_f32 v131, v126, v127
	global_store_dwordx4 v11, v[128:131], s[42:43]
	s_nop 1
	ds_read2_b32 v[120:121], v23 offset0:8 offset1:41
	ds_read2_b32 v[122:123], v23 offset0:74 offset1:107
	ds_read2_b32 v[124:125], v23 offset0:140 offset1:173
	ds_read2_b32 v[126:127], v23 offset0:206 offset1:239
	s_waitcnt lgkmcnt(0)
	v_cvt_pk_bf16_f32 v128, v120, v121
	v_cvt_pk_bf16_f32 v129, v122, v123
	v_cvt_pk_bf16_f32 v130, v124, v125
	v_cvt_pk_bf16_f32 v131, v126, v127
	global_store_dwordx4 v12, v[128:131], s[42:43]
	s_nop 1
	ds_read2_b32 v[120:121], v23 offset0:16 offset1:49
	ds_read2_b32 v[122:123], v23 offset0:82 offset1:115
	ds_read2_b32 v[124:125], v23 offset0:148 offset1:181
	ds_read2_b32 v[126:127], v23 offset0:214 offset1:247
	s_waitcnt lgkmcnt(0)
	v_cvt_pk_bf16_f32 v128, v120, v121
	v_cvt_pk_bf16_f32 v129, v122, v123
	v_cvt_pk_bf16_f32 v130, v124, v125
	v_cvt_pk_bf16_f32 v131, v126, v127
	global_store_dwordx4 v13, v[128:131], s[42:43]
	s_nop 1
	ds_read2_b32 v[120:121], v23 offset0:24 offset1:57
	ds_read2_b32 v[122:123], v23 offset0:90 offset1:123
	ds_read2_b32 v[124:125], v23 offset0:156 offset1:189
	ds_read2_b32 v[126:127], v23 offset0:222 offset1:255
	s_waitcnt lgkmcnt(0)
; #define GAS __attribute__((address_space(1)))
; #define LAS __attribute__((address_space(3)))
; #define LDS_WAIT() asm volatile("s_waitcnt lgkmcnt(0)" ::: "memory")
; __device__ __forceinline__ unsigned pk2(float lo, float hi) { return f2bf(lo) | (f2bf(hi) << 16); }
;     if (ldt == 0) ldt = K;
;     asm volatile("" : "+v"(lane));
;     const int kb = item / nblk, nb = item % nblk, k0 = 64 * kb, n0 = 32 * nb;
;     { float wv[32];
;       const float* wp = W + (size_t)(k0 + (lane >> 5)) * ldw + n0 + (lane & 31);
; #pragma unroll
;       for (int i = 0; i < 32; ++i) wv[i] = wp[(size_t)(2 * i) * ldw];
; #pragma unroll
;       for (int i = 0; i < 32; ++i) scr[(2 * i + (lane >> 5)) * 33 + (lane & 31)] = wv[i]; }
;     LDS_WAIT(); asm volatile("" ::: "memory");
;     const int c = lane & 7;
;     const int r0 = (mode == 0) ? n0 : (256 * (n0 >> 7) + (n0 & 127) + (mode == 2 ? 128 : 0));
; #pragma unroll
;     for (int j = 0; j < 4; ++j) { const int n = (lane >> 3) + 8 * j; const LAS float* s = scr + (8 * c) * 33 + n;
;         v4u o; o.x = pk2(s[0 * 33], s[1 * 33]); o.y = pk2(s[2 * 33], s[3 * 33]); o.z = pk2(s[4 * 33], s[5 * 33]); o.w = pk2(s[6 * 33], s[7 * 33]);
;         *(GAS v4u*)(WT + (size_t)(r0 + n) * ldt + k0 + 8 * c) = o; }
;     LDS_WAIT(); asm volatile("" ::: "memory");
; }
	v_cvt_pk_bf16_f32 v128, v120, v121
	v_cvt_pk_bf16_f32 v129, v122, v123
	v_cvt_pk_bf16_f32 v130, v124, v125
	v_cvt_pk_bf16_f32 v131, v126, v127
	global_store_dwordx4 v14, v[128:131], s[42:43]
	s_nop 1
	s_add_i32 s48, s44, 0x3c0
	s_lshr_b32 s46, s48, 6
	s_and_b32 s47, s48, 63
	s_lshl_b32 s40, s46, 19
	s_lshl_b32 s41, s47, 7
	s_add_u32 s40, s40, s41
	s_add_u32 s40, s40, s36
	s_addc_u32 s41, s37, 0
	global_load_dwordx4 v[24:27], v3, s[40:41]
	global_load_dwordx4 v[28:31], v4, s[40:41]
	global_load_dwordx4 v[32:35], v5, s[40:41]
	global_load_dwordx4 v[36:39], v6, s[40:41]
	global_load_dwordx4 v[40:43], v7, s[40:41]
	global_load_dwordx4 v[44:47], v8, s[40:41]
	global_load_dwordx4 v[48:51], v9, s[40:41]
	global_load_dwordx4 v[52:55], v10, s[40:41]
	s_add_i32 s48, s44, 0x140
	s_lshr_b32 s46, s48, 6
	s_and_b32 s47, s48, 63
	s_mul_i32 s42, s47, 0x58000
	s_lshl_b32 s43, s46, 7
	s_add_u32 s42, s42, s43
	s_add_u32 s42, s42, s38
	s_addc_u32 s43, s39, 0
	s_waitcnt vmcnt(20)
	ds_write2_b32 v15, v56, v57 offset1:1
	ds_write2_b32 v15, v58, v59 offset0:2 offset1:3
	ds_write2_b32 v16, v60, v61 offset1:1
	ds_write2_b32 v16, v62, v63 offset0:2 offset1:3
	ds_write2_b32 v17, v64, v65 offset1:1
	ds_write2_b32 v17, v66, v67 offset0:2 offset1:3
	ds_write2_b32 v18, v68, v69 offset1:1
	ds_write2_b32 v18, v70, v71 offset0:2 offset1:3
	ds_write2_b32 v19, v72, v73 offset1:1
	ds_write2_b32 v19, v74, v75 offset0:2 offset1:3
	ds_write2_b32 v20, v76, v77 offset1:1
	ds_write2_b32 v20, v78, v79 offset0:2 offset1:3
	ds_write2_b32 v21, v80, v81 offset1:1
	ds_write2_b32 v21, v82, v83 offset0:2 offset1:3
	ds_write2_b32 v22, v84, v85 offset1:1
	ds_write2_b32 v22, v86, v87 offset0:2 offset1:3
	s_waitcnt lgkmcnt(0)
	ds_read2_b32 v[120:121], v23 offset0:0 offset1:33
	ds_read2_b32 v[122:123], v23 offset0:66 offset1:99
	ds_read2_b32 v[124:125], v23 offset0:132 offset1:165
	ds_read2_b32 v[126:127], v23 offset0:198 offset1:231
	s_waitcnt lgkmcnt(0)
	v_cvt_pk_bf16_f32 v128, v120, v121
	v_cvt_pk_bf16_f32 v129, v122, v123
	v_cvt_pk_bf16_f32 v130, v124, v125
	v_cvt_pk_bf16_f32 v131, v126, v127
	global_store_dwordx4 v11, v[128:131], s[42:43]
	s_nop 1
	ds_read2_b32 v[120:121], v23 offset0:8 offset1:41
	ds_read2_b32 v[122:123], v23 offset0:74 offset1:107
	ds_read2_b32 v[124:125], v23 offset0:140 offset1:173
	ds_read2_b32 v[126:127], v23 offset0:206 offset1:239
	s_waitcnt lgkmcnt(0)
	v_cvt_pk_bf16_f32 v128, v120, v121
	v_cvt_pk_bf16_f32 v129, v122, v123
	v_cvt_pk_bf16_f32 v130, v124, v125
	v_cvt_pk_bf16_f32 v131, v126, v127
	global_store_dwordx4 v12, v[128:131], s[42:43]
	s_nop 1
	ds_read2_b32 v[120:121], v23 offset0:16 offset1:49
	ds_read2_b32 v[122:123], v23 offset0:82 offset1:115
	ds_read2_b32 v[124:125], v23 offset0:148 offset1:181
	ds_read2_b32 v[126:127], v23 offset0:214 offset1:247
	s_waitcnt lgkmcnt(0)
	v_cvt_pk_bf16_f32 v128, v120, v121
	v_cvt_pk_bf16_f32 v129, v122, v123
	v_cvt_pk_bf16_f32 v130, v124, v125
	v_cvt_pk_bf16_f32 v131, v126, v127
	global_store_dwordx4 v13, v[128:131], s[42:43]
	s_nop 1
	ds_read2_b32 v[120:121], v23 offset0:24 offset1:57
	ds_read2_b32 v[122:123], v23 offset0:90 offset1:123
	ds_read2_b32 v[124:125], v23 offset0:156 offset1:189
	ds_read2_b32 v[126:127], v23 offset0:222 offset1:255
	s_waitcnt lgkmcnt(0)
	v_cvt_pk_bf16_f32 v128, v120, v121
	v_cvt_pk_bf16_f32 v129, v122, v123
	v_cvt_pk_bf16_f32 v130, v124, v125
	v_cvt_pk_bf16_f32 v131, v126, v127
	global_store_dwordx4 v14, v[128:131], s[42:43]
	s_nop 1
	s_add_i32 s48, s44, 0x500
	s_lshr_b32 s46, s48, 6
	s_and_b32 s47, s48, 63
	s_lshl_b32 s40, s46, 19
	s_lshl_b32 s41, s47, 7
	s_add_u32 s40, s40, s41
	s_add_u32 s40, s40, s36
	s_addc_u32 s41, s37, 0
	global_load_dwordx4 v[56:59], v3, s[40:41]
	global_load_dwordx4 v[60:63], v4, s[40:41]
	global_load_dwordx4 v[64:67], v5, s[40:41]
	global_load_dwordx4 v[68:71], v6, s[40:41]
	global_load_dwordx4 v[72:75], v7, s[40:41]
	global_load_dwordx4 v[76:79], v8, s[40:41]
	global_load_dwordx4 v[80:83], v9, s[40:41]
	global_load_dwordx4 v[84:87], v10, s[40:41]
	s_add_i32 s48, s44, 0x280
	s_lshr_b32 s46, s48, 6
	s_and_b32 s47, s48, 63
	s_mul_i32 s42, s47, 0x58000
	s_lshl_b32 s43, s46, 7
	s_add_u32 s42, s42, s43
	s_add_u32 s42, s42, s38
	s_addc_u32 s43, s39, 0
	s_waitcnt vmcnt(24)
	ds_write2_b32 v15, v88, v89 offset1:1
	ds_write2_b32 v15, v90, v91 offset0:2 offset1:3
	ds_write2_b32 v16, v92, v93 offset1:1
	ds_write2_b32 v16, v94, v95 offset0:2 offset1:3
	ds_write2_b32 v17, v96, v97 offset1:1
	ds_write2_b32 v17, v98, v99 offset0:2 offset1:3
	ds_write2_b32 v18, v100, v101 offset1:1
	ds_write2_b32 v18, v102, v103 offset0:2 offset1:3
	ds_write2_b32 v19, v104, v105 offset1:1
	ds_write2_b32 v19, v106, v107 offset0:2 offset1:3
	ds_write2_b32 v20, v108, v109 offset1:1
	ds_write2_b32 v20, v110, v111 offset0:2 offset1:3
	ds_write2_b32 v21, v112, v113 offset1:1
	ds_write2_b32 v21, v114, v115 offset0:2 offset1:3
	ds_write2_b32 v22, v116, v117 offset1:1
	ds_write2_b32 v22, v118, v119 offset0:2 offset1:3
	s_waitcnt lgkmcnt(0)
	ds_read2_b32 v[120:121], v23 offset0:0 offset1:33
	ds_read2_b32 v[122:123], v23 offset0:66 offset1:99
	ds_read2_b32 v[124:125], v23 offset0:132 offset1:165
	ds_read2_b32 v[126:127], v23 offset0:198 offset1:231
	s_waitcnt lgkmcnt(0)
	v_cvt_pk_bf16_f32 v128, v120, v121
	v_cvt_pk_bf16_f32 v129, v122, v123
	v_cvt_pk_bf16_f32 v130, v124, v125
	v_cvt_pk_bf16_f32 v131, v126, v127
	global_store_dwordx4 v11, v[128:131], s[42:43]
	s_nop 1
	ds_read2_b32 v[120:121], v23 offset0:8 offset1:41
	ds_read2_b32 v[122:123], v23 offset0:74 offset1:107
	ds_read2_b32 v[124:125], v23 offset0:140 offset1:173
	ds_read2_b32 v[126:127], v23 offset0:206 offset1:239
	s_waitcnt lgkmcnt(0)
; #define GAS __attribute__((address_space(1)))
; #define LAS __attribute__((address_space(3)))
; #define LDS_WAIT() asm volatile("s_waitcnt lgkmcnt(0)" ::: "memory")
; __device__ __forceinline__ unsigned pk2(float lo, float hi) { return f2bf(lo) | (f2bf(hi) << 16); }
;     if (ldt == 0) ldt = K;
;     asm volatile("" : "+v"(lane));
;     const int kb = item / nblk, nb = item % nblk, k0 = 64 * kb, n0 = 32 * nb;
;     { float wv[32];
;       const float* wp = W + (size_t)(k0 + (lane >> 5)) * ldw + n0 + (lane & 31);
; #pragma unroll
;       for (int i = 0; i < 32; ++i) wv[i] = wp[(size_t)(2 * i) * ldw];
; #pragma unroll
;       for (int i = 0; i < 32; ++i) scr[(2 * i + (lane >> 5)) * 33 + (lane & 31)] = wv[i]; }
;     LDS_WAIT(); asm volatile("" ::: "memory");
;     const int c = lane & 7;
;     const int r0 = (mode == 0) ? n0 : (256 * (n0 >> 7) + (n0 & 127) + (mode == 2 ? 128 : 0));
; #pragma unroll
;     for (int j = 0; j < 4; ++j) { const int n = (lane >> 3) + 8 * j; const LAS float* s = scr + (8 * c) * 33 + n;
;         v4u o; o.x = pk2(s[0 * 33], s[1 * 33]); o.y = pk2(s[2 * 33], s[3 * 33]); o.z = pk2(s[4 * 33], s[5 * 33]); o.w = pk2(s[6 * 33], s[7 * 33]);
;         *(GAS v4u*)(WT + (size_t)(r0 + n) * ldt + k0 + 8 * c) = o; }
;     LDS_WAIT(); asm volatile("" ::: "memory");
; }
	v_cvt_pk_bf16_f32 v128, v120, v121
	v_cvt_pk_bf16_f32 v129, v122, v123
	v_cvt_pk_bf16_f32 v130, v124, v125
	v_cvt_pk_bf16_f32 v131, v126, v127
	global_store_dwordx4 v12, v[128:131], s[42:43]
	s_nop 1
	ds_read2_b32 v[120:121], v23 offset0:16 offset1:49
	ds_read2_b32 v[122:123], v23 offset0:82 offset1:115
	ds_read2_b32 v[124:125], v23 offset0:148 offset1:181
	ds_read2_b32 v[126:127], v23 offset0:214 offset1:247
	s_waitcnt lgkmcnt(0)
	v_cvt_pk_bf16_f32 v128, v120, v121
	v_cvt_pk_bf16_f32 v129, v122, v123
	v_cvt_pk_bf16_f32 v130, v124, v125
	v_cvt_pk_bf16_f32 v131, v126, v127
	global_store_dwordx4 v13, v[128:131], s[42:43]
	s_nop 1
	ds_read2_b32 v[120:121], v23 offset0:24 offset1:57
	ds_read2_b32 v[122:123], v23 offset0:90 offset1:123
	ds_read2_b32 v[124:125], v23 offset0:156 offset1:189
	ds_read2_b32 v[126:127], v23 offset0:222 offset1:255
	s_waitcnt lgkmcnt(0)
	v_cvt_pk_bf16_f32 v128, v120, v121
	v_cvt_pk_bf16_f32 v129, v122, v123
	v_cvt_pk_bf16_f32 v130, v124, v125
	v_cvt_pk_bf16_f32 v131, v126, v127
	global_store_dwordx4 v14, v[128:131], s[42:43]
	s_nop 1
	s_add_i32 s48, s44, 0x640
	s_lshr_b32 s46, s48, 6
	s_and_b32 s47, s48, 63
	s_lshl_b32 s40, s46, 19
	s_lshl_b32 s41, s47, 7
	s_add_u32 s40, s40, s41
	s_add_u32 s40, s40, s36
	s_addc_u32 s41, s37, 0
	global_load_dwordx4 v[88:91], v3, s[40:41]
	global_load_dwordx4 v[92:95], v4, s[40:41]
	global_load_dwordx4 v[96:99], v5, s[40:41]
	global_load_dwordx4 v[100:103], v6, s[40:41]
	global_load_dwordx4 v[104:107], v7, s[40:41]
	global_load_dwordx4 v[108:111], v8, s[40:41]
	global_load_dwordx4 v[112:115], v9, s[40:41]
	global_load_dwordx4 v[116:119], v10, s[40:41]
	s_add_i32 s48, s44, 0x3c0
	s_lshr_b32 s46, s48, 6
	s_and_b32 s47, s48, 63
	s_mul_i32 s42, s47, 0x58000
	s_lshl_b32 s43, s46, 7
	s_add_u32 s42, s42, s43
	s_add_u32 s42, s42, s38
	s_addc_u32 s43, s39, 0
	s_waitcnt vmcnt(24)
	ds_write2_b32 v15, v24, v25 offset1:1
	ds_write2_b32 v15, v26, v27 offset0:2 offset1:3
	ds_write2_b32 v16, v28, v29 offset1:1
	ds_write2_b32 v16, v30, v31 offset0:2 offset1:3
	ds_write2_b32 v17, v32, v33 offset1:1
	ds_write2_b32 v17, v34, v35 offset0:2 offset1:3
	ds_write2_b32 v18, v36, v37 offset1:1
	ds_write2_b32 v18, v38, v39 offset0:2 offset1:3
	ds_write2_b32 v19, v40, v41 offset1:1
	ds_write2_b32 v19, v42, v43 offset0:2 offset1:3
	ds_write2_b32 v20, v44, v45 offset1:1
	ds_write2_b32 v20, v46, v47 offset0:2 offset1:3
	ds_write2_b32 v21, v48, v49 offset1:1
	ds_write2_b32 v21, v50, v51 offset0:2 offset1:3
	ds_write2_b32 v22, v52, v53 offset1:1
	ds_write2_b32 v22, v54, v55 offset0:2 offset1:3
	s_waitcnt lgkmcnt(0)
	ds_read2_b32 v[120:121], v23 offset0:0 offset1:33
	ds_read2_b32 v[122:123], v23 offset0:66 offset1:99
	ds_read2_b32 v[124:125], v23 offset0:132 offset1:165
	ds_read2_b32 v[126:127], v23 offset0:198 offset1:231
	s_waitcnt lgkmcnt(0)
	v_cvt_pk_bf16_f32 v128, v120, v121
	v_cvt_pk_bf16_f32 v129, v122, v123
	v_cvt_pk_bf16_f32 v130, v124, v125
	v_cvt_pk_bf16_f32 v131, v126, v127
	global_store_dwordx4 v11, v[128:131], s[42:43]
	s_nop 1
	ds_read2_b32 v[120:121], v23 offset0:8 offset1:41
	ds_read2_b32 v[122:123], v23 offset0:74 offset1:107
	ds_read2_b32 v[124:125], v23 offset0:140 offset1:173
	ds_read2_b32 v[126:127], v23 offset0:206 offset1:239
	s_waitcnt lgkmcnt(0)
	v_cvt_pk_bf16_f32 v128, v120, v121
	v_cvt_pk_bf16_f32 v129, v122, v123
	v_cvt_pk_bf16_f32 v130, v124, v125
	v_cvt_pk_bf16_f32 v131, v126, v127
	global_store_dwordx4 v12, v[128:131], s[42:43]
	s_nop 1
	ds_read2_b32 v[120:121], v23 offset0:16 offset1:49
	ds_read2_b32 v[122:123], v23 offset0:82 offset1:115
	ds_read2_b32 v[124:125], v23 offset0:148 offset1:181
	ds_read2_b32 v[126:127], v23 offset0:214 offset1:247
	s_waitcnt lgkmcnt(0)
	v_cvt_pk_bf16_f32 v128, v120, v121
	v_cvt_pk_bf16_f32 v129, v122, v123
	v_cvt_pk_bf16_f32 v130, v124, v125
	v_cvt_pk_bf16_f32 v131, v126, v127
	global_store_dwordx4 v13, v[128:131], s[42:43]
	s_nop 1
	ds_read2_b32 v[120:121], v23 offset0:24 offset1:57
	ds_read2_b32 v[122:123], v23 offset0:90 offset1:123
	ds_read2_b32 v[124:125], v23 offset0:156 offset1:189
	ds_read2_b32 v[126:127], v23 offset0:222 offset1:255
	s_waitcnt lgkmcnt(0)
	v_cvt_pk_bf16_f32 v128, v120, v121
	v_cvt_pk_bf16_f32 v129, v122, v123
	v_cvt_pk_bf16_f32 v130, v124, v125
	v_cvt_pk_bf16_f32 v131, v126, v127
	global_store_dwordx4 v14, v[128:131], s[42:43]
	s_nop 1
	s_add_i32 s48, s44, 0x780
	s_lshr_b32 s46, s48, 6
	s_and_b32 s47, s48, 63
	s_lshl_b32 s40, s46, 19
	s_lshl_b32 s41, s47, 7
	s_add_u32 s40, s40, s41
	s_add_u32 s40, s40, s36
	s_addc_u32 s41, s37, 0
	global_load_dwordx4 v[24:27], v3, s[40:41]
	global_load_dwordx4 v[28:31], v4, s[40:41]
	global_load_dwordx4 v[32:35], v5, s[40:41]
	global_load_dwordx4 v[36:39], v6, s[40:41]
	global_load_dwordx4 v[40:43], v7, s[40:41]
	global_load_dwordx4 v[44:47], v8, s[40:41]
	global_load_dwordx4 v[48:51], v9, s[40:41]
	global_load_dwordx4 v[52:55], v10, s[40:41]
	s_add_i32 s48, s44, 0x500
	s_lshr_b32 s46, s48, 6
	s_and_b32 s47, s48, 63
	s_mul_i32 s42, s47, 0x58000
	s_lshl_b32 s43, s46, 7
	s_add_u32 s42, s42, s43
	s_add_u32 s42, s42, s38
	s_addc_u32 s43, s39, 0
	s_waitcnt vmcnt(24)
	ds_write2_b32 v15, v56, v57 offset1:1
	ds_write2_b32 v15, v58, v59 offset0:2 offset1:3
	ds_write2_b32 v16, v60, v61 offset1:1
	ds_write2_b32 v16, v62, v63 offset0:2 offset1:3
	ds_write2_b32 v17, v64, v65 offset1:1
	ds_write2_b32 v17, v66, v67 offset0:2 offset1:3
	ds_write2_b32 v18, v68, v69 offset1:1
	ds_write2_b32 v18, v70, v71 offset0:2 offset1:3
	ds_write2_b32 v19, v72, v73 offset1:1
	ds_write2_b32 v19, v74, v75 offset0:2 offset1:3
	ds_write2_b32 v20, v76, v77 offset1:1
	ds_write2_b32 v20, v78, v79 offset0:2 offset1:3
	ds_write2_b32 v21, v80, v81 offset1:1
	ds_write2_b32 v21, v82, v83 offset0:2 offset1:3
	ds_write2_b32 v22, v84, v85 offset1:1
	ds_write2_b32 v22, v86, v87 offset0:2 offset1:3
	s_waitcnt lgkmcnt(0)
; #define GAS __attribute__((address_space(1)))
; #define LAS __attribute__((address_space(3)))
; #define LDS_WAIT() asm volatile("s_waitcnt lgkmcnt(0)" ::: "memory")
; __device__ __forceinline__ unsigned pk2(float lo, float hi) { return f2bf(lo) | (f2bf(hi) << 16); }
;     if (ldt == 0) ldt = K;
;     asm volatile("" : "+v"(lane));
;     const int kb = item / nblk, nb = item % nblk, k0 = 64 * kb, n0 = 32 * nb;
;     { float wv[32];
;       const float* wp = W + (size_t)(k0 + (lane >> 5)) * ldw + n0 + (lane & 31);
; #pragma unroll
;       for (int i = 0; i < 32; ++i) wv[i] = wp[(size_t)(2 * i) * ldw];
; #pragma unroll
;       for (int i = 0; i < 32; ++i) scr[(2 * i + (lane >> 5)) * 33 + (lane & 31)] = wv[i]; }
;     LDS_WAIT(); asm volatile("" ::: "memory");
;     const int c = lane & 7;
;     const int r0 = (mode == 0) ? n0 : (256 * (n0 >> 7) + (n0 & 127) + (mode == 2 ? 128 : 0));
; #pragma unroll
;     for (int j = 0; j < 4; ++j) { const int n = (lane >> 3) + 8 * j; const LAS float* s = scr + (8 * c) * 33 + n;
;         v4u o; o.x = pk2(s[0 * 33], s[1 * 33]); o.y = pk2(s[2 * 33], s[3 * 33]); o.z = pk2(s[4 * 33], s[5 * 33]); o.w = pk2(s[6 * 33], s[7 * 33]);
;         *(GAS v4u*)(WT + (size_t)(r0 + n) * ldt + k0 + 8 * c) = o; }
;     LDS_WAIT(); asm volatile("" ::: "memory");
; }
	ds_read2_b32 v[120:121], v23 offset0:0 offset1:33
	ds_read2_b32 v[122:123], v23 offset0:66 offset1:99
	ds_read2_b32 v[124:125], v23 offset0:132 offset1:165
	ds_read2_b32 v[126:127], v23 offset0:198 offset1:231
	s_waitcnt lgkmcnt(0)
	v_cvt_pk_bf16_f32 v128, v120, v121
	v_cvt_pk_bf16_f32 v129, v122, v123
	v_cvt_pk_bf16_f32 v130, v124, v125
	v_cvt_pk_bf16_f32 v131, v126, v127
	global_store_dwordx4 v11, v[128:131], s[42:43]
	s_nop 1
	ds_read2_b32 v[120:121], v23 offset0:8 offset1:41
	ds_read2_b32 v[122:123], v23 offset0:74 offset1:107
	ds_read2_b32 v[124:125], v23 offset0:140 offset1:173
	ds_read2_b32 v[126:127], v23 offset0:206 offset1:239
	s_waitcnt lgkmcnt(0)
	v_cvt_pk_bf16_f32 v128, v120, v121
	v_cvt_pk_bf16_f32 v129, v122, v123
	v_cvt_pk_bf16_f32 v130, v124, v125
	v_cvt_pk_bf16_f32 v131, v126, v127
	global_store_dwordx4 v12, v[128:131], s[42:43]
	s_nop 1
	ds_read2_b32 v[120:121], v23 offset0:16 offset1:49
	ds_read2_b32 v[122:123], v23 offset0:82 offset1:115
	ds_read2_b32 v[124:125], v23 offset0:148 offset1:181
	ds_read2_b32 v[126:127], v23 offset0:214 offset1:247
	s_waitcnt lgkmcnt(0)
	v_cvt_pk_bf16_f32 v128, v120, v121
	v_cvt_pk_bf16_f32 v129, v122, v123
	v_cvt_pk_bf16_f32 v130, v124, v125
	v_cvt_pk_bf16_f32 v131, v126, v127
	global_store_dwordx4 v13, v[128:131], s[42:43]
	s_nop 1
	ds_read2_b32 v[120:121], v23 offset0:24 offset1:57
	ds_read2_b32 v[122:123], v23 offset0:90 offset1:123
	ds_read2_b32 v[124:125], v23 offset0:156 offset1:189
	ds_read2_b32 v[126:127], v23 offset0:222 offset1:255
	s_waitcnt lgkmcnt(0)
	v_cvt_pk_bf16_f32 v128, v120, v121
	v_cvt_pk_bf16_f32 v129, v122, v123
	v_cvt_pk_bf16_f32 v130, v124, v125
	v_cvt_pk_bf16_f32 v131, v126, v127
	global_store_dwordx4 v14, v[128:131], s[42:43]
	s_nop 1
	s_add_i32 s48, s44, 0x8c0
	s_lshr_b32 s46, s48, 6
	s_and_b32 s47, s48, 63
	s_lshl_b32 s40, s46, 19
	s_lshl_b32 s41, s47, 7
	s_add_u32 s40, s40, s41
	s_add_u32 s40, s40, s36
	s_addc_u32 s41, s37, 0
	global_load_dwordx4 v[56:59], v3, s[40:41]
	global_load_dwordx4 v[60:63], v4, s[40:41]
	global_load_dwordx4 v[64:67], v5, s[40:41]
	global_load_dwordx4 v[68:71], v6, s[40:41]
	global_load_dwordx4 v[72:75], v7, s[40:41]
	global_load_dwordx4 v[76:79], v8, s[40:41]
	global_load_dwordx4 v[80:83], v9, s[40:41]
	global_load_dwordx4 v[84:87], v10, s[40:41]
	s_add_i32 s48, s44, 0x640
	s_lshr_b32 s46, s48, 6
	s_and_b32 s47, s48, 63
	s_mul_i32 s42, s47, 0x58000
	s_lshl_b32 s43, s46, 7
	s_add_u32 s42, s42, s43
	s_add_u32 s42, s42, s38
	s_addc_u32 s43, s39, 0
	s_waitcnt vmcnt(24)
	ds_write2_b32 v15, v88, v89 offset1:1
	ds_write2_b32 v15, v90, v91 offset0:2 offset1:3
	ds_write2_b32 v16, v92, v93 offset1:1
	ds_write2_b32 v16, v94, v95 offset0:2 offset1:3
	ds_write2_b32 v17, v96, v97 offset1:1
	ds_write2_b32 v17, v98, v99 offset0:2 offset1:3
	ds_write2_b32 v18, v100, v101 offset1:1
	ds_write2_b32 v18, v102, v103 offset0:2 offset1:3
	ds_write2_b32 v19, v104, v105 offset1:1
	ds_write2_b32 v19, v106, v107 offset0:2 offset1:3
	ds_write2_b32 v20, v108, v109 offset1:1
	ds_write2_b32 v20, v110, v111 offset0:2 offset1:3
	ds_write2_b32 v21, v112, v113 offset1:1
	ds_write2_b32 v21, v114, v115 offset0:2 offset1:3
	ds_write2_b32 v22, v116, v117 offset1:1
	ds_write2_b32 v22, v118, v119 offset0:2 offset1:3
	s_waitcnt lgkmcnt(0)
	ds_read2_b32 v[120:121], v23 offset0:0 offset1:33
	ds_read2_b32 v[122:123], v23 offset0:66 offset1:99
	ds_read2_b32 v[124:125], v23 offset0:132 offset1:165
	ds_read2_b32 v[126:127], v23 offset0:198 offset1:231
	s_waitcnt lgkmcnt(0)
	v_cvt_pk_bf16_f32 v128, v120, v121
	v_cvt_pk_bf16_f32 v129, v122, v123
	v_cvt_pk_bf16_f32 v130, v124, v125
	v_cvt_pk_bf16_f32 v131, v126, v127
	global_store_dwordx4 v11, v[128:131], s[42:43]
	s_nop 1
	ds_read2_b32 v[120:121], v23 offset0:8 offset1:41
	ds_read2_b32 v[122:123], v23 offset0:74 offset1:107
	ds_read2_b32 v[124:125], v23 offset0:140 offset1:173
	ds_read2_b32 v[126:127], v23 offset0:206 offset1:239
	s_waitcnt lgkmcnt(0)
	v_cvt_pk_bf16_f32 v128, v120, v121
	v_cvt_pk_bf16_f32 v129, v122, v123
	v_cvt_pk_bf16_f32 v130, v124, v125
	v_cvt_pk_bf16_f32 v131, v126, v127
	global_store_dwordx4 v12, v[128:131], s[42:43]
	s_nop 1
	ds_read2_b32 v[120:121], v23 offset0:16 offset1:49
	ds_read2_b32 v[122:123], v23 offset0:82 offset1:115
	ds_read2_b32 v[124:125], v23 offset0:148 offset1:181
	ds_read2_b32 v[126:127], v23 offset0:214 offset1:247
	s_waitcnt lgkmcnt(0)
	v_cvt_pk_bf16_f32 v128, v120, v121
	v_cvt_pk_bf16_f32 v129, v122, v123
	v_cvt_pk_bf16_f32 v130, v124, v125
	v_cvt_pk_bf16_f32 v131, v126, v127
	global_store_dwordx4 v13, v[128:131], s[42:43]
	s_nop 1
	ds_read2_b32 v[120:121], v23 offset0:24 offset1:57
	ds_read2_b32 v[122:123], v23 offset0:90 offset1:123
	ds_read2_b32 v[124:125], v23 offset0:156 offset1:189
	ds_read2_b32 v[126:127], v23 offset0:222 offset1:255
	s_waitcnt lgkmcnt(0)
	v_cvt_pk_bf16_f32 v128, v120, v121
	v_cvt_pk_bf16_f32 v129, v122, v123
	v_cvt_pk_bf16_f32 v130, v124, v125
	v_cvt_pk_bf16_f32 v131, v126, v127
	global_store_dwordx4 v14, v[128:131], s[42:43]
	s_nop 1
	s_add_i32 s48, s44, 0xa00
	s_lshr_b32 s46, s48, 6
	s_and_b32 s47, s48, 63
	s_lshl_b32 s40, s46, 19
	s_lshl_b32 s41, s47, 7
	s_add_u32 s40, s40, s41
	s_add_u32 s40, s40, s36
	s_addc_u32 s41, s37, 0
	global_load_dwordx4 v[88:91], v3, s[40:41]
	global_load_dwordx4 v[92:95], v4, s[40:41]
	global_load_dwordx4 v[96:99], v5, s[40:41]
	global_load_dwordx4 v[100:103], v6, s[40:41]
	global_load_dwordx4 v[104:107], v7, s[40:41]
	global_load_dwordx4 v[108:111], v8, s[40:41]
	global_load_dwordx4 v[112:115], v9, s[40:41]
	global_load_dwordx4 v[116:119], v10, s[40:41]
	s_add_i32 s48, s44, 0x780
	s_lshr_b32 s46, s48, 6
	s_and_b32 s47, s48, 63
	s_mul_i32 s42, s47, 0x58000
	s_lshl_b32 s43, s46, 7
	s_add_u32 s42, s42, s43
	s_add_u32 s42, s42, s38
	s_addc_u32 s43, s39, 0
	s_waitcnt vmcnt(24)
; #define GAS __attribute__((address_space(1)))
; #define LAS __attribute__((address_space(3)))
; #define LDS_WAIT() asm volatile("s_waitcnt lgkmcnt(0)" ::: "memory")
; __device__ __forceinline__ unsigned pk2(float lo, float hi) { return f2bf(lo) | (f2bf(hi) << 16); }
;     if (ldt == 0) ldt = K;
;     asm volatile("" : "+v"(lane));
;     const int kb = item / nblk, nb = item % nblk, k0 = 64 * kb, n0 = 32 * nb;
;     { float wv[32];
;       const float* wp = W + (size_t)(k0 + (lane >> 5)) * ldw + n0 + (lane & 31);
; #pragma unroll
;       for (int i = 0; i < 32; ++i) wv[i] = wp[(size_t)(2 * i) * ldw];
; #pragma unroll
;       for (int i = 0; i < 32; ++i) scr[(2 * i + (lane >> 5)) * 33 + (lane & 31)] = wv[i]; }
;     LDS_WAIT(); asm volatile("" ::: "memory");
;     const int c = lane & 7;
;     const int r0 = (mode == 0) ? n0 : (256 * (n0 >> 7) + (n0 & 127) + (mode == 2 ? 128 : 0));
; #pragma unroll
;     for (int j = 0; j < 4; ++j) { const int n = (lane >> 3) + 8 * j; const LAS float* s = scr + (8 * c) * 33 + n;
;         v4u o; o.x = pk2(s[0 * 33], s[1 * 33]); o.y = pk2(s[2 * 33], s[3 * 33]); o.z = pk2(s[4 * 33], s[5 * 33]); o.w = pk2(s[6 * 33], s[7 * 33]);
;         *(GAS v4u*)(WT + (size_t)(r0 + n) * ldt + k0 + 8 * c) = o; }
;     LDS_WAIT(); asm volatile("" ::: "memory");
; }
	ds_write2_b32 v15, v24, v25 offset1:1
	ds_write2_b32 v15, v26, v27 offset0:2 offset1:3
	ds_write2_b32 v16, v28, v29 offset1:1
	ds_write2_b32 v16, v30, v31 offset0:2 offset1:3
	ds_write2_b32 v17, v32, v33 offset1:1
	ds_write2_b32 v17, v34, v35 offset0:2 offset1:3
	ds_write2_b32 v18, v36, v37 offset1:1
	ds_write2_b32 v18, v38, v39 offset0:2 offset1:3
	ds_write2_b32 v19, v40, v41 offset1:1
	ds_write2_b32 v19, v42, v43 offset0:2 offset1:3
	ds_write2_b32 v20, v44, v45 offset1:1
	ds_write2_b32 v20, v46, v47 offset0:2 offset1:3
	ds_write2_b32 v21, v48, v49 offset1:1
	ds_write2_b32 v21, v50, v51 offset0:2 offset1:3
	ds_write2_b32 v22, v52, v53 offset1:1
	ds_write2_b32 v22, v54, v55 offset0:2 offset1:3
	s_waitcnt lgkmcnt(0)
	ds_read2_b32 v[120:121], v23 offset0:0 offset1:33
	ds_read2_b32 v[122:123], v23 offset0:66 offset1:99
	ds_read2_b32 v[124:125], v23 offset0:132 offset1:165
	ds_read2_b32 v[126:127], v23 offset0:198 offset1:231
	s_waitcnt lgkmcnt(0)
	v_cvt_pk_bf16_f32 v128, v120, v121
	v_cvt_pk_bf16_f32 v129, v122, v123
	v_cvt_pk_bf16_f32 v130, v124, v125
	v_cvt_pk_bf16_f32 v131, v126, v127
	global_store_dwordx4 v11, v[128:131], s[42:43]
	s_nop 1
	ds_read2_b32 v[120:121], v23 offset0:8 offset1:41
	ds_read2_b32 v[122:123], v23 offset0:74 offset1:107
	ds_read2_b32 v[124:125], v23 offset0:140 offset1:173
	ds_read2_b32 v[126:127], v23 offset0:206 offset1:239
	s_waitcnt lgkmcnt(0)
	v_cvt_pk_bf16_f32 v128, v120, v121
	v_cvt_pk_bf16_f32 v129, v122, v123
	v_cvt_pk_bf16_f32 v130, v124, v125
	v_cvt_pk_bf16_f32 v131, v126, v127
	global_store_dwordx4 v12, v[128:131], s[42:43]
	s_nop 1
	ds_read2_b32 v[120:121], v23 offset0:16 offset1:49
	ds_read2_b32 v[122:123], v23 offset0:82 offset1:115
	ds_read2_b32 v[124:125], v23 offset0:148 offset1:181
	ds_read2_b32 v[126:127], v23 offset0:214 offset1:247
	s_waitcnt lgkmcnt(0)
	v_cvt_pk_bf16_f32 v128, v120, v121
	v_cvt_pk_bf16_f32 v129, v122, v123
	v_cvt_pk_bf16_f32 v130, v124, v125
	v_cvt_pk_bf16_f32 v131, v126, v127
	global_store_dwordx4 v13, v[128:131], s[42:43]
	s_nop 1
	ds_read2_b32 v[120:121], v23 offset0:24 offset1:57
	ds_read2_b32 v[122:123], v23 offset0:90 offset1:123
	ds_read2_b32 v[124:125], v23 offset0:156 offset1:189
	ds_read2_b32 v[126:127], v23 offset0:222 offset1:255
	s_waitcnt lgkmcnt(0)
	v_cvt_pk_bf16_f32 v128, v120, v121
	v_cvt_pk_bf16_f32 v129, v122, v123
	v_cvt_pk_bf16_f32 v130, v124, v125
	v_cvt_pk_bf16_f32 v131, v126, v127
	global_store_dwordx4 v14, v[128:131], s[42:43]
	s_nop 1
	s_add_i32 s48, s44, 0xb40
	s_lshr_b32 s46, s48, 6
	s_and_b32 s47, s48, 63
	s_lshl_b32 s40, s46, 19
	s_lshl_b32 s41, s47, 7
	s_add_u32 s40, s40, s41
	s_add_u32 s40, s40, s36
	s_addc_u32 s41, s37, 0
	global_load_dwordx4 v[24:27], v3, s[40:41]
	global_load_dwordx4 v[28:31], v4, s[40:41]
	global_load_dwordx4 v[32:35], v5, s[40:41]
	global_load_dwordx4 v[36:39], v6, s[40:41]
	global_load_dwordx4 v[40:43], v7, s[40:41]
	global_load_dwordx4 v[44:47], v8, s[40:41]
	global_load_dwordx4 v[48:51], v9, s[40:41]
	global_load_dwordx4 v[52:55], v10, s[40:41]
	s_add_i32 s48, s44, 0x8c0
	s_lshr_b32 s46, s48, 6
	s_and_b32 s47, s48, 63
	s_mul_i32 s42, s47, 0x58000
	s_lshl_b32 s43, s46, 7
	s_add_u32 s42, s42, s43
	s_add_u32 s42, s42, s38
	s_addc_u32 s43, s39, 0
	s_waitcnt vmcnt(24)
	ds_write2_b32 v15, v56, v57 offset1:1
	ds_write2_b32 v15, v58, v59 offset0:2 offset1:3
	ds_write2_b32 v16, v60, v61 offset1:1
	ds_write2_b32 v16, v62, v63 offset0:2 offset1:3
	ds_write2_b32 v17, v64, v65 offset1:1
	ds_write2_b32 v17, v66, v67 offset0:2 offset1:3
	ds_write2_b32 v18, v68, v69 offset1:1
	ds_write2_b32 v18, v70, v71 offset0:2 offset1:3
	ds_write2_b32 v19, v72, v73 offset1:1
	ds_write2_b32 v19, v74, v75 offset0:2 offset1:3
	ds_write2_b32 v20, v76, v77 offset1:1
	ds_write2_b32 v20, v78, v79 offset0:2 offset1:3
	ds_write2_b32 v21, v80, v81 offset1:1
	ds_write2_b32 v21, v82, v83 offset0:2 offset1:3
	ds_write2_b32 v22, v84, v85 offset1:1
	ds_write2_b32 v22, v86, v87 offset0:2 offset1:3
	s_waitcnt lgkmcnt(0)
	ds_read2_b32 v[120:121], v23 offset0:0 offset1:33
	ds_read2_b32 v[122:123], v23 offset0:66 offset1:99
	ds_read2_b32 v[124:125], v23 offset0:132 offset1:165
	ds_read2_b32 v[126:127], v23 offset0:198 offset1:231
	s_waitcnt lgkmcnt(0)
	v_cvt_pk_bf16_f32 v128, v120, v121
	v_cvt_pk_bf16_f32 v129, v122, v123
	v_cvt_pk_bf16_f32 v130, v124, v125
	v_cvt_pk_bf16_f32 v131, v126, v127
	global_store_dwordx4 v11, v[128:131], s[42:43]
	s_nop 1
	ds_read2_b32 v[120:121], v23 offset0:8 offset1:41
	ds_read2_b32 v[122:123], v23 offset0:74 offset1:107
	ds_read2_b32 v[124:125], v23 offset0:140 offset1:173
	ds_read2_b32 v[126:127], v23 offset0:206 offset1:239
	s_waitcnt lgkmcnt(0)
	v_cvt_pk_bf16_f32 v128, v120, v121
	v_cvt_pk_bf16_f32 v129, v122, v123
	v_cvt_pk_bf16_f32 v130, v124, v125
	v_cvt_pk_bf16_f32 v131, v126, v127
	global_store_dwordx4 v12, v[128:131], s[42:43]
	s_nop 1
	ds_read2_b32 v[120:121], v23 offset0:16 offset1:49
	ds_read2_b32 v[122:123], v23 offset0:82 offset1:115
	ds_read2_b32 v[124:125], v23 offset0:148 offset1:181
	ds_read2_b32 v[126:127], v23 offset0:214 offset1:247
	s_waitcnt lgkmcnt(0)
	v_cvt_pk_bf16_f32 v128, v120, v121
	v_cvt_pk_bf16_f32 v129, v122, v123
	v_cvt_pk_bf16_f32 v130, v124, v125
	v_cvt_pk_bf16_f32 v131, v126, v127
	global_store_dwordx4 v13, v[128:131], s[42:43]
	s_nop 1
	ds_read2_b32 v[120:121], v23 offset0:24 offset1:57
	ds_read2_b32 v[122:123], v23 offset0:90 offset1:123
	ds_read2_b32 v[124:125], v23 offset0:156 offset1:189
	ds_read2_b32 v[126:127], v23 offset0:222 offset1:255
	s_waitcnt lgkmcnt(0)
; #define GAS __attribute__((address_space(1)))
; #define LAS __attribute__((address_space(3)))
; #define LDS_WAIT() asm volatile("s_waitcnt lgkmcnt(0)" ::: "memory")
; __device__ __forceinline__ unsigned pk2(float lo, float hi) { return f2bf(lo) | (f2bf(hi) << 16); }
;     if (ldt == 0) ldt = K;
;     asm volatile("" : "+v"(lane));
;     const int kb = item / nblk, nb = item % nblk, k0 = 64 * kb, n0 = 32 * nb;
;     { float wv[32];
;       const float* wp = W + (size_t)(k0 + (lane >> 5)) * ldw + n0 + (lane & 31);
; #pragma unroll
;       for (int i = 0; i < 32; ++i) wv[i] = wp[(size_t)(2 * i) * ldw];
; #pragma unroll
;       for (int i = 0; i < 32; ++i) scr[(2 * i + (lane >> 5)) * 33 + (lane & 31)] = wv[i]; }
;     LDS_WAIT(); asm volatile("" ::: "memory");
;     const int c = lane & 7;
;     const int r0 = (mode == 0) ? n0 : (256 * (n0 >> 7) + (n0 & 127) + (mode == 2 ? 128 : 0));
; #pragma unroll
;     for (int j = 0; j < 4; ++j) { const int n = (lane >> 3) + 8 * j; const LAS float* s = scr + (8 * c) * 33 + n;
;         v4u o; o.x = pk2(s[0 * 33], s[1 * 33]); o.y = pk2(s[2 * 33], s[3 * 33]); o.z = pk2(s[4 * 33], s[5 * 33]); o.w = pk2(s[6 * 33], s[7 * 33]);
;         *(GAS v4u*)(WT + (size_t)(r0 + n) * ldt + k0 + 8 * c) = o; }
;     LDS_WAIT(); asm volatile("" ::: "memory");
; }
	v_cvt_pk_bf16_f32 v128, v120, v121
	v_cvt_pk_bf16_f32 v129, v122, v123
	v_cvt_pk_bf16_f32 v130, v124, v125
	v_cvt_pk_bf16_f32 v131, v126, v127
	global_store_dwordx4 v14, v[128:131], s[42:43]
	s_nop 1
	s_add_i32 s48, s44, 0xc80
	s_lshr_b32 s46, s48, 6
	s_and_b32 s47, s48, 63
	s_lshl_b32 s40, s46, 19
	s_lshl_b32 s41, s47, 7
	s_add_u32 s40, s40, s41
	s_add_u32 s40, s40, s36
	s_addc_u32 s41, s37, 0
	global_load_dwordx4 v[56:59], v3, s[40:41]
	global_load_dwordx4 v[60:63], v4, s[40:41]
	global_load_dwordx4 v[64:67], v5, s[40:41]
	global_load_dwordx4 v[68:71], v6, s[40:41]
	global_load_dwordx4 v[72:75], v7, s[40:41]
	global_load_dwordx4 v[76:79], v8, s[40:41]
	global_load_dwordx4 v[80:83], v9, s[40:41]
	global_load_dwordx4 v[84:87], v10, s[40:41]
	s_add_i32 s48, s44, 0xa00
	s_lshr_b32 s46, s48, 6
	s_and_b32 s47, s48, 63
	s_mul_i32 s42, s47, 0x58000
	s_lshl_b32 s43, s46, 7
	s_add_u32 s42, s42, s43
	s_add_u32 s42, s42, s38
	s_addc_u32 s43, s39, 0
	s_waitcnt vmcnt(24)
	ds_write2_b32 v15, v88, v89 offset1:1
	ds_write2_b32 v15, v90, v91 offset0:2 offset1:3
	ds_write2_b32 v16, v92, v93 offset1:1
	ds_write2_b32 v16, v94, v95 offset0:2 offset1:3
	ds_write2_b32 v17, v96, v97 offset1:1
	ds_write2_b32 v17, v98, v99 offset0:2 offset1:3
	ds_write2_b32 v18, v100, v101 offset1:1
	ds_write2_b32 v18, v102, v103 offset0:2 offset1:3
	ds_write2_b32 v19, v104, v105 offset1:1
	ds_write2_b32 v19, v106, v107 offset0:2 offset1:3
	ds_write2_b32 v20, v108, v109 offset1:1
	ds_write2_b32 v20, v110, v111 offset0:2 offset1:3
	ds_write2_b32 v21, v112, v113 offset1:1
	ds_write2_b32 v21, v114, v115 offset0:2 offset1:3
	ds_write2_b32 v22, v116, v117 offset1:1
	ds_write2_b32 v22, v118, v119 offset0:2 offset1:3
	s_waitcnt lgkmcnt(0)
	ds_read2_b32 v[120:121], v23 offset0:0 offset1:33
	ds_read2_b32 v[122:123], v23 offset0:66 offset1:99
	ds_read2_b32 v[124:125], v23 offset0:132 offset1:165
	ds_read2_b32 v[126:127], v23 offset0:198 offset1:231
	s_waitcnt lgkmcnt(0)
	v_cvt_pk_bf16_f32 v128, v120, v121
	v_cvt_pk_bf16_f32 v129, v122, v123
	v_cvt_pk_bf16_f32 v130, v124, v125
	v_cvt_pk_bf16_f32 v131, v126, v127
	global_store_dwordx4 v11, v[128:131], s[42:43]
	s_nop 1
	ds_read2_b32 v[120:121], v23 offset0:8 offset1:41
	ds_read2_b32 v[122:123], v23 offset0:74 offset1:107
	ds_read2_b32 v[124:125], v23 offset0:140 offset1:173
	ds_read2_b32 v[126:127], v23 offset0:206 offset1:239
	s_waitcnt lgkmcnt(0)
	v_cvt_pk_bf16_f32 v128, v120, v121
	v_cvt_pk_bf16_f32 v129, v122, v123
	v_cvt_pk_bf16_f32 v130, v124, v125
	v_cvt_pk_bf16_f32 v131, v126, v127
	global_store_dwordx4 v12, v[128:131], s[42:43]
	s_nop 1
	ds_read2_b32 v[120:121], v23 offset0:16 offset1:49
	ds_read2_b32 v[122:123], v23 offset0:82 offset1:115
	ds_read2_b32 v[124:125], v23 offset0:148 offset1:181
	ds_read2_b32 v[126:127], v23 offset0:214 offset1:247
	s_waitcnt lgkmcnt(0)
	v_cvt_pk_bf16_f32 v128, v120, v121
	v_cvt_pk_bf16_f32 v129, v122, v123
	v_cvt_pk_bf16_f32 v130, v124, v125
	v_cvt_pk_bf16_f32 v131, v126, v127
	global_store_dwordx4 v13, v[128:131], s[42:43]
	s_nop 1
	ds_read2_b32 v[120:121], v23 offset0:24 offset1:57
	ds_read2_b32 v[122:123], v23 offset0:90 offset1:123
	ds_read2_b32 v[124:125], v23 offset0:156 offset1:189
	ds_read2_b32 v[126:127], v23 offset0:222 offset1:255
	s_waitcnt lgkmcnt(0)
	v_cvt_pk_bf16_f32 v128, v120, v121
	v_cvt_pk_bf16_f32 v129, v122, v123
	v_cvt_pk_bf16_f32 v130, v124, v125
	v_cvt_pk_bf16_f32 v131, v126, v127
	global_store_dwordx4 v14, v[128:131], s[42:43]
	s_nop 1
	s_add_i32 s48, s44, 0xdc0
	s_lshr_b32 s46, s48, 6
	s_and_b32 s47, s48, 63
	s_lshl_b32 s40, s46, 19
	s_lshl_b32 s41, s47, 7
	s_add_u32 s40, s40, s41
	s_add_u32 s40, s40, s36
	s_addc_u32 s41, s37, 0
	global_load_dwordx4 v[88:91], v3, s[40:41]
	global_load_dwordx4 v[92:95], v4, s[40:41]
	global_load_dwordx4 v[96:99], v5, s[40:41]
	global_load_dwordx4 v[100:103], v6, s[40:41]
	global_load_dwordx4 v[104:107], v7, s[40:41]
	global_load_dwordx4 v[108:111], v8, s[40:41]
	global_load_dwordx4 v[112:115], v9, s[40:41]
	global_load_dwordx4 v[116:119], v10, s[40:41]
	s_add_i32 s48, s44, 0xb40
	s_lshr_b32 s46, s48, 6
	s_and_b32 s47, s48, 63
	s_mul_i32 s42, s47, 0x58000
	s_lshl_b32 s43, s46, 7
	s_add_u32 s42, s42, s43
	s_add_u32 s42, s42, s38
	s_addc_u32 s43, s39, 0
	s_waitcnt vmcnt(24)
	ds_write2_b32 v15, v24, v25 offset1:1
	ds_write2_b32 v15, v26, v27 offset0:2 offset1:3
	ds_write2_b32 v16, v28, v29 offset1:1
	ds_write2_b32 v16, v30, v31 offset0:2 offset1:3
	ds_write2_b32 v17, v32, v33 offset1:1
	ds_write2_b32 v17, v34, v35 offset0:2 offset1:3
	ds_write2_b32 v18, v36, v37 offset1:1
	ds_write2_b32 v18, v38, v39 offset0:2 offset1:3
	ds_write2_b32 v19, v40, v41 offset1:1
	ds_write2_b32 v19, v42, v43 offset0:2 offset1:3
	ds_write2_b32 v20, v44, v45 offset1:1
	ds_write2_b32 v20, v46, v47 offset0:2 offset1:3
	ds_write2_b32 v21, v48, v49 offset1:1
	ds_write2_b32 v21, v50, v51 offset0:2 offset1:3
	ds_write2_b32 v22, v52, v53 offset1:1
	ds_write2_b32 v22, v54, v55 offset0:2 offset1:3
	s_waitcnt lgkmcnt(0)
	ds_read2_b32 v[120:121], v23 offset0:0 offset1:33
	ds_read2_b32 v[122:123], v23 offset0:66 offset1:99
	ds_read2_b32 v[124:125], v23 offset0:132 offset1:165
	ds_read2_b32 v[126:127], v23 offset0:198 offset1:231
	s_waitcnt lgkmcnt(0)
	v_cvt_pk_bf16_f32 v128, v120, v121
	v_cvt_pk_bf16_f32 v129, v122, v123
	v_cvt_pk_bf16_f32 v130, v124, v125
	v_cvt_pk_bf16_f32 v131, v126, v127
	global_store_dwordx4 v11, v[128:131], s[42:43]
	s_nop 1
	ds_read2_b32 v[120:121], v23 offset0:8 offset1:41
	ds_read2_b32 v[122:123], v23 offset0:74 offset1:107
	ds_read2_b32 v[124:125], v23 offset0:140 offset1:173
	ds_read2_b32 v[126:127], v23 offset0:206 offset1:239
	s_waitcnt lgkmcnt(0)
; #define GAS __attribute__((address_space(1)))
; #define LAS __attribute__((address_space(3)))
; #define LDS_WAIT() asm volatile("s_waitcnt lgkmcnt(0)" ::: "memory")
; __device__ __forceinline__ unsigned pk2(float lo, float hi) { return f2bf(lo) | (f2bf(hi) << 16); }
;     if (ldt == 0) ldt = K;
;     asm volatile("" : "+v"(lane));
;     const int kb = item / nblk, nb = item % nblk, k0 = 64 * kb, n0 = 32 * nb;
;     { float wv[32];
;       const float* wp = W + (size_t)(k0 + (lane >> 5)) * ldw + n0 + (lane & 31);
; #pragma unroll
;       for (int i = 0; i < 32; ++i) wv[i] = wp[(size_t)(2 * i) * ldw];
; #pragma unroll
;       for (int i = 0; i < 32; ++i) scr[(2 * i + (lane >> 5)) * 33 + (lane & 31)] = wv[i]; }
;     LDS_WAIT(); asm volatile("" ::: "memory");
;     const int c = lane & 7;
;     const int r0 = (mode == 0) ? n0 : (256 * (n0 >> 7) + (n0 & 127) + (mode == 2 ? 128 : 0));
; #pragma unroll
;     for (int j = 0; j < 4; ++j) { const int n = (lane >> 3) + 8 * j; const LAS float* s = scr + (8 * c) * 33 + n;
;         v4u o; o.x = pk2(s[0 * 33], s[1 * 33]); o.y = pk2(s[2 * 33], s[3 * 33]); o.z = pk2(s[4 * 33], s[5 * 33]); o.w = pk2(s[6 * 33], s[7 * 33]);
;         *(GAS v4u*)(WT + (size_t)(r0 + n) * ldt + k0 + 8 * c) = o; }
;     LDS_WAIT(); asm volatile("" ::: "memory");
; }
; template <bool LATE = false>
; __device__ __forceinline__ void transpose_tail(Frame& F, const Args& a, int bx, int lo, int first, int count) {
;     if (F.G != 256 || bx < lo) return;
;     LAS float* scr = (LAS float*)(F.lds + F.wave * 16384);
;     for (int j = (bx - lo) * NWAVES + F.wave; j < count; j += (F.G - lo) * NWAVES) { if (LATE) transpose_late(a, F, scr, first + j); else transpose_early(a, F, scr, first + j); }
; }
	v_cvt_pk_bf16_f32 v128, v120, v121
	v_cvt_pk_bf16_f32 v129, v122, v123
	v_cvt_pk_bf16_f32 v130, v124, v125
	v_cvt_pk_bf16_f32 v131, v126, v127
	global_store_dwordx4 v12, v[128:131], s[42:43]
	s_nop 1
	ds_read2_b32 v[120:121], v23 offset0:16 offset1:49
	ds_read2_b32 v[122:123], v23 offset0:82 offset1:115
	ds_read2_b32 v[124:125], v23 offset0:148 offset1:181
	ds_read2_b32 v[126:127], v23 offset0:214 offset1:247
	s_waitcnt lgkmcnt(0)
	v_cvt_pk_bf16_f32 v128, v120, v121
	v_cvt_pk_bf16_f32 v129, v122, v123
	v_cvt_pk_bf16_f32 v130, v124, v125
	v_cvt_pk_bf16_f32 v131, v126, v127
	global_store_dwordx4 v13, v[128:131], s[42:43]
	s_nop 1
	ds_read2_b32 v[120:121], v23 offset0:24 offset1:57
	ds_read2_b32 v[122:123], v23 offset0:90 offset1:123
	ds_read2_b32 v[124:125], v23 offset0:156 offset1:189
	ds_read2_b32 v[126:127], v23 offset0:222 offset1:255
	s_waitcnt lgkmcnt(0)
	v_cvt_pk_bf16_f32 v128, v120, v121
	v_cvt_pk_bf16_f32 v129, v122, v123
	v_cvt_pk_bf16_f32 v130, v124, v125
	v_cvt_pk_bf16_f32 v131, v126, v127
	global_store_dwordx4 v14, v[128:131], s[42:43]
	s_nop 1
	s_add_i32 s48, s44, 0xf00
	s_lshr_b32 s46, s48, 6
	s_and_b32 s47, s48, 63
	s_lshl_b32 s40, s46, 19
	s_lshl_b32 s41, s47, 7
	s_add_u32 s40, s40, s41
	s_add_u32 s40, s40, s36
	s_addc_u32 s41, s37, 0
	global_load_dwordx4 v[24:27], v3, s[40:41]
	global_load_dwordx4 v[28:31], v4, s[40:41]
	global_load_dwordx4 v[32:35], v5, s[40:41]
	global_load_dwordx4 v[36:39], v6, s[40:41]
	global_load_dwordx4 v[40:43], v7, s[40:41]
	global_load_dwordx4 v[44:47], v8, s[40:41]
	global_load_dwordx4 v[48:51], v9, s[40:41]
	global_load_dwordx4 v[52:55], v10, s[40:41]
	s_add_i32 s48, s44, 0xc80
	s_lshr_b32 s46, s48, 6
	s_and_b32 s47, s48, 63
	s_mul_i32 s42, s47, 0x58000
	s_lshl_b32 s43, s46, 7
	s_add_u32 s42, s42, s43
	s_add_u32 s42, s42, s38
	s_addc_u32 s43, s39, 0
	s_waitcnt vmcnt(24)
	ds_write2_b32 v15, v56, v57 offset1:1
	ds_write2_b32 v15, v58, v59 offset0:2 offset1:3
	ds_write2_b32 v16, v60, v61 offset1:1
	ds_write2_b32 v16, v62, v63 offset0:2 offset1:3
	ds_write2_b32 v17, v64, v65 offset1:1
	ds_write2_b32 v17, v66, v67 offset0:2 offset1:3
	ds_write2_b32 v18, v68, v69 offset1:1
	ds_write2_b32 v18, v70, v71 offset0:2 offset1:3
	ds_write2_b32 v19, v72, v73 offset1:1
	ds_write2_b32 v19, v74, v75 offset0:2 offset1:3
	ds_write2_b32 v20, v76, v77 offset1:1
	ds_write2_b32 v20, v78, v79 offset0:2 offset1:3
	ds_write2_b32 v21, v80, v81 offset1:1
	ds_write2_b32 v21, v82, v83 offset0:2 offset1:3
	ds_write2_b32 v22, v84, v85 offset1:1
	ds_write2_b32 v22, v86, v87 offset0:2 offset1:3
	s_waitcnt lgkmcnt(0)
	ds_read2_b32 v[120:121], v23 offset0:0 offset1:33
	ds_read2_b32 v[122:123], v23 offset0:66 offset1:99
	ds_read2_b32 v[124:125], v23 offset0:132 offset1:165
	ds_read2_b32 v[126:127], v23 offset0:198 offset1:231
	s_waitcnt lgkmcnt(0)
	v_cvt_pk_bf16_f32 v128, v120, v121
	v_cvt_pk_bf16_f32 v129, v122, v123
	v_cvt_pk_bf16_f32 v130, v124, v125
	v_cvt_pk_bf16_f32 v131, v126, v127
	global_store_dwordx4 v11, v[128:131], s[42:43]
	s_nop 1
	ds_read2_b32 v[120:121], v23 offset0:8 offset1:41
	ds_read2_b32 v[122:123], v23 offset0:74 offset1:107
	ds_read2_b32 v[124:125], v23 offset0:140 offset1:173
	ds_read2_b32 v[126:127], v23 offset0:206 offset1:239
	s_waitcnt lgkmcnt(0)
	v_cvt_pk_bf16_f32 v128, v120, v121
	v_cvt_pk_bf16_f32 v129, v122, v123
	v_cvt_pk_bf16_f32 v130, v124, v125
	v_cvt_pk_bf16_f32 v131, v126, v127
	global_store_dwordx4 v12, v[128:131], s[42:43]
	s_nop 1
	ds_read2_b32 v[120:121], v23 offset0:16 offset1:49
	ds_read2_b32 v[122:123], v23 offset0:82 offset1:115
	ds_read2_b32 v[124:125], v23 offset0:148 offset1:181
	ds_read2_b32 v[126:127], v23 offset0:214 offset1:247
	s_waitcnt lgkmcnt(0)
	v_cvt_pk_bf16_f32 v128, v120, v121
	v_cvt_pk_bf16_f32 v129, v122, v123
	v_cvt_pk_bf16_f32 v130, v124, v125
	v_cvt_pk_bf16_f32 v131, v126, v127
	global_store_dwordx4 v13, v[128:131], s[42:43]
	s_nop 1
	ds_read2_b32 v[120:121], v23 offset0:24 offset1:57
	ds_read2_b32 v[122:123], v23 offset0:90 offset1:123
	ds_read2_b32 v[124:125], v23 offset0:156 offset1:189
	ds_read2_b32 v[126:127], v23 offset0:222 offset1:255
	s_waitcnt lgkmcnt(0)
	v_cvt_pk_bf16_f32 v128, v120, v121
	v_cvt_pk_bf16_f32 v129, v122, v123
	v_cvt_pk_bf16_f32 v130, v124, v125
	v_cvt_pk_bf16_f32 v131, v126, v127
	global_store_dwordx4 v14, v[128:131], s[42:43]
	s_nop 1
	s_add_i32 s48, s44, 0x1040
	s_lshr_b32 s46, s48, 6
	s_and_b32 s47, s48, 63
	s_lshl_b32 s40, s46, 19
	s_lshl_b32 s41, s47, 7
	s_add_u32 s40, s40, s41
	s_add_u32 s40, s40, s36
	s_addc_u32 s41, s37, 0
	global_load_dwordx4 v[56:59], v3, s[40:41]
	global_load_dwordx4 v[60:63], v4, s[40:41]
	global_load_dwordx4 v[64:67], v5, s[40:41]
	global_load_dwordx4 v[68:71], v6, s[40:41]
	global_load_dwordx4 v[72:75], v7, s[40:41]
	global_load_dwordx4 v[76:79], v8, s[40:41]
	global_load_dwordx4 v[80:83], v9, s[40:41]
	global_load_dwordx4 v[84:87], v10, s[40:41]
	s_add_i32 s48, s44, 0xdc0
	s_lshr_b32 s46, s48, 6
	s_and_b32 s47, s48, 63
	s_mul_i32 s42, s47, 0x58000
	s_lshl_b32 s43, s46, 7
	s_add_u32 s42, s42, s43
	s_add_u32 s42, s42, s38
	s_addc_u32 s43, s39, 0
	s_waitcnt vmcnt(24)
	ds_write2_b32 v15, v88, v89 offset1:1
	ds_write2_b32 v15, v90, v91 offset0:2 offset1:3
	ds_write2_b32 v16, v92, v93 offset1:1
	ds_write2_b32 v16, v94, v95 offset0:2 offset1:3
	ds_write2_b32 v17, v96, v97 offset1:1
	ds_write2_b32 v17, v98, v99 offset0:2 offset1:3
	ds_write2_b32 v18, v100, v101 offset1:1
	ds_write2_b32 v18, v102, v103 offset0:2 offset1:3
	ds_write2_b32 v19, v104, v105 offset1:1
	ds_write2_b32 v19, v106, v107 offset0:2 offset1:3
	ds_write2_b32 v20, v108, v109 offset1:1
	ds_write2_b32 v20, v110, v111 offset0:2 offset1:3
	ds_write2_b32 v21, v112, v113 offset1:1
	ds_write2_b32 v21, v114, v115 offset0:2 offset1:3
	ds_write2_b32 v22, v116, v117 offset1:1
	ds_write2_b32 v22, v118, v119 offset0:2 offset1:3
	s_waitcnt lgkmcnt(0)
; #define GAS __attribute__((address_space(1)))
; #define LAS __attribute__((address_space(3)))
; #define LDS_WAIT() asm volatile("s_waitcnt lgkmcnt(0)" ::: "memory")
; __device__ __forceinline__ unsigned pk2(float lo, float hi) { return f2bf(lo) | (f2bf(hi) << 16); }
;     if (ldt == 0) ldt = K;
;     asm volatile("" : "+v"(lane));
;     const int kb = item / nblk, nb = item % nblk, k0 = 64 * kb, n0 = 32 * nb;
;     { float wv[32];
;       const float* wp = W + (size_t)(k0 + (lane >> 5)) * ldw + n0 + (lane & 31);
; #pragma unroll
;       for (int i = 0; i < 32; ++i) wv[i] = wp[(size_t)(2 * i) * ldw];
; #pragma unroll
;       for (int i = 0; i < 32; ++i) scr[(2 * i + (lane >> 5)) * 33 + (lane & 31)] = wv[i]; }
;     LDS_WAIT(); asm volatile("" ::: "memory");
;     const int c = lane & 7;
;     const int r0 = (mode == 0) ? n0 : (256 * (n0 >> 7) + (n0 & 127) + (mode == 2 ? 128 : 0));
; #pragma unroll
;     for (int j = 0; j < 4; ++j) { const int n = (lane >> 3) + 8 * j; const LAS float* s = scr + (8 * c) * 33 + n;
;         v4u o; o.x = pk2(s[0 * 33], s[1 * 33]); o.y = pk2(s[2 * 33], s[3 * 33]); o.z = pk2(s[4 * 33], s[5 * 33]); o.w = pk2(s[6 * 33], s[7 * 33]);
;         *(GAS v4u*)(WT + (size_t)(r0 + n) * ldt + k0 + 8 * c) = o; }
;     LDS_WAIT(); asm volatile("" ::: "memory");
; }
; template <bool LATE = false>
; __device__ __forceinline__ void transpose_tail(Frame& F, const Args& a, int bx, int lo, int first, int count) {
;     if (F.G != 256 || bx < lo) return;
;     LAS float* scr = (LAS float*)(F.lds + F.wave * 16384);
;     for (int j = (bx - lo) * NWAVES + F.wave; j < count; j += (F.G - lo) * NWAVES) { if (LATE) transpose_late(a, F, scr, first + j); else transpose_early(a, F, scr, first + j); }
; }
	ds_read2_b32 v[120:121], v23 offset0:0 offset1:33
	ds_read2_b32 v[122:123], v23 offset0:66 offset1:99
	ds_read2_b32 v[124:125], v23 offset0:132 offset1:165
	ds_read2_b32 v[126:127], v23 offset0:198 offset1:231
	s_waitcnt lgkmcnt(0)
	v_cvt_pk_bf16_f32 v128, v120, v121
	v_cvt_pk_bf16_f32 v129, v122, v123
	v_cvt_pk_bf16_f32 v130, v124, v125
	v_cvt_pk_bf16_f32 v131, v126, v127
	global_store_dwordx4 v11, v[128:131], s[42:43]
	s_nop 1
	ds_read2_b32 v[120:121], v23 offset0:8 offset1:41
	ds_read2_b32 v[122:123], v23 offset0:74 offset1:107
	ds_read2_b32 v[124:125], v23 offset0:140 offset1:173
	ds_read2_b32 v[126:127], v23 offset0:206 offset1:239
	s_waitcnt lgkmcnt(0)
	v_cvt_pk_bf16_f32 v128, v120, v121
	v_cvt_pk_bf16_f32 v129, v122, v123
	v_cvt_pk_bf16_f32 v130, v124, v125
	v_cvt_pk_bf16_f32 v131, v126, v127
	global_store_dwordx4 v12, v[128:131], s[42:43]
	s_nop 1
	ds_read2_b32 v[120:121], v23 offset0:16 offset1:49
	ds_read2_b32 v[122:123], v23 offset0:82 offset1:115
	ds_read2_b32 v[124:125], v23 offset0:148 offset1:181
	ds_read2_b32 v[126:127], v23 offset0:214 offset1:247
	s_waitcnt lgkmcnt(0)
	v_cvt_pk_bf16_f32 v128, v120, v121
	v_cvt_pk_bf16_f32 v129, v122, v123
	v_cvt_pk_bf16_f32 v130, v124, v125
	v_cvt_pk_bf16_f32 v131, v126, v127
	global_store_dwordx4 v13, v[128:131], s[42:43]
	s_nop 1
	ds_read2_b32 v[120:121], v23 offset0:24 offset1:57
	ds_read2_b32 v[122:123], v23 offset0:90 offset1:123
	ds_read2_b32 v[124:125], v23 offset0:156 offset1:189
	ds_read2_b32 v[126:127], v23 offset0:222 offset1:255
	s_waitcnt lgkmcnt(0)
	v_cvt_pk_bf16_f32 v128, v120, v121
	v_cvt_pk_bf16_f32 v129, v122, v123
	v_cvt_pk_bf16_f32 v130, v124, v125
	v_cvt_pk_bf16_f32 v131, v126, v127
	global_store_dwordx4 v14, v[128:131], s[42:43]
	s_nop 1
	s_add_i32 s48, s44, 0x1180
	s_lshr_b32 s46, s48, 6
	s_and_b32 s47, s48, 63
	s_lshl_b32 s40, s46, 19
	s_lshl_b32 s41, s47, 7
	s_add_u32 s40, s40, s41
	s_add_u32 s40, s40, s36
	s_addc_u32 s41, s37, 0
	global_load_dwordx4 v[88:91], v3, s[40:41]
	global_load_dwordx4 v[92:95], v4, s[40:41]
	global_load_dwordx4 v[96:99], v5, s[40:41]
	global_load_dwordx4 v[100:103], v6, s[40:41]
	global_load_dwordx4 v[104:107], v7, s[40:41]
	global_load_dwordx4 v[108:111], v8, s[40:41]
	global_load_dwordx4 v[112:115], v9, s[40:41]
	global_load_dwordx4 v[116:119], v10, s[40:41]
	s_add_i32 s48, s44, 0xf00
	s_lshr_b32 s46, s48, 6
	s_and_b32 s47, s48, 63
	s_mul_i32 s42, s47, 0x58000
	s_lshl_b32 s43, s46, 7
	s_add_u32 s42, s42, s43
	s_add_u32 s42, s42, s38
	s_addc_u32 s43, s39, 0
	s_waitcnt vmcnt(24)
	ds_write2_b32 v15, v24, v25 offset1:1
	ds_write2_b32 v15, v26, v27 offset0:2 offset1:3
	ds_write2_b32 v16, v28, v29 offset1:1
	ds_write2_b32 v16, v30, v31 offset0:2 offset1:3
	ds_write2_b32 v17, v32, v33 offset1:1
	ds_write2_b32 v17, v34, v35 offset0:2 offset1:3
	ds_write2_b32 v18, v36, v37 offset1:1
	ds_write2_b32 v18, v38, v39 offset0:2 offset1:3
	ds_write2_b32 v19, v40, v41 offset1:1
	ds_write2_b32 v19, v42, v43 offset0:2 offset1:3
	ds_write2_b32 v20, v44, v45 offset1:1
	ds_write2_b32 v20, v46, v47 offset0:2 offset1:3
	ds_write2_b32 v21, v48, v49 offset1:1
	ds_write2_b32 v21, v50, v51 offset0:2 offset1:3
	ds_write2_b32 v22, v52, v53 offset1:1
	ds_write2_b32 v22, v54, v55 offset0:2 offset1:3
	s_waitcnt lgkmcnt(0)
	ds_read2_b32 v[120:121], v23 offset0:0 offset1:33
	ds_read2_b32 v[122:123], v23 offset0:66 offset1:99
	ds_read2_b32 v[124:125], v23 offset0:132 offset1:165
	ds_read2_b32 v[126:127], v23 offset0:198 offset1:231
	s_waitcnt lgkmcnt(0)
	v_cvt_pk_bf16_f32 v128, v120, v121
	v_cvt_pk_bf16_f32 v129, v122, v123
	v_cvt_pk_bf16_f32 v130, v124, v125
	v_cvt_pk_bf16_f32 v131, v126, v127
	global_store_dwordx4 v11, v[128:131], s[42:43]
	s_nop 1
	ds_read2_b32 v[120:121], v23 offset0:8 offset1:41
	ds_read2_b32 v[122:123], v23 offset0:74 offset1:107
	ds_read2_b32 v[124:125], v23 offset0:140 offset1:173
	ds_read2_b32 v[126:127], v23 offset0:206 offset1:239
	s_waitcnt lgkmcnt(0)
	v_cvt_pk_bf16_f32 v128, v120, v121
	v_cvt_pk_bf16_f32 v129, v122, v123
	v_cvt_pk_bf16_f32 v130, v124, v125
	v_cvt_pk_bf16_f32 v131, v126, v127
	global_store_dwordx4 v12, v[128:131], s[42:43]
	s_nop 1
	ds_read2_b32 v[120:121], v23 offset0:16 offset1:49
	ds_read2_b32 v[122:123], v23 offset0:82 offset1:115
	ds_read2_b32 v[124:125], v23 offset0:148 offset1:181
	ds_read2_b32 v[126:127], v23 offset0:214 offset1:247
	s_waitcnt lgkmcnt(0)
	v_cvt_pk_bf16_f32 v128, v120, v121
	v_cvt_pk_bf16_f32 v129, v122, v123
	v_cvt_pk_bf16_f32 v130, v124, v125
	v_cvt_pk_bf16_f32 v131, v126, v127
	global_store_dwordx4 v13, v[128:131], s[42:43]
	s_nop 1
	ds_read2_b32 v[120:121], v23 offset0:24 offset1:57
	ds_read2_b32 v[122:123], v23 offset0:90 offset1:123
	ds_read2_b32 v[124:125], v23 offset0:156 offset1:189
	ds_read2_b32 v[126:127], v23 offset0:222 offset1:255
	s_waitcnt lgkmcnt(0)
	v_cvt_pk_bf16_f32 v128, v120, v121
	v_cvt_pk_bf16_f32 v129, v122, v123
	v_cvt_pk_bf16_f32 v130, v124, v125
	v_cvt_pk_bf16_f32 v131, v126, v127
	global_store_dwordx4 v14, v[128:131], s[42:43]
	s_nop 1
	s_add_i32 s48, s44, 0x12c0
	s_lshr_b32 s46, s48, 6
	s_and_b32 s47, s48, 63
	s_lshl_b32 s40, s46, 19
	s_lshl_b32 s41, s47, 7
	s_add_u32 s40, s40, s41
	s_add_u32 s40, s40, s36
	s_addc_u32 s41, s37, 0
	global_load_dwordx4 v[24:27], v3, s[40:41]
	global_load_dwordx4 v[28:31], v4, s[40:41]
	global_load_dwordx4 v[32:35], v5, s[40:41]
	global_load_dwordx4 v[36:39], v6, s[40:41]
	global_load_dwordx4 v[40:43], v7, s[40:41]
	global_load_dwordx4 v[44:47], v8, s[40:41]
	global_load_dwordx4 v[48:51], v9, s[40:41]
	global_load_dwordx4 v[52:55], v10, s[40:41]
	s_add_i32 s48, s44, 0x1040
	s_lshr_b32 s46, s48, 6
	s_and_b32 s47, s48, 63
	s_mul_i32 s42, s47, 0x58000
	s_lshl_b32 s43, s46, 7
	s_add_u32 s42, s42, s43
	s_add_u32 s42, s42, s38
	s_addc_u32 s43, s39, 0
	s_waitcnt vmcnt(24)
; #define GAS __attribute__((address_space(1)))
; #define LAS __attribute__((address_space(3)))
; #define LDS_WAIT() asm volatile("s_waitcnt lgkmcnt(0)" ::: "memory")
; __device__ __forceinline__ unsigned pk2(float lo, float hi) { return f2bf(lo) | (f2bf(hi) << 16); }
;     if (ldt == 0) ldt = K;
;     asm volatile("" : "+v"(lane));
;     const int kb = item / nblk, nb = item % nblk, k0 = 64 * kb, n0 = 32 * nb;
;     { float wv[32];
;       const float* wp = W + (size_t)(k0 + (lane >> 5)) * ldw + n0 + (lane & 31);
; #pragma unroll
;       for (int i = 0; i < 32; ++i) wv[i] = wp[(size_t)(2 * i) * ldw];
; #pragma unroll
;       for (int i = 0; i < 32; ++i) scr[(2 * i + (lane >> 5)) * 33 + (lane & 31)] = wv[i]; }
;     LDS_WAIT(); asm volatile("" ::: "memory");
;     const int c = lane & 7;
;     const int r0 = (mode == 0) ? n0 : (256 * (n0 >> 7) + (n0 & 127) + (mode == 2 ? 128 : 0));
; #pragma unroll
;     for (int j = 0; j < 4; ++j) { const int n = (lane >> 3) + 8 * j; const LAS float* s = scr + (8 * c) * 33 + n;
;         v4u o; o.x = pk2(s[0 * 33], s[1 * 33]); o.y = pk2(s[2 * 33], s[3 * 33]); o.z = pk2(s[4 * 33], s[5 * 33]); o.w = pk2(s[6 * 33], s[7 * 33]);
;         *(GAS v4u*)(WT + (size_t)(r0 + n) * ldt + k0 + 8 * c) = o; }
;     LDS_WAIT(); asm volatile("" ::: "memory");
; }
; template <bool LATE = false>
; __device__ __forceinline__ void transpose_tail(Frame& F, const Args& a, int bx, int lo, int first, int count) {
;     if (F.G != 256 || bx < lo) return;
;     LAS float* scr = (LAS float*)(F.lds + F.wave * 16384);
;     for (int j = (bx - lo) * NWAVES + F.wave; j < count; j += (F.G - lo) * NWAVES) { if (LATE) transpose_late(a, F, scr, first + j); else transpose_early(a, F, scr, first + j); }
; }
	ds_write2_b32 v15, v56, v57 offset1:1
	ds_write2_b32 v15, v58, v59 offset0:2 offset1:3
	ds_write2_b32 v16, v60, v61 offset1:1
	ds_write2_b32 v16, v62, v63 offset0:2 offset1:3
	ds_write2_b32 v17, v64, v65 offset1:1
	ds_write2_b32 v17, v66, v67 offset0:2 offset1:3
	ds_write2_b32 v18, v68, v69 offset1:1
	ds_write2_b32 v18, v70, v71 offset0:2 offset1:3
	ds_write2_b32 v19, v72, v73 offset1:1
	ds_write2_b32 v19, v74, v75 offset0:2 offset1:3
	ds_write2_b32 v20, v76, v77 offset1:1
	ds_write2_b32 v20, v78, v79 offset0:2 offset1:3
	ds_write2_b32 v21, v80, v81 offset1:1
	ds_write2_b32 v21, v82, v83 offset0:2 offset1:3
	ds_write2_b32 v22, v84, v85 offset1:1
	ds_write2_b32 v22, v86, v87 offset0:2 offset1:3
	s_waitcnt lgkmcnt(0)
	ds_read2_b32 v[120:121], v23 offset0:0 offset1:33
	ds_read2_b32 v[122:123], v23 offset0:66 offset1:99
	ds_read2_b32 v[124:125], v23 offset0:132 offset1:165
	ds_read2_b32 v[126:127], v23 offset0:198 offset1:231
	s_waitcnt lgkmcnt(0)
	v_cvt_pk_bf16_f32 v128, v120, v121
	v_cvt_pk_bf16_f32 v129, v122, v123
	v_cvt_pk_bf16_f32 v130, v124, v125
	v_cvt_pk_bf16_f32 v131, v126, v127
	global_store_dwordx4 v11, v[128:131], s[42:43]
	s_nop 1
	ds_read2_b32 v[120:121], v23 offset0:8 offset1:41
	ds_read2_b32 v[122:123], v23 offset0:74 offset1:107
	ds_read2_b32 v[124:125], v23 offset0:140 offset1:173
	ds_read2_b32 v[126:127], v23 offset0:206 offset1:239
	s_waitcnt lgkmcnt(0)
	v_cvt_pk_bf16_f32 v128, v120, v121
	v_cvt_pk_bf16_f32 v129, v122, v123
	v_cvt_pk_bf16_f32 v130, v124, v125
	v_cvt_pk_bf16_f32 v131, v126, v127
	global_store_dwordx4 v12, v[128:131], s[42:43]
	s_nop 1
	ds_read2_b32 v[120:121], v23 offset0:16 offset1:49
	ds_read2_b32 v[122:123], v23 offset0:82 offset1:115
	ds_read2_b32 v[124:125], v23 offset0:148 offset1:181
	ds_read2_b32 v[126:127], v23 offset0:214 offset1:247
	s_waitcnt lgkmcnt(0)
	v_cvt_pk_bf16_f32 v128, v120, v121
	v_cvt_pk_bf16_f32 v129, v122, v123
	v_cvt_pk_bf16_f32 v130, v124, v125
	v_cvt_pk_bf16_f32 v131, v126, v127
	global_store_dwordx4 v13, v[128:131], s[42:43]
	s_nop 1
	ds_read2_b32 v[120:121], v23 offset0:24 offset1:57
	ds_read2_b32 v[122:123], v23 offset0:90 offset1:123
	ds_read2_b32 v[124:125], v23 offset0:156 offset1:189
	ds_read2_b32 v[126:127], v23 offset0:222 offset1:255
	s_waitcnt lgkmcnt(0)
	v_cvt_pk_bf16_f32 v128, v120, v121
	v_cvt_pk_bf16_f32 v129, v122, v123
	v_cvt_pk_bf16_f32 v130, v124, v125
	v_cvt_pk_bf16_f32 v131, v126, v127
	global_store_dwordx4 v14, v[128:131], s[42:43]
	s_nop 1
	s_add_i32 s48, s44, 0x1400
	s_lshr_b32 s46, s48, 6
	s_and_b32 s47, s48, 63
	s_lshl_b32 s40, s46, 19
	s_lshl_b32 s41, s47, 7
	s_add_u32 s40, s40, s41
	s_add_u32 s40, s40, s36
	s_addc_u32 s41, s37, 0
	global_load_dwordx4 v[56:59], v3, s[40:41]
	global_load_dwordx4 v[60:63], v4, s[40:41]
	global_load_dwordx4 v[64:67], v5, s[40:41]
	global_load_dwordx4 v[68:71], v6, s[40:41]
	global_load_dwordx4 v[72:75], v7, s[40:41]
	global_load_dwordx4 v[76:79], v8, s[40:41]
	global_load_dwordx4 v[80:83], v9, s[40:41]
	global_load_dwordx4 v[84:87], v10, s[40:41]
	s_add_i32 s48, s44, 0x1180
	s_lshr_b32 s46, s48, 6
	s_and_b32 s47, s48, 63
	s_mul_i32 s42, s47, 0x58000
	s_lshl_b32 s43, s46, 7
	s_add_u32 s42, s42, s43
	s_add_u32 s42, s42, s38
	s_addc_u32 s43, s39, 0
	s_waitcnt vmcnt(24)
	ds_write2_b32 v15, v88, v89 offset1:1
	ds_write2_b32 v15, v90, v91 offset0:2 offset1:3
	ds_write2_b32 v16, v92, v93 offset1:1
	ds_write2_b32 v16, v94, v95 offset0:2 offset1:3
	ds_write2_b32 v17, v96, v97 offset1:1
	ds_write2_b32 v17, v98, v99 offset0:2 offset1:3
	ds_write2_b32 v18, v100, v101 offset1:1
	ds_write2_b32 v18, v102, v103 offset0:2 offset1:3
	ds_write2_b32 v19, v104, v105 offset1:1
	ds_write2_b32 v19, v106, v107 offset0:2 offset1:3
	ds_write2_b32 v20, v108, v109 offset1:1
	ds_write2_b32 v20, v110, v111 offset0:2 offset1:3
	ds_write2_b32 v21, v112, v113 offset1:1
	ds_write2_b32 v21, v114, v115 offset0:2 offset1:3
	ds_write2_b32 v22, v116, v117 offset1:1
	ds_write2_b32 v22, v118, v119 offset0:2 offset1:3
	s_waitcnt lgkmcnt(0)
	ds_read2_b32 v[120:121], v23 offset0:0 offset1:33
	ds_read2_b32 v[122:123], v23 offset0:66 offset1:99
	ds_read2_b32 v[124:125], v23 offset0:132 offset1:165
	ds_read2_b32 v[126:127], v23 offset0:198 offset1:231
	s_waitcnt lgkmcnt(0)
	v_cvt_pk_bf16_f32 v128, v120, v121
	v_cvt_pk_bf16_f32 v129, v122, v123
	v_cvt_pk_bf16_f32 v130, v124, v125
	v_cvt_pk_bf16_f32 v131, v126, v127
	global_store_dwordx4 v11, v[128:131], s[42:43]
	s_nop 1
	ds_read2_b32 v[120:121], v23 offset0:8 offset1:41
	ds_read2_b32 v[122:123], v23 offset0:74 offset1:107
	ds_read2_b32 v[124:125], v23 offset0:140 offset1:173
	ds_read2_b32 v[126:127], v23 offset0:206 offset1:239
	s_waitcnt lgkmcnt(0)
	v_cvt_pk_bf16_f32 v128, v120, v121
	v_cvt_pk_bf16_f32 v129, v122, v123
	v_cvt_pk_bf16_f32 v130, v124, v125
	v_cvt_pk_bf16_f32 v131, v126, v127
	global_store_dwordx4 v12, v[128:131], s[42:43]
	s_nop 1
	ds_read2_b32 v[120:121], v23 offset0:16 offset1:49
	ds_read2_b32 v[122:123], v23 offset0:82 offset1:115
	ds_read2_b32 v[124:125], v23 offset0:148 offset1:181
	ds_read2_b32 v[126:127], v23 offset0:214 offset1:247
	s_waitcnt lgkmcnt(0)
	v_cvt_pk_bf16_f32 v128, v120, v121
	v_cvt_pk_bf16_f32 v129, v122, v123
	v_cvt_pk_bf16_f32 v130, v124, v125
	v_cvt_pk_bf16_f32 v131, v126, v127
	global_store_dwordx4 v13, v[128:131], s[42:43]
	s_nop 1
	ds_read2_b32 v[120:121], v23 offset0:24 offset1:57
	ds_read2_b32 v[122:123], v23 offset0:90 offset1:123
	ds_read2_b32 v[124:125], v23 offset0:156 offset1:189
	ds_read2_b32 v[126:127], v23 offset0:222 offset1:255
	s_waitcnt lgkmcnt(0)
	v_cvt_pk_bf16_f32 v128, v120, v121
	v_cvt_pk_bf16_f32 v129, v122, v123
	v_cvt_pk_bf16_f32 v130, v124, v125
	v_cvt_pk_bf16_f32 v131, v126, v127
	global_store_dwordx4 v14, v[128:131], s[42:43]
	s_nop 1
	s_cmpk_lt_i32 s44, 0xc0
	s_cbranch_scc0 .Ltr1dP12_no14
	s_add_i32 s48, s44, 0x1540
	s_lshr_b32 s46, s48, 6
	s_and_b32 s47, s48, 63
	s_lshl_b32 s40, s46, 19
	s_lshl_b32 s41, s47, 7
	s_add_u32 s40, s40, s41
	s_add_u32 s40, s40, s36
	s_addc_u32 s41, s37, 0
	global_load_dwordx4 v[88:91], v3, s[40:41]
	global_load_dwordx4 v[92:95], v4, s[40:41]
	global_load_dwordx4 v[96:99], v5, s[40:41]
	global_load_dwordx4 v[100:103], v6, s[40:41]
	global_load_dwordx4 v[104:107], v7, s[40:41]
	global_load_dwordx4 v[108:111], v8, s[40:41]
	global_load_dwordx4 v[112:115], v9, s[40:41]
	global_load_dwordx4 v[116:119], v10, s[40:41]
; #define GAS __attribute__((address_space(1)))
; #define LAS __attribute__((address_space(3)))
; #define LDS_WAIT() asm volatile("s_waitcnt lgkmcnt(0)" ::: "memory")
; __device__ __forceinline__ unsigned pk2(float lo, float hi) { return f2bf(lo) | (f2bf(hi) << 16); }
;     if (ldt == 0) ldt = K;
;     asm volatile("" : "+v"(lane));
;     const int kb = item / nblk, nb = item % nblk, k0 = 64 * kb, n0 = 32 * nb;
;     { float wv[32];
;       const float* wp = W + (size_t)(k0 + (lane >> 5)) * ldw + n0 + (lane & 31);
; #pragma unroll
;       for (int i = 0; i < 32; ++i) wv[i] = wp[(size_t)(2 * i) * ldw];
; #pragma unroll
;       for (int i = 0; i < 32; ++i) scr[(2 * i + (lane >> 5)) * 33 + (lane & 31)] = wv[i]; }
;     LDS_WAIT(); asm volatile("" ::: "memory");
;     const int c = lane & 7;
;     const int r0 = (mode == 0) ? n0 : (256 * (n0 >> 7) + (n0 & 127) + (mode == 2 ? 128 : 0));
; #pragma unroll
;     for (int j = 0; j < 4; ++j) { const int n = (lane >> 3) + 8 * j; const LAS float* s = scr + (8 * c) * 33 + n;
;         v4u o; o.x = pk2(s[0 * 33], s[1 * 33]); o.y = pk2(s[2 * 33], s[3 * 33]); o.z = pk2(s[4 * 33], s[5 * 33]); o.w = pk2(s[6 * 33], s[7 * 33]);
;         *(GAS v4u*)(WT + (size_t)(r0 + n) * ldt + k0 + 8 * c) = o; }
;     LDS_WAIT(); asm volatile("" ::: "memory");
; }
; template <bool LATE = false>
; __device__ __forceinline__ void transpose_tail(Frame& F, const Args& a, int bx, int lo, int first, int count) {
;     if (F.G != 256 || bx < lo) return;
;     LAS float* scr = (LAS float*)(F.lds + F.wave * 16384);
;     for (int j = (bx - lo) * NWAVES + F.wave; j < count; j += (F.G - lo) * NWAVES) { if (LATE) transpose_late(a, F, scr, first + j); else transpose_early(a, F, scr, first + j); }
; }
.Ltr1dP12_no14:
	s_add_i32 s48, s44, 0x12c0
	s_lshr_b32 s46, s48, 6
	s_and_b32 s47, s48, 63
	s_mul_i32 s42, s47, 0x58000
	s_lshl_b32 s43, s46, 7
	s_add_u32 s42, s42, s43
	s_add_u32 s42, s42, s38
	s_addc_u32 s43, s39, 0
	s_waitcnt vmcnt(16)
	ds_write2_b32 v15, v24, v25 offset1:1
	ds_write2_b32 v15, v26, v27 offset0:2 offset1:3
	ds_write2_b32 v16, v28, v29 offset1:1
	ds_write2_b32 v16, v30, v31 offset0:2 offset1:3
	ds_write2_b32 v17, v32, v33 offset1:1
	ds_write2_b32 v17, v34, v35 offset0:2 offset1:3
	ds_write2_b32 v18, v36, v37 offset1:1
	ds_write2_b32 v18, v38, v39 offset0:2 offset1:3
	ds_write2_b32 v19, v40, v41 offset1:1
	ds_write2_b32 v19, v42, v43 offset0:2 offset1:3
	ds_write2_b32 v20, v44, v45 offset1:1
	ds_write2_b32 v20, v46, v47 offset0:2 offset1:3
	ds_write2_b32 v21, v48, v49 offset1:1
	ds_write2_b32 v21, v50, v51 offset0:2 offset1:3
	ds_write2_b32 v22, v52, v53 offset1:1
	ds_write2_b32 v22, v54, v55 offset0:2 offset1:3
	s_waitcnt lgkmcnt(0)
	ds_read2_b32 v[120:121], v23 offset0:0 offset1:33
	ds_read2_b32 v[122:123], v23 offset0:66 offset1:99
	ds_read2_b32 v[124:125], v23 offset0:132 offset1:165
	ds_read2_b32 v[126:127], v23 offset0:198 offset1:231
	s_waitcnt lgkmcnt(0)
	v_cvt_pk_bf16_f32 v128, v120, v121
	v_cvt_pk_bf16_f32 v129, v122, v123
	v_cvt_pk_bf16_f32 v130, v124, v125
	v_cvt_pk_bf16_f32 v131, v126, v127
	global_store_dwordx4 v11, v[128:131], s[42:43]
	s_nop 1
	ds_read2_b32 v[120:121], v23 offset0:8 offset1:41
	ds_read2_b32 v[122:123], v23 offset0:74 offset1:107
	ds_read2_b32 v[124:125], v23 offset0:140 offset1:173
	ds_read2_b32 v[126:127], v23 offset0:206 offset1:239
	s_waitcnt lgkmcnt(0)
	v_cvt_pk_bf16_f32 v128, v120, v121
	v_cvt_pk_bf16_f32 v129, v122, v123
	v_cvt_pk_bf16_f32 v130, v124, v125
	v_cvt_pk_bf16_f32 v131, v126, v127
	global_store_dwordx4 v12, v[128:131], s[42:43]
	s_nop 1
	ds_read2_b32 v[120:121], v23 offset0:16 offset1:49
	ds_read2_b32 v[122:123], v23 offset0:82 offset1:115
	ds_read2_b32 v[124:125], v23 offset0:148 offset1:181
	ds_read2_b32 v[126:127], v23 offset0:214 offset1:247
	s_waitcnt lgkmcnt(0)
	v_cvt_pk_bf16_f32 v128, v120, v121
	v_cvt_pk_bf16_f32 v129, v122, v123
	v_cvt_pk_bf16_f32 v130, v124, v125
	v_cvt_pk_bf16_f32 v131, v126, v127
	global_store_dwordx4 v13, v[128:131], s[42:43]
	s_nop 1
	ds_read2_b32 v[120:121], v23 offset0:24 offset1:57
	ds_read2_b32 v[122:123], v23 offset0:90 offset1:123
	ds_read2_b32 v[124:125], v23 offset0:156 offset1:189
	ds_read2_b32 v[126:127], v23 offset0:222 offset1:255
	s_waitcnt lgkmcnt(0)
	v_cvt_pk_bf16_f32 v128, v120, v121
	v_cvt_pk_bf16_f32 v129, v122, v123
	v_cvt_pk_bf16_f32 v130, v124, v125
	v_cvt_pk_bf16_f32 v131, v126, v127
	global_store_dwordx4 v14, v[128:131], s[42:43]
	s_nop 1
	s_add_i32 s48, s44, 0x1400
	s_lshr_b32 s46, s48, 6
	s_and_b32 s47, s48, 63
	s_mul_i32 s42, s47, 0x58000
	s_lshl_b32 s43, s46, 7
	s_add_u32 s42, s42, s43
	s_add_u32 s42, s42, s38
	s_addc_u32 s43, s39, 0
	s_waitcnt vmcnt(8)
	ds_write2_b32 v15, v56, v57 offset1:1
	ds_write2_b32 v15, v58, v59 offset0:2 offset1:3
	ds_write2_b32 v16, v60, v61 offset1:1
	ds_write2_b32 v16, v62, v63 offset0:2 offset1:3
	ds_write2_b32 v17, v64, v65 offset1:1
	ds_write2_b32 v17, v66, v67 offset0:2 offset1:3
	ds_write2_b32 v18, v68, v69 offset1:1
	ds_write2_b32 v18, v70, v71 offset0:2 offset1:3
	ds_write2_b32 v19, v72, v73 offset1:1
	ds_write2_b32 v19, v74, v75 offset0:2 offset1:3
	ds_write2_b32 v20, v76, v77 offset1:1
	ds_write2_b32 v20, v78, v79 offset0:2 offset1:3
	ds_write2_b32 v21, v80, v81 offset1:1
	ds_write2_b32 v21, v82, v83 offset0:2 offset1:3
	ds_write2_b32 v22, v84, v85 offset1:1
	ds_write2_b32 v22, v86, v87 offset0:2 offset1:3
	s_waitcnt lgkmcnt(0)
	ds_read2_b32 v[120:121], v23 offset0:0 offset1:33
	ds_read2_b32 v[122:123], v23 offset0:66 offset1:99
	ds_read2_b32 v[124:125], v23 offset0:132 offset1:165
	ds_read2_b32 v[126:127], v23 offset0:198 offset1:231
	s_waitcnt lgkmcnt(0)
	v_cvt_pk_bf16_f32 v128, v120, v121
	v_cvt_pk_bf16_f32 v129, v122, v123
	v_cvt_pk_bf16_f32 v130, v124, v125
	v_cvt_pk_bf16_f32 v131, v126, v127
	global_store_dwordx4 v11, v[128:131], s[42:43]
	s_nop 1
	ds_read2_b32 v[120:121], v23 offset0:8 offset1:41
	ds_read2_b32 v[122:123], v23 offset0:74 offset1:107
	ds_read2_b32 v[124:125], v23 offset0:140 offset1:173
	ds_read2_b32 v[126:127], v23 offset0:206 offset1:239
	s_waitcnt lgkmcnt(0)
	v_cvt_pk_bf16_f32 v128, v120, v121
	v_cvt_pk_bf16_f32 v129, v122, v123
	v_cvt_pk_bf16_f32 v130, v124, v125
	v_cvt_pk_bf16_f32 v131, v126, v127
	global_store_dwordx4 v12, v[128:131], s[42:43]
	s_nop 1
	ds_read2_b32 v[120:121], v23 offset0:16 offset1:49
	ds_read2_b32 v[122:123], v23 offset0:82 offset1:115
	ds_read2_b32 v[124:125], v23 offset0:148 offset1:181
	ds_read2_b32 v[126:127], v23 offset0:214 offset1:247
	s_waitcnt lgkmcnt(0)
	v_cvt_pk_bf16_f32 v128, v120, v121
	v_cvt_pk_bf16_f32 v129, v122, v123
	v_cvt_pk_bf16_f32 v130, v124, v125
	v_cvt_pk_bf16_f32 v131, v126, v127
	global_store_dwordx4 v13, v[128:131], s[42:43]
	s_nop 1
	ds_read2_b32 v[120:121], v23 offset0:24 offset1:57
	ds_read2_b32 v[122:123], v23 offset0:90 offset1:123
	ds_read2_b32 v[124:125], v23 offset0:156 offset1:189
	ds_read2_b32 v[126:127], v23 offset0:222 offset1:255
	s_waitcnt lgkmcnt(0)
	v_cvt_pk_bf16_f32 v128, v120, v121
	v_cvt_pk_bf16_f32 v129, v122, v123
	v_cvt_pk_bf16_f32 v130, v124, v125
	v_cvt_pk_bf16_f32 v131, v126, v127
	global_store_dwordx4 v14, v[128:131], s[42:43]
	s_nop 1
	s_cmpk_lt_i32 s44, 0xc0
	s_cbranch_scc0 .Ltr1dP12_done
; #define GAS __attribute__((address_space(1)))
; #define LAS __attribute__((address_space(3)))
; #define LDS_WAIT() asm volatile("s_waitcnt lgkmcnt(0)" ::: "memory")
; __device__ __forceinline__ unsigned pk2(float lo, float hi) { return f2bf(lo) | (f2bf(hi) << 16); }
; __device__ __forceinline__ void xcd_barrier(const XcdBarrier& b) {
;     asm volatile("s_waitcnt vmcnt(0)" ::: "memory");
;     __syncthreads();
;     if (threadIdx.x == 0) {
;         unsigned* bar = b.bar;
;         __builtin_amdgcn_s_waitcnt(0);
;         unsigned nloc = b.st[0], nx = b.st[1];
;         if (nloc == 0u) { xcd_barrier_complete(bar, b.x, nloc, nx); b.st[0] = nloc; b.st[1] = nx; }
;     if (ldt == 0) ldt = K;
;     asm volatile("" : "+v"(lane));
;     const int kb = item / nblk, nb = item % nblk, k0 = 64 * kb, n0 = 32 * nb;
;     { float wv[32];
;       const float* wp = W + (size_t)(k0 + (lane >> 5)) * ldw + n0 + (lane & 31);
; #pragma unroll
;       for (int i = 0; i < 32; ++i) wv[i] = wp[(size_t)(2 * i) * ldw];
; #pragma unroll
;       for (int i = 0; i < 32; ++i) scr[(2 * i + (lane >> 5)) * 33 + (lane & 31)] = wv[i]; }
;     LDS_WAIT(); asm volatile("" ::: "memory");
;     const int c = lane & 7;
;     const int r0 = (mode == 0) ? n0 : (256 * (n0 >> 7) + (n0 & 127) + (mode == 2 ? 128 : 0));
; #pragma unroll
;     for (int j = 0; j < 4; ++j) { const int n = (lane >> 3) + 8 * j; const LAS float* s = scr + (8 * c) * 33 + n;
;         v4u o; o.x = pk2(s[0 * 33], s[1 * 33]); o.y = pk2(s[2 * 33], s[3 * 33]); o.z = pk2(s[4 * 33], s[5 * 33]); o.w = pk2(s[6 * 33], s[7 * 33]);
;         *(GAS v4u*)(WT + (size_t)(r0 + n) * ldt + k0 + 8 * c) = o; }
;     LDS_WAIT(); asm volatile("" ::: "memory");
; }
	s_add_i32 s48, s44, 0x1540
	s_lshr_b32 s46, s48, 6
	s_and_b32 s47, s48, 63
	s_mul_i32 s42, s47, 0x58000
	s_lshl_b32 s43, s46, 7
	s_add_u32 s42, s42, s43
	s_add_u32 s42, s42, s38
	s_addc_u32 s43, s39, 0
	s_waitcnt vmcnt(8)
	ds_write2_b32 v15, v88, v89 offset1:1
	ds_write2_b32 v15, v90, v91 offset0:2 offset1:3
	ds_write2_b32 v16, v92, v93 offset1:1
	ds_write2_b32 v16, v94, v95 offset0:2 offset1:3
	ds_write2_b32 v17, v96, v97 offset1:1
	ds_write2_b32 v17, v98, v99 offset0:2 offset1:3
	ds_write2_b32 v18, v100, v101 offset1:1
	ds_write2_b32 v18, v102, v103 offset0:2 offset1:3
	ds_write2_b32 v19, v104, v105 offset1:1
	ds_write2_b32 v19, v106, v107 offset0:2 offset1:3
	ds_write2_b32 v20, v108, v109 offset1:1
	ds_write2_b32 v20, v110, v111 offset0:2 offset1:3
	ds_write2_b32 v21, v112, v113 offset1:1
	ds_write2_b32 v21, v114, v115 offset0:2 offset1:3
	ds_write2_b32 v22, v116, v117 offset1:1
	ds_write2_b32 v22, v118, v119 offset0:2 offset1:3
	s_waitcnt lgkmcnt(0)
	ds_read2_b32 v[120:121], v23 offset0:0 offset1:33
	ds_read2_b32 v[122:123], v23 offset0:66 offset1:99
	ds_read2_b32 v[124:125], v23 offset0:132 offset1:165
	ds_read2_b32 v[126:127], v23 offset0:198 offset1:231
	s_waitcnt lgkmcnt(0)
	v_cvt_pk_bf16_f32 v128, v120, v121
	v_cvt_pk_bf16_f32 v129, v122, v123
	v_cvt_pk_bf16_f32 v130, v124, v125
	v_cvt_pk_bf16_f32 v131, v126, v127
	global_store_dwordx4 v11, v[128:131], s[42:43]
	s_nop 1
	ds_read2_b32 v[120:121], v23 offset0:8 offset1:41
	ds_read2_b32 v[122:123], v23 offset0:74 offset1:107
	ds_read2_b32 v[124:125], v23 offset0:140 offset1:173
	ds_read2_b32 v[126:127], v23 offset0:206 offset1:239
	s_waitcnt lgkmcnt(0)
	v_cvt_pk_bf16_f32 v128, v120, v121
	v_cvt_pk_bf16_f32 v129, v122, v123
	v_cvt_pk_bf16_f32 v130, v124, v125
	v_cvt_pk_bf16_f32 v131, v126, v127
	global_store_dwordx4 v12, v[128:131], s[42:43]
	s_nop 1
	ds_read2_b32 v[120:121], v23 offset0:16 offset1:49
	ds_read2_b32 v[122:123], v23 offset0:82 offset1:115
	ds_read2_b32 v[124:125], v23 offset0:148 offset1:181
	ds_read2_b32 v[126:127], v23 offset0:214 offset1:247
	s_waitcnt lgkmcnt(0)
	v_cvt_pk_bf16_f32 v128, v120, v121
	v_cvt_pk_bf16_f32 v129, v122, v123
	v_cvt_pk_bf16_f32 v130, v124, v125
	v_cvt_pk_bf16_f32 v131, v126, v127
	global_store_dwordx4 v13, v[128:131], s[42:43]
	s_nop 1
	ds_read2_b32 v[120:121], v23 offset0:24 offset1:57
	ds_read2_b32 v[122:123], v23 offset0:90 offset1:123
	ds_read2_b32 v[124:125], v23 offset0:156 offset1:189
	ds_read2_b32 v[126:127], v23 offset0:222 offset1:255
	s_waitcnt lgkmcnt(0)
	v_cvt_pk_bf16_f32 v128, v120, v121
	v_cvt_pk_bf16_f32 v129, v122, v123
	v_cvt_pk_bf16_f32 v130, v124, v125
	v_cvt_pk_bf16_f32 v131, v126, v127
	global_store_dwordx4 v14, v[128:131], s[42:43]
	s_nop 1
.Ltr1dP12_done:
.LBB0_1590:
	s_cmp_gt_i32 s93, 13
	s_cselect_b64 s[0:1], -1, 0
	s_and_b64 s[4:5], s[6:7], s[0:1]
	s_andn2_b64 vcc, exec, s[4:5]
	s_cbranch_vccnz .LBB0_1638
	s_cmp_gt_i32 s92, -1
	s_mov_b64 s[4:5], -1
	s_cbranch_scc0 .LBB0_1625
	s_waitcnt vmcnt(0)
	s_waitcnt vmcnt(0) lgkmcnt(0)
	s_barrier
	s_mov_b64 s[4:5], exec
	v_readlane_b32 s6, v245, 31
	v_readlane_b32 s7, v245, 32
	s_and_b64 s[6:7], s[4:5], s[6:7]
	s_mov_b64 exec, s[6:7]
	s_cbranch_execz .LBB0_1624
	s_add_i32 s3, 0, 0x26020
	v_mov_b32_e32 v2, s3
	s_waitcnt vmcnt(0) expcnt(0) lgkmcnt(0)
	ds_read_b32 v2, v2
	s_add_i32 s3, 0, 0x26024
	v_mov_b32_e32 v3, s3
	ds_read_b32 v5, v3
	s_waitcnt lgkmcnt(1)
	v_cmp_ne_u32_e32 vcc, 0, v2
	s_cbranch_vccnz .LBB0_1617
	v_readlane_b32 s6, v245, 8
	v_readlane_b32 s7, v245, 9
	s_load_dwordx2 s[10:11], s[6:7], 0x4
	s_add_u32 s6, s34, 0x4200
	s_addc_u32 s7, s35, 0
	s_add_u32 s8, s34, 0x4400
	s_addc_u32 s9, s35, 0
	s_waitcnt lgkmcnt(0)
	s_mul_i32 s3, s10, s96
	s_add_u32 s10, s34, 0x4500
	s_mul_i32 s3, s3, s11
	s_addc_u32 s11, s35, 0
	s_add_u32 s12, s34, 0x4600
	s_addc_u32 s13, s35, 0
	s_add_u32 s14, s34, 0x4700
	s_addc_u32 s15, s35, 0
	s_add_u32 s16, s34, 0x4800
	s_addc_u32 s17, s35, 0
	s_add_u32 s18, s34, 0x4900
	s_addc_u32 s19, s35, 0
	s_add_u32 s20, s34, 0x4a00
	s_addc_u32 s21, s35, 0
	s_add_u32 s22, s34, 0x4b00
	s_addc_u32 s23, s35, 0
	s_add_u32 s24, s34, 0x4c00
	s_addc_u32 s25, s35, 0
	s_add_u32 s26, s34, 0x4d00
	s_addc_u32 s27, s35, 0
	s_add_u32 s28, s34, 0x4e00
	s_addc_u32 s29, s35, 0
	s_add_u32 s30, s34, 0x4f00
	s_addc_u32 s31, s35, 0
	s_add_u32 s36, s34, 0x5000
	s_addc_u32 s37, s35, 0
	s_add_u32 s38, s34, 0x5100
	s_addc_u32 s39, s35, 0
	s_add_u32 s40, s34, 0x5200
	s_addc_u32 s41, s35, 0
	s_add_u32 s42, s34, 0x5300
	s_addc_u32 s43, s35, 0
	s_mov_b32 s33, 1
	v_mov_b32_e32 v18, 0
	s_branch .LBB0_1596
